# prep1 decay loop and scan chunk loop: f32->bf16 RNE via v_cvt_pk_bf16_f32 instead of the bfe+add3 bit trick (218 sites, one VALU less each)
# speedup vs baseline: 1.0079x; 1.0022x over previous
.LBB0_573:
	s_add_i32 s46, s44, 1
	v_min_i32_e32 v20, s46, v181
	v_sub_u32_e32 v21, v181, v20
	v_cndmask_b32_e64 v20, v21, v20, s[18:19]
	v_lshl_add_u32 v20, v20, 6, v183
	v_ashrrev_i32_e32 v21, 31, v20
	v_lshl_add_u64 v[22:23], v[20:21], 1, v[206:207]
	global_load_dwordx4 v[54:57], v[22:23], off
	v_ashrrev_i32_e32 v22, 6, v20
	v_ashrrev_i32_e32 v23, 31, v22
	v_lshlrev_b64 v[24:25], 9, v[22:23]
	v_lshl_add_u64 v[24:25], v[208:209], 0, v[24:25]
	v_lshlrev_b64 v[20:21], 8, v[20:21]
	global_load_dword v187, v[24:25], off
	v_lshl_add_u64 v[24:25], v[210:211], 0, v[20:21]
	s_movk_i32 s45, 0x2000
	v_add_co_u32_e32 v26, vcc, s45, v24
	s_movk_i32 s47, 0x3000
	s_nop 0
	v_addc_co_u32_e32 v27, vcc, 0, v25, vcc
	global_load_dwordx4 v[58:61], v[24:25], off
	v_add_co_u32_e32 v24, vcc, s47, v24
	v_lshl_add_u64 v[20:21], v[212:213], 0, v[20:21]
	s_nop 0
	v_addc_co_u32_e32 v25, vcc, 0, v25, vcc
	global_load_dwordx4 v[70:73], v[26:27], off offset:-4096
	global_load_dwordx4 v[74:77], v[26:27], off
	global_load_dwordx4 v[82:85], v[24:25], off
	global_load_dwordx4 v[90:93], v[20:21], off
	v_add_co_u32_e32 v24, vcc, s45, v20
	v_add_u32_e32 v158, v163, v150
	s_nop 0
	v_addc_co_u32_e32 v25, vcc, 0, v21, vcc
	v_add_co_u32_e32 v20, vcc, s47, v20
	global_load_dwordx4 v[94:97], v[24:25], off offset:-4096
	global_load_dwordx4 v[98:101], v[24:25], off
	v_addc_co_u32_e32 v21, vcc, 0, v21, vcc
	global_load_dwordx4 v[102:105], v[20:21], off
	v_lshl_add_u64 v[20:21], v[2:3], 0, v[22:23]
	v_lshlrev_b64 v[20:21], 14, v[20:21]
	v_lshl_or_b32 v20, v198, 7, v20
	v_lshl_add_u64 v[20:21], v[152:153], 0, v[20:21]
	global_load_dwordx4 v[86:89], v[20:21], off
	global_load_dwordx4 v[78:81], v[20:21], off offset:32
	global_load_dwordx4 v[66:69], v[20:21], off offset:64
	global_load_dwordx4 v[62:65], v[20:21], off offset:96
	s_waitcnt lgkmcnt(0)
	s_barrier
	ds_read_b128 v[106:109], v173 offset:28160
	ds_read_b128 v[234:237], v158 offset:45568
	ds_read_b128 v[110:113], v173 offset:28192
	ds_read_b128 v[238:241], v158 offset:45600
	ds_read_b128 v[134:137], v173 offset:28224
	ds_read_b128 v[242:245], v158 offset:45632
	ds_read_b128 v[114:117], v173 offset:28256
	ds_read_b128 v[246:249], v158 offset:45664
	ds_read_b128 v[118:121], v173 offset:28288
	ds_read_b128 v[250:253], v158 offset:45696
	ds_read_b128 v[122:125], v173 offset:28320
	ds_read_b128 v[126:129], v173 offset:28352
	ds_read_b128 v[130:133], v173 offset:28384
	s_and_b32 s45, s44, 1
	s_mul_i32 s47, s45, 0x1200
	v_add_u32_e32 v189, s47, v154
	v_add3_u32 v189, v189, v165, v150
	s_waitcnt lgkmcnt(11)
	v_mfma_f32_32x32x16_bf16 v[20:35], v[106:109], v[234:237], 0
	ds_read_b128 v[234:237], v158 offset:45728
	s_waitcnt lgkmcnt(10)
	v_mfma_f32_32x32x16_bf16 v[20:35], v[110:113], v[238:241], v[20:35]
	ds_read_b128 v[238:241], v158 offset:45760
	s_waitcnt lgkmcnt(9)
	v_mfma_f32_32x32x16_bf16 v[20:35], v[134:137], v[242:245], v[20:35]
	ds_read_b128 v[242:245], v158 offset:45792
	s_waitcnt lgkmcnt(8)
	v_mfma_f32_32x32x16_bf16 v[20:35], v[114:117], v[246:249], v[20:35]
	s_waitcnt lgkmcnt(6)
	v_mfma_f32_32x32x16_bf16 v[20:35], v[118:121], v[250:253], v[20:35]
	s_waitcnt lgkmcnt(2)
	v_mfma_f32_32x32x16_bf16 v[20:35], v[122:125], v[234:237], v[20:35]
	s_waitcnt lgkmcnt(1)
	v_mfma_f32_32x32x16_bf16 v[20:35], v[126:129], v[238:241], v[20:35]
	s_waitcnt lgkmcnt(0)
	v_mfma_f32_32x32x16_bf16 v[20:35], v[130:133], v[242:245], v[20:35]
	s_nop 11
	v_cndmask_b32_e64 v20, 0, v20, s[78:79]
	v_cndmask_b32_e64 v21, 0, v21, s[80:81]
	v_bfe_u32 v158, v20, 16, 1
	v_cndmask_b32_e64 v22, 0, v22, s[82:83]
	v_bfe_u32 v159, v21, 16, 1
	v_add3_u32 v20, v20, v158, s73
	v_add3_u32 v21, v21, v159, s73
	ds_write_b16_d16_hi v175, v20 offset:8704
	ds_write_b16_d16_hi v175, v21 offset:8848
	v_cvt_pk_bf16_f32 v20, v22, v22
	ds_write_b16_d16_hi v175, v20 offset:8992
	v_cndmask_b32_e64 v20, 0, v23, s[84:85]
	v_cvt_pk_bf16_f32 v20, v20, v20
	ds_write_b16_d16_hi v175, v20 offset:9136
	v_cndmask_b32_e64 v20, 0, v24, s[86:87]
	v_cvt_pk_bf16_f32 v20, v20, v20
	ds_write_b16_d16_hi v175, v20 offset:9856
	v_cndmask_b32_e64 v20, 0, v25, s[88:89]
	v_cvt_pk_bf16_f32 v20, v20, v20
	ds_write_b16_d16_hi v175, v20 offset:10000
	v_cndmask_b32_e64 v20, 0, v26, s[90:91]
	v_cvt_pk_bf16_f32 v20, v20, v20
	ds_write_b16_d16_hi v175, v20 offset:10144
	v_cndmask_b32_e64 v20, 0, v27, s[92:93]
	v_cvt_pk_bf16_f32 v20, v20, v20
	ds_write_b16_d16_hi v175, v20 offset:10288
	v_cndmask_b32_e64 v20, 0, v28, s[94:95]
	v_cvt_pk_bf16_f32 v20, v20, v20
	ds_write_b16_d16_hi v175, v20 offset:11008
	v_cndmask_b32_e64 v20, 0, v29, s[96:97]
	v_cvt_pk_bf16_f32 v20, v20, v20
	ds_write_b16_d16_hi v175, v20 offset:11152
	v_cndmask_b32_e64 v20, 0, v30, s[16:17]
	v_cvt_pk_bf16_f32 v20, v20, v20
	ds_write_b16_d16_hi v175, v20 offset:11296
	v_cndmask_b32_e64 v20, 0, v31, s[8:9]
	v_cvt_pk_bf16_f32 v20, v20, v20
	ds_write_b16_d16_hi v175, v20 offset:11440
	v_cndmask_b32_e64 v20, 0, v32, s[0:1]
	v_cvt_pk_bf16_f32 v20, v20, v20
	ds_write_b16_d16_hi v175, v20 offset:12160
	v_cndmask_b32_e64 v20, 0, v33, s[10:11]
	v_cvt_pk_bf16_f32 v20, v20, v20
	ds_write_b16_d16_hi v175, v20 offset:12304
	v_cndmask_b32_e64 v20, 0, v34, s[12:13]
	v_cvt_pk_bf16_f32 v20, v20, v20
	ds_write_b16_d16_hi v175, v20 offset:12448
	v_cndmask_b32_e64 v20, 0, v35, s[14:15]
	v_bfe_u32 v21, v20, 16, 1
	v_add3_u32 v20, v20, v21, s73
	ds_write_b16_d16_hi v175, v20 offset:12592
	s_waitcnt lgkmcnt(0)
	s_barrier
	s_and_saveexec_b64 vcc, s[6:7]
	s_cbranch_execz .LBB0_575
	v_mov_b32_e32 v20, s44
	v_cndmask_b32_e64 v20, v185, v20, s[18:19]
	v_lshl_add_u32 v230, v20, 6, v183
	ds_read_b128 v[234:237], v169
	ds_read_b128 v[238:241], v169 offset:32
	ds_read_b128 v[242:245], v169 offset:64
	ds_read_b128 v[246:249], v169 offset:96
	ds_read_b128 v[250:253], v169 offset:128
	ds_read_b128 v[158:161], v169 offset:160
	v_ashrrev_i32_e32 v231, 31, v230
	s_waitcnt lgkmcnt(5)
	v_mfma_f32_32x32x16_bf16 v[20:35], v[106:109], v[234:237], 0
	ds_read_b128 v[106:109], v169 offset:192
	ds_read_b128 v[234:237], v177 offset:8704
	s_waitcnt lgkmcnt(6)
	v_mfma_f32_32x32x16_bf16 v[20:35], v[110:113], v[238:241], v[20:35]
	ds_read_b128 v[110:113], v169 offset:224
	ds_read_b128 v[238:241], v189 offset:17920
	s_waitcnt lgkmcnt(7)
	v_mfma_f32_32x32x16_bf16 v[20:35], v[134:137], v[242:245], v[20:35]
	ds_read_b128 v[242:245], v177 offset:8736
	ds_read_b128 v[134:137], v189 offset:17952
	s_waitcnt lgkmcnt(8)
	v_mfma_f32_32x32x16_bf16 v[20:35], v[114:117], v[246:249], v[20:35]
	ds_read_b128 v[246:249], v177 offset:8768
	ds_read_b128 v[114:117], v189 offset:17984
	s_waitcnt lgkmcnt(9)
	v_mfma_f32_32x32x16_bf16 v[20:35], v[118:121], v[250:253], v[20:35]
	ds_read_b128 v[250:253], v177 offset:8800
	ds_read_b128 v[118:121], v189 offset:18016
	s_waitcnt lgkmcnt(10)
	v_mfma_f32_32x32x16_bf16 v[20:35], v[122:125], v[158:161], v[20:35]
	s_waitcnt lgkmcnt(9)
	v_mfma_f32_32x32x16_bf16 v[20:35], v[126:129], v[106:109], v[20:35]
	s_waitcnt lgkmcnt(7)
	v_mfma_f32_32x32x16_bf16 v[20:35], v[130:133], v[110:113], v[20:35]
	s_waitcnt lgkmcnt(6)
	v_mfma_f32_32x32x16_bf16 v[20:35], v[234:237], v[238:241], v[20:35]
	s_waitcnt lgkmcnt(4)
	v_mfma_f32_32x32x16_bf16 v[20:35], v[242:245], v[134:137], v[20:35]
	s_waitcnt lgkmcnt(2)
	v_mfma_f32_32x32x16_bf16 v[20:35], v[246:249], v[114:117], v[20:35]
	s_waitcnt lgkmcnt(0)
	v_mfma_f32_32x32x16_bf16 v[20:35], v[250:253], v[118:121], v[20:35]
	v_lshl_add_u64 v[106:107], v[214:215], 0, v[230:231]
	v_mov_b32_e32 v109, v107
	s_nop 9
	v_cvt_pk_bf16_f32 v20, v20, v20
	v_or_b32_e32 v108, v106, v162
	v_lshlrev_b64 v[108:109], 11, v[108:109]
	v_lshl_add_u64 v[108:109], v[216:217], 0, v[108:109]
	v_mov_b64_e32 v[158:159], v[108:109]
	s_mov_b64 s[98:99], 0x1000
	v_mov_b32_e32 v160, 0x3000
	v_mov_b32_e32 v161, 0
	global_store_short_d16_hi v[108:109], v20, off
	v_cvt_pk_bf16_f32 v108, v21, v21
	global_store_short_d16_hi v[158:159], v108, off offset:2048
	v_cvt_pk_bf16_f32 v22, v22, v22
	v_lshl_add_u64 v[158:159], v[158:159], 0, s[98:99]
	global_store_short_d16_hi v[158:159], v22, off
	v_cvt_pk_bf16_f32 v22, v23, v23
	global_store_short_d16_hi v[158:159], v22, off offset:2048
	v_cvt_pk_bf16_f32 v22, v24, v24
	v_lshl_add_u64 v[158:159], v[158:159], 0, v[160:161]
	global_store_short_d16_hi v[158:159], v22, off
	v_cvt_pk_bf16_f32 v22, v25, v25
	global_store_short_d16_hi v[158:159], v22, off offset:2048
	v_cvt_pk_bf16_f32 v22, v26, v26
	v_lshl_add_u64 v[158:159], v[158:159], 0, s[98:99]
	global_store_short_d16_hi v[158:159], v22, off
	v_cvt_pk_bf16_f32 v22, v27, v27
	global_store_short_d16_hi v[158:159], v22, off offset:2048
	v_cvt_pk_bf16_f32 v22, v28, v28
	v_lshl_add_u64 v[158:159], v[158:159], 0, v[160:161]
	global_store_short_d16_hi v[158:159], v22, off
	v_cvt_pk_bf16_f32 v22, v29, v29
	global_store_short_d16_hi v[158:159], v22, off offset:2048
	v_cvt_pk_bf16_f32 v22, v30, v30
	v_lshl_add_u64 v[158:159], v[158:159], 0, s[98:99]
	global_store_short_d16_hi v[158:159], v22, off
	v_cvt_pk_bf16_f32 v22, v31, v31
	global_store_short_d16_hi v[158:159], v22, off offset:2048
	v_cvt_pk_bf16_f32 v22, v32, v32
	v_lshl_add_u64 v[158:159], v[158:159], 0, v[160:161]
	global_store_short_d16_hi v[158:159], v22, off
	v_cvt_pk_bf16_f32 v22, v33, v33
	global_store_short_d16_hi v[158:159], v22, off offset:2048
	v_cvt_pk_bf16_f32 v22, v34, v34
	v_lshl_add_u64 v[158:159], v[158:159], 0, s[98:99]
	global_store_short_d16_hi v[158:159], v22, off
	v_bfe_u32 v20, v35, 16, 1
	v_add3_u32 v22, v35, v20, s73
	global_store_short_d16_hi v[158:159], v22, off offset:2048

.Lp1e_skip:
	global_load_dword v4, v6, s[8:9]
	global_load_dword v5, v6, s[8:9] offset:2048
	s_nop 0
	global_load_dword v6, v[154:155], off offset:-4096
	global_load_dword v7, v[146:147], off offset:2048
	global_load_dword v228, v[154:155], off
	s_nop 0
	global_load_dword v154, v[154:155], off offset:2048
	v_add_co_u32_e32 v146, vcc, s0, v158
	s_movk_i32 s0, 0x5000
	s_nop 0
	v_addc_co_u32_e32 v147, vcc, 0, v159, vcc
	v_add_co_u32_e32 v160, vcc, s17, v158
	s_nop 1
	v_addc_co_u32_e32 v161, vcc, 0, v159, vcc
	global_load_dword v155, v[160:161], off offset:-4096
	global_load_dword v156, v[146:147], off offset:2048
	s_nop 0
	global_load_dword v146, v[160:161], off
	global_load_dword v252, v[160:161], off offset:2048
	v_add_co_u32_e32 v160, vcc, s0, v158
	s_movk_i32 s0, 0x7000
	s_nop 0
	v_addc_co_u32_e32 v161, vcc, 0, v159, vcc
	v_add_co_u32_e32 v174, vcc, s62, v158
	s_nop 1
	v_addc_co_u32_e32 v175, vcc, 0, v159, vcc
	v_add_co_u32_e32 v158, vcc, s0, v158
	global_load_dword v253, v[174:175], off offset:-4096
	global_load_dword v227, v[160:161], off offset:2048
	global_load_dword v145, v[174:175], off
	global_load_dword v147, v[174:175], off offset:2048
	v_addc_co_u32_e32 v159, vcc, 0, v159, vcc
	global_load_dword v230, v[158:159], off
	global_load_dword v231, v[158:159], off offset:2048
	global_load_dword v157, v141, s[10:11]
	ds_read_b128 v[174:177], v9
	ds_read_b128 v[178:181], v9 offset:16
	ds_read_b128 v[182:185], v9 offset:32
	ds_read_b128 v[186:189], v9 offset:48
	ds_read_b128 v[212:215], v9 offset:4480
	ds_read_b128 v[234:237], v9 offset:4992
	s_waitcnt vmcnt(15) lgkmcnt(5)
	v_mul_f32_e32 v141, v5, v175
	v_fmac_f32_e32 v141, v4, v174
	s_waitcnt vmcnt(11) lgkmcnt(4)
	v_mul_f32_e32 v158, v154, v179
	v_fmac_f32_e32 v141, v6, v176
	v_fmac_f32_e32 v158, v228, v178
	v_fmac_f32_e32 v141, v7, v177
	ds_read_b128 v[174:177], v9 offset:128
	s_waitcnt vmcnt(10)
	v_fmac_f32_e32 v158, v155, v180
	s_waitcnt vmcnt(9)
	v_fmac_f32_e32 v158, v156, v181
	s_waitcnt vmcnt(0)
	v_add_f32_e32 v141, v157, v141
	v_add_f32_e32 v141, v141, v158
	s_waitcnt lgkmcnt(4)
	v_mul_f32_e32 v158, v252, v183
	v_fmac_f32_e32 v158, v146, v182
	v_fmac_f32_e32 v158, v253, v184
	v_fmac_f32_e32 v158, v227, v185
	v_add_f32_e32 v141, v141, v158
	s_waitcnt lgkmcnt(3)
	v_mul_f32_e32 v158, v147, v187
	v_fmac_f32_e32 v158, v145, v186
	v_fmac_f32_e32 v158, v230, v188
	v_fmac_f32_e32 v158, v231, v189
	v_add_f32_e32 v141, v141, v158
	v_min_f32_e32 v158, 0, v141
	v_mul_f32_e64 v141, |v141|, s18
	v_exp_f32_e32 v141, v141
	s_nop 0
	v_add_f32_e32 v141, 1.0, v141
	v_cmp_gt_f32_e32 vcc, s71, v141
	s_nop 1
	v_cndmask_b32_e64 v159, 0, 32, vcc
	v_ldexp_f32 v141, v141, v159
	v_log_f32_e32 v141, v141
	s_nop 0
	v_mul_f32_e32 v159, 0x3f317217, v141
	v_fma_f32 v159, v141, s48, -v159
	v_fmac_f32_e32 v159, 0x3377d1cf, v141
	v_fmac_f32_e32 v159, 0x3f317217, v141
	v_cmp_lt_f32_e64 s[0:1], |v141|, s49
	s_nop 1
	v_cndmask_b32_e64 v141, v141, v159, s[0:1]
	v_cndmask_b32_e32 v159, 0, v233, vcc
	v_sub_f32_e32 v141, v141, v159
	v_sub_f32_e32 v141, v158, v141
	s_waitcnt lgkmcnt(0)
	v_mul_f32_e32 v158, v5, v175
	v_fmac_f32_e32 v158, v4, v174
	v_fmac_f32_e32 v158, v6, v176
	v_fmac_f32_e32 v158, v7, v177
	ds_read_b128 v[174:177], v9 offset:144
	v_add_f32_e32 v158, v157, v158
	s_mov_b32 s0, 0x3d800000
	v_mul_f32_e32 v173, 0x3d800000, v141
	v_fma_f32 v141, v141, s0, 0
	s_waitcnt lgkmcnt(0)
	v_mul_f32_e32 v159, v154, v175
	v_fmac_f32_e32 v159, v228, v174
	v_fmac_f32_e32 v159, v155, v176
	v_fmac_f32_e32 v159, v156, v177
	ds_read_b128 v[174:177], v9 offset:160
	v_add_f32_e32 v158, v158, v159
	s_waitcnt lgkmcnt(0)
	v_mul_f32_e32 v159, v252, v175
	v_fmac_f32_e32 v159, v146, v174
	v_fmac_f32_e32 v159, v253, v176
	v_fmac_f32_e32 v159, v227, v177
	ds_read_b128 v[174:177], v9 offset:176
	v_add_f32_e32 v158, v158, v159
	s_waitcnt lgkmcnt(0)
	v_mul_f32_e32 v159, v147, v175
	v_fmac_f32_e32 v159, v145, v174
	v_fmac_f32_e32 v159, v230, v176
	v_fmac_f32_e32 v159, v231, v177
	v_add_f32_e32 v158, v158, v159
	v_min_f32_e32 v159, 0, v158
	v_mul_f32_e64 v158, |v158|, s18
	v_exp_f32_e32 v158, v158
	ds_read_b128 v[176:179], v9 offset:256
	v_add_f32_e32 v158, 1.0, v158
	v_cmp_gt_f32_e32 vcc, s71, v158
	s_nop 1
	v_cndmask_b32_e64 v160, 0, 32, vcc
	v_ldexp_f32 v158, v158, v160
	v_log_f32_e32 v158, v158
	s_nop 0
	v_mul_f32_e32 v160, 0x3f317217, v158
	v_fma_f32 v160, v158, s48, -v160
	v_fmac_f32_e32 v160, 0x3377d1cf, v158
	v_fmac_f32_e32 v160, 0x3f317217, v158
	v_cmp_lt_f32_e64 s[0:1], |v158|, s49
	s_nop 1
	v_cndmask_b32_e64 v158, v158, v160, s[0:1]
	v_cndmask_b32_e32 v160, 0, v233, vcc
	v_sub_f32_e32 v158, v158, v160
	v_sub_f32_e32 v158, v159, v158
	v_mul_f32_e32 v174, 0x3d800000, v158
	v_fmac_f32_e32 v141, 0x3d800000, v158
	s_waitcnt lgkmcnt(0)
	v_mul_f32_e32 v158, v5, v177
	v_fmac_f32_e32 v158, v4, v176
	v_fmac_f32_e32 v158, v6, v178
	v_fmac_f32_e32 v158, v7, v179
	ds_read_b128 v[176:179], v9 offset:272
	v_add_f32_e32 v158, v157, v158
	s_waitcnt lgkmcnt(0)
	v_mul_f32_e32 v159, v154, v177
	v_fmac_f32_e32 v159, v228, v176
	v_fmac_f32_e32 v159, v155, v178
	v_fmac_f32_e32 v159, v156, v179
	ds_read_b128 v[176:179], v9 offset:288
	v_add_f32_e32 v158, v158, v159
	s_waitcnt lgkmcnt(0)
	v_mul_f32_e32 v159, v252, v177
	v_fmac_f32_e32 v159, v146, v176
	v_fmac_f32_e32 v159, v253, v178
	v_fmac_f32_e32 v159, v227, v179
	ds_read_b128 v[176:179], v9 offset:304
	v_add_f32_e32 v158, v158, v159
	s_waitcnt lgkmcnt(0)
	v_mul_f32_e32 v159, v147, v177
	v_fmac_f32_e32 v159, v145, v176
	v_fmac_f32_e32 v159, v230, v178
	v_fmac_f32_e32 v159, v231, v179
	v_add_f32_e32 v158, v158, v159
	v_min_f32_e32 v159, 0, v158
	v_mul_f32_e64 v158, |v158|, s18
	v_exp_f32_e32 v158, v158
	ds_read_b128 v[176:179], v9 offset:384
	v_add_f32_e32 v158, 1.0, v158
	v_cmp_gt_f32_e32 vcc, s71, v158
	s_nop 1
	v_cndmask_b32_e64 v160, 0, 32, vcc
	v_ldexp_f32 v158, v158, v160
	v_log_f32_e32 v158, v158
	s_nop 0
	v_mul_f32_e32 v160, 0x3f317217, v158
	v_fma_f32 v160, v158, s48, -v160
	v_fmac_f32_e32 v160, 0x3377d1cf, v158
	v_fmac_f32_e32 v160, 0x3f317217, v158
	v_cmp_lt_f32_e64 s[0:1], |v158|, s49
	s_nop 1
	v_cndmask_b32_e64 v158, v158, v160, s[0:1]
	v_cndmask_b32_e32 v160, 0, v233, vcc
	v_sub_f32_e32 v158, v158, v160
	v_sub_f32_e32 v158, v159, v158
	v_mul_f32_e32 v175, 0x3d800000, v158
	v_fmac_f32_e32 v141, 0x3d800000, v158
	s_waitcnt lgkmcnt(0)
	v_mul_f32_e32 v158, v5, v177
	v_fmac_f32_e32 v158, v4, v176
	v_fmac_f32_e32 v158, v6, v178
	v_fmac_f32_e32 v158, v7, v179
	ds_read_b128 v[176:179], v9 offset:400
	v_add_f32_e32 v158, v157, v158
	s_waitcnt lgkmcnt(0)
	v_mul_f32_e32 v159, v154, v177
	v_fmac_f32_e32 v159, v228, v176
	v_fmac_f32_e32 v159, v155, v178
	v_fmac_f32_e32 v159, v156, v179
	ds_read_b128 v[176:179], v9 offset:416
	v_add_f32_e32 v158, v158, v159
	s_waitcnt lgkmcnt(0)
	v_mul_f32_e32 v159, v252, v177
	v_fmac_f32_e32 v159, v146, v176
	v_fmac_f32_e32 v159, v253, v178
	v_fmac_f32_e32 v159, v227, v179
	ds_read_b128 v[176:179], v9 offset:432
	v_add_f32_e32 v158, v158, v159
	s_waitcnt lgkmcnt(0)
	v_mul_f32_e32 v159, v147, v177
	v_fmac_f32_e32 v159, v145, v176
	v_fmac_f32_e32 v159, v230, v178
	v_fmac_f32_e32 v159, v231, v179
	v_add_f32_e32 v158, v158, v159
	v_min_f32_e32 v159, 0, v158
	v_mul_f32_e64 v158, |v158|, s18
	v_exp_f32_e32 v158, v158
	ds_read_b128 v[178:181], v9 offset:512
	v_add_f32_e32 v158, 1.0, v158
	v_cmp_gt_f32_e32 vcc, s71, v158
	s_nop 1
	v_cndmask_b32_e64 v160, 0, 32, vcc
	v_ldexp_f32 v158, v158, v160
	v_log_f32_e32 v158, v158
	s_nop 0
	v_mul_f32_e32 v160, 0x3f317217, v158
	v_fma_f32 v160, v158, s48, -v160
	v_fmac_f32_e32 v160, 0x3377d1cf, v158
	v_fmac_f32_e32 v160, 0x3f317217, v158
	v_cmp_lt_f32_e64 s[0:1], |v158|, s49
	s_nop 1
	v_cndmask_b32_e64 v158, v158, v160, s[0:1]
	v_cndmask_b32_e32 v160, 0, v233, vcc
	v_sub_f32_e32 v158, v158, v160
	v_sub_f32_e32 v158, v159, v158
	v_mul_f32_e32 v176, 0x3d800000, v158
	v_fmac_f32_e32 v141, 0x3d800000, v158
	s_waitcnt lgkmcnt(0)
	v_mul_f32_e32 v158, v5, v179
	v_fmac_f32_e32 v158, v4, v178
	v_fmac_f32_e32 v158, v6, v180
	v_fmac_f32_e32 v158, v7, v181
	ds_read_b128 v[178:181], v9 offset:528
	v_add_f32_e32 v158, v157, v158
	s_waitcnt lgkmcnt(0)
	v_mul_f32_e32 v159, v154, v179
	v_fmac_f32_e32 v159, v228, v178
	v_fmac_f32_e32 v159, v155, v180
	v_fmac_f32_e32 v159, v156, v181
	ds_read_b128 v[178:181], v9 offset:544
	v_add_f32_e32 v158, v158, v159
	s_waitcnt lgkmcnt(0)
	v_mul_f32_e32 v159, v252, v179
	v_fmac_f32_e32 v159, v146, v178
	v_fmac_f32_e32 v159, v253, v180
	v_fmac_f32_e32 v159, v227, v181
	ds_read_b128 v[178:181], v9 offset:560
	v_add_f32_e32 v158, v158, v159
	s_waitcnt lgkmcnt(0)
	v_mul_f32_e32 v159, v147, v179
	v_fmac_f32_e32 v159, v145, v178
	v_fmac_f32_e32 v159, v230, v180
	v_fmac_f32_e32 v159, v231, v181
	v_add_f32_e32 v158, v158, v159
	v_min_f32_e32 v159, 0, v158
	v_mul_f32_e64 v158, |v158|, s18
	v_exp_f32_e32 v158, v158
	ds_read_b128 v[178:181], v9 offset:640
	v_add_f32_e32 v158, 1.0, v158
	v_cmp_gt_f32_e32 vcc, s71, v158
	s_nop 1
	v_cndmask_b32_e64 v160, 0, 32, vcc
	v_ldexp_f32 v158, v158, v160
	v_log_f32_e32 v158, v158
	s_nop 0
	v_mul_f32_e32 v160, 0x3f317217, v158
	v_fma_f32 v160, v158, s48, -v160
	v_fmac_f32_e32 v160, 0x3377d1cf, v158
	v_fmac_f32_e32 v160, 0x3f317217, v158
	v_cmp_lt_f32_e64 s[0:1], |v158|, s49
	s_nop 1
	v_cndmask_b32_e64 v158, v158, v160, s[0:1]
	v_cndmask_b32_e32 v160, 0, v233, vcc
	v_sub_f32_e32 v158, v158, v160
	v_sub_f32_e32 v158, v159, v158
	v_mul_f32_e32 v177, 0x3d800000, v158
	v_fmac_f32_e32 v141, 0x3d800000, v158
	s_waitcnt lgkmcnt(0)
	v_mul_f32_e32 v158, v5, v179
	v_fmac_f32_e32 v158, v4, v178
	v_fmac_f32_e32 v158, v6, v180
	v_fmac_f32_e32 v158, v7, v181
	ds_read_b128 v[178:181], v9 offset:656
	v_add_f32_e32 v158, v157, v158
	s_waitcnt lgkmcnt(0)
	v_mul_f32_e32 v159, v154, v179
	v_fmac_f32_e32 v159, v228, v178
	v_fmac_f32_e32 v159, v155, v180
	v_fmac_f32_e32 v159, v156, v181
	ds_read_b128 v[178:181], v9 offset:672
	v_add_f32_e32 v158, v158, v159
	s_waitcnt lgkmcnt(0)
	v_mul_f32_e32 v159, v252, v179
	v_fmac_f32_e32 v159, v146, v178
	v_fmac_f32_e32 v159, v253, v180
	v_fmac_f32_e32 v159, v227, v181
	ds_read_b128 v[178:181], v9 offset:688
	v_add_f32_e32 v158, v158, v159
	s_waitcnt lgkmcnt(0)
	v_mul_f32_e32 v159, v147, v179
	v_fmac_f32_e32 v159, v145, v178
	v_fmac_f32_e32 v159, v230, v180
	v_fmac_f32_e32 v159, v231, v181
	v_add_f32_e32 v158, v158, v159
	v_min_f32_e32 v159, 0, v158
	v_mul_f32_e64 v158, |v158|, s18
	v_exp_f32_e32 v158, v158
	ds_read_b128 v[180:183], v9 offset:768
	v_add_f32_e32 v158, 1.0, v158
	v_cmp_gt_f32_e32 vcc, s71, v158
	s_nop 1
	v_cndmask_b32_e64 v160, 0, 32, vcc
	v_ldexp_f32 v158, v158, v160
	v_log_f32_e32 v158, v158
	s_nop 0
	v_mul_f32_e32 v160, 0x3f317217, v158
	v_fma_f32 v160, v158, s48, -v160
	v_fmac_f32_e32 v160, 0x3377d1cf, v158
	v_fmac_f32_e32 v160, 0x3f317217, v158
	v_cmp_lt_f32_e64 s[0:1], |v158|, s49
	s_nop 1
	v_cndmask_b32_e64 v158, v158, v160, s[0:1]
	v_cndmask_b32_e32 v160, 0, v233, vcc
	v_sub_f32_e32 v158, v158, v160
	v_sub_f32_e32 v158, v159, v158
	v_mul_f32_e32 v178, 0x3d800000, v158
	v_fmac_f32_e32 v141, 0x3d800000, v158
	s_waitcnt lgkmcnt(0)
	v_mul_f32_e32 v158, v5, v181
	v_fmac_f32_e32 v158, v4, v180
	v_fmac_f32_e32 v158, v6, v182
	v_fmac_f32_e32 v158, v7, v183
	ds_read_b128 v[180:183], v9 offset:784
	v_add_f32_e32 v158, v157, v158
	s_waitcnt lgkmcnt(0)
	v_mul_f32_e32 v159, v154, v181
	v_fmac_f32_e32 v159, v228, v180
	v_fmac_f32_e32 v159, v155, v182
	v_fmac_f32_e32 v159, v156, v183
	ds_read_b128 v[180:183], v9 offset:800
	v_add_f32_e32 v158, v158, v159
	s_waitcnt lgkmcnt(0)
	v_mul_f32_e32 v159, v252, v181
	v_fmac_f32_e32 v159, v146, v180
	v_fmac_f32_e32 v159, v253, v182
	v_fmac_f32_e32 v159, v227, v183
	ds_read_b128 v[180:183], v9 offset:816
	v_add_f32_e32 v158, v158, v159
	s_waitcnt lgkmcnt(0)
	v_mul_f32_e32 v159, v147, v181
	v_fmac_f32_e32 v159, v145, v180
	v_fmac_f32_e32 v159, v230, v182
	v_fmac_f32_e32 v159, v231, v183
	v_add_f32_e32 v158, v158, v159
	v_min_f32_e32 v159, 0, v158
	v_mul_f32_e64 v158, |v158|, s18
	v_exp_f32_e32 v158, v158
	ds_read_b128 v[180:183], v9 offset:896
	v_add_f32_e32 v158, 1.0, v158
	v_cmp_gt_f32_e32 vcc, s71, v158
	s_nop 1
	v_cndmask_b32_e64 v160, 0, 32, vcc
	v_ldexp_f32 v158, v158, v160
	v_log_f32_e32 v158, v158
	s_nop 0
	v_mul_f32_e32 v160, 0x3f317217, v158
	v_fma_f32 v160, v158, s48, -v160
	v_fmac_f32_e32 v160, 0x3377d1cf, v158
	v_fmac_f32_e32 v160, 0x3f317217, v158
	v_cmp_lt_f32_e64 s[0:1], |v158|, s49
	s_nop 1
	v_cndmask_b32_e64 v158, v158, v160, s[0:1]
	v_cndmask_b32_e32 v160, 0, v233, vcc
	v_sub_f32_e32 v158, v158, v160
	v_sub_f32_e32 v158, v159, v158
	v_mul_f32_e32 v179, 0x3d800000, v158
	v_fmac_f32_e32 v141, 0x3d800000, v158
	s_waitcnt lgkmcnt(0)
	v_mul_f32_e32 v158, v5, v181
	v_fmac_f32_e32 v158, v4, v180
	v_fmac_f32_e32 v158, v6, v182
	v_fmac_f32_e32 v158, v7, v183
	ds_read_b128 v[180:183], v9 offset:912
	v_add_f32_e32 v158, v157, v158
	s_waitcnt lgkmcnt(0)
	v_mul_f32_e32 v159, v154, v181
	v_fmac_f32_e32 v159, v228, v180
	v_fmac_f32_e32 v159, v155, v182
	v_fmac_f32_e32 v159, v156, v183
	ds_read_b128 v[180:183], v9 offset:928
	v_add_f32_e32 v158, v158, v159
	s_waitcnt lgkmcnt(0)
	v_mul_f32_e32 v159, v252, v181
	v_fmac_f32_e32 v159, v146, v180
	v_fmac_f32_e32 v159, v253, v182
	v_fmac_f32_e32 v159, v227, v183
	ds_read_b128 v[180:183], v9 offset:944
	v_add_f32_e32 v158, v158, v159
	s_waitcnt lgkmcnt(0)
	v_mul_f32_e32 v159, v147, v181
	v_fmac_f32_e32 v159, v145, v180
	v_fmac_f32_e32 v159, v230, v182
	v_fmac_f32_e32 v159, v231, v183
	v_add_f32_e32 v158, v158, v159
	v_min_f32_e32 v159, 0, v158
	v_mul_f32_e64 v158, |v158|, s18
	v_exp_f32_e32 v158, v158
	ds_read_b128 v[182:185], v9 offset:1024
	v_add_f32_e32 v158, 1.0, v158
	v_cmp_gt_f32_e32 vcc, s71, v158
	s_nop 1
	v_cndmask_b32_e64 v160, 0, 32, vcc
	v_ldexp_f32 v158, v158, v160
	v_log_f32_e32 v158, v158
	s_nop 0
	v_mul_f32_e32 v160, 0x3f317217, v158
	v_fma_f32 v160, v158, s48, -v160
	v_fmac_f32_e32 v160, 0x3377d1cf, v158
	v_fmac_f32_e32 v160, 0x3f317217, v158
	v_cmp_lt_f32_e64 s[0:1], |v158|, s49
	s_nop 1
	v_cndmask_b32_e64 v158, v158, v160, s[0:1]
	v_cndmask_b32_e32 v160, 0, v233, vcc
	v_sub_f32_e32 v158, v158, v160
	v_sub_f32_e32 v158, v159, v158
	v_mul_f32_e32 v180, 0x3d800000, v158
	v_fmac_f32_e32 v141, 0x3d800000, v158
	s_waitcnt lgkmcnt(0)
	v_mul_f32_e32 v158, v5, v183
	v_fmac_f32_e32 v158, v4, v182
	v_fmac_f32_e32 v158, v6, v184
	v_fmac_f32_e32 v158, v7, v185
	ds_read_b128 v[182:185], v9 offset:1040
	v_add_f32_e32 v158, v157, v158
	s_waitcnt lgkmcnt(0)
	v_mul_f32_e32 v159, v154, v183
	v_fmac_f32_e32 v159, v228, v182
	v_fmac_f32_e32 v159, v155, v184
	v_fmac_f32_e32 v159, v156, v185
	ds_read_b128 v[182:185], v9 offset:1056
	v_add_f32_e32 v158, v158, v159
	s_waitcnt lgkmcnt(0)
	v_mul_f32_e32 v159, v252, v183
	v_fmac_f32_e32 v159, v146, v182
	v_fmac_f32_e32 v159, v253, v184
	v_fmac_f32_e32 v159, v227, v185
	ds_read_b128 v[182:185], v9 offset:1072
	v_add_f32_e32 v158, v158, v159
	s_waitcnt lgkmcnt(0)
	v_mul_f32_e32 v159, v147, v183
	v_fmac_f32_e32 v159, v145, v182
	v_fmac_f32_e32 v159, v230, v184
	v_fmac_f32_e32 v159, v231, v185
	v_add_f32_e32 v158, v158, v159
	v_min_f32_e32 v159, 0, v158
	v_mul_f32_e64 v158, |v158|, s18
	v_exp_f32_e32 v158, v158
	ds_read_b128 v[182:185], v9 offset:1152
	v_add_f32_e32 v158, 1.0, v158
	v_cmp_gt_f32_e32 vcc, s71, v158
	s_nop 1
	v_cndmask_b32_e64 v160, 0, 32, vcc
	v_ldexp_f32 v158, v158, v160
	v_log_f32_e32 v158, v158
	s_nop 0
	v_mul_f32_e32 v160, 0x3f317217, v158
	v_fma_f32 v160, v158, s48, -v160
	v_fmac_f32_e32 v160, 0x3377d1cf, v158
	v_fmac_f32_e32 v160, 0x3f317217, v158
	v_cmp_lt_f32_e64 s[0:1], |v158|, s49
	s_nop 1
	v_cndmask_b32_e64 v158, v158, v160, s[0:1]
	v_cndmask_b32_e32 v160, 0, v233, vcc
	v_sub_f32_e32 v158, v158, v160
	v_sub_f32_e32 v158, v159, v158
	v_mul_f32_e32 v181, 0x3d800000, v158
	v_fmac_f32_e32 v141, 0x3d800000, v158
	s_waitcnt lgkmcnt(0)
	v_mul_f32_e32 v158, v5, v183
	v_fmac_f32_e32 v158, v4, v182
	v_fmac_f32_e32 v158, v6, v184
	v_fmac_f32_e32 v158, v7, v185
	ds_read_b128 v[182:185], v9 offset:1168
	v_add_f32_e32 v158, v157, v158
	s_waitcnt lgkmcnt(0)
	v_mul_f32_e32 v159, v154, v183
	v_fmac_f32_e32 v159, v228, v182
	v_fmac_f32_e32 v159, v155, v184
	v_fmac_f32_e32 v159, v156, v185
	ds_read_b128 v[182:185], v9 offset:1184
	v_add_f32_e32 v158, v158, v159
	s_waitcnt lgkmcnt(0)
	v_mul_f32_e32 v159, v252, v183
	v_fmac_f32_e32 v159, v146, v182
	v_fmac_f32_e32 v159, v253, v184
	v_fmac_f32_e32 v159, v227, v185
	ds_read_b128 v[182:185], v9 offset:1200
	v_add_f32_e32 v158, v158, v159
	s_waitcnt lgkmcnt(0)
	v_mul_f32_e32 v159, v147, v183
	v_fmac_f32_e32 v159, v145, v182
	v_fmac_f32_e32 v159, v230, v184
	v_fmac_f32_e32 v159, v231, v185
	v_add_f32_e32 v158, v158, v159
	v_min_f32_e32 v159, 0, v158
	v_mul_f32_e64 v158, |v158|, s18
	v_exp_f32_e32 v158, v158
	ds_read_b128 v[184:187], v9 offset:1280
	v_add_f32_e32 v158, 1.0, v158
	v_cmp_gt_f32_e32 vcc, s71, v158
	s_nop 1
	v_cndmask_b32_e64 v160, 0, 32, vcc
	v_ldexp_f32 v158, v158, v160
	v_log_f32_e32 v158, v158
	s_nop 0
	v_mul_f32_e32 v160, 0x3f317217, v158
	v_fma_f32 v160, v158, s48, -v160
	v_fmac_f32_e32 v160, 0x3377d1cf, v158
	v_fmac_f32_e32 v160, 0x3f317217, v158
	v_cmp_lt_f32_e64 s[0:1], |v158|, s49
	s_nop 1
	v_cndmask_b32_e64 v158, v158, v160, s[0:1]
	v_cndmask_b32_e32 v160, 0, v233, vcc
	v_sub_f32_e32 v158, v158, v160
	v_sub_f32_e32 v158, v159, v158
	v_mul_f32_e32 v182, 0x3d800000, v158
	v_fmac_f32_e32 v141, 0x3d800000, v158
	s_waitcnt lgkmcnt(0)
	v_mul_f32_e32 v158, v5, v185
	v_fmac_f32_e32 v158, v4, v184
	v_fmac_f32_e32 v158, v6, v186
	v_fmac_f32_e32 v158, v7, v187
	ds_read_b128 v[184:187], v9 offset:1296
	v_add_f32_e32 v158, v157, v158
	s_waitcnt lgkmcnt(0)
	v_mul_f32_e32 v159, v154, v185
	v_fmac_f32_e32 v159, v228, v184
	v_fmac_f32_e32 v159, v155, v186
	v_fmac_f32_e32 v159, v156, v187
	ds_read_b128 v[184:187], v9 offset:1312
	v_add_f32_e32 v158, v158, v159
	s_waitcnt lgkmcnt(0)
	v_mul_f32_e32 v159, v252, v185
	v_fmac_f32_e32 v159, v146, v184
	v_fmac_f32_e32 v159, v253, v186
	v_fmac_f32_e32 v159, v227, v187
	ds_read_b128 v[184:187], v9 offset:1328
	v_add_f32_e32 v158, v158, v159
	s_waitcnt lgkmcnt(0)
	v_mul_f32_e32 v159, v147, v185
	v_fmac_f32_e32 v159, v145, v184
	v_fmac_f32_e32 v159, v230, v186
	v_fmac_f32_e32 v159, v231, v187
	v_add_f32_e32 v158, v158, v159
	v_min_f32_e32 v159, 0, v158
	v_mul_f32_e64 v158, |v158|, s18
	v_exp_f32_e32 v158, v158
	ds_read_b128 v[184:187], v9 offset:1408
	v_add_f32_e32 v158, 1.0, v158
	v_cmp_gt_f32_e32 vcc, s71, v158
	s_nop 1
	v_cndmask_b32_e64 v160, 0, 32, vcc
	v_ldexp_f32 v158, v158, v160
	v_log_f32_e32 v158, v158
	s_nop 0
	v_mul_f32_e32 v160, 0x3f317217, v158
	v_fma_f32 v160, v158, s48, -v160
	v_fmac_f32_e32 v160, 0x3377d1cf, v158
	v_fmac_f32_e32 v160, 0x3f317217, v158
	v_cmp_lt_f32_e64 s[0:1], |v158|, s49
	s_nop 1
	v_cndmask_b32_e64 v158, v158, v160, s[0:1]
	v_cndmask_b32_e32 v160, 0, v233, vcc
	v_sub_f32_e32 v158, v158, v160
	v_sub_f32_e32 v158, v159, v158
	v_mul_f32_e32 v183, 0x3d800000, v158
	v_fmac_f32_e32 v141, 0x3d800000, v158
	s_waitcnt lgkmcnt(0)
	v_mul_f32_e32 v158, v5, v185
	v_fmac_f32_e32 v158, v4, v184
	v_fmac_f32_e32 v158, v6, v186
	v_fmac_f32_e32 v158, v7, v187
	ds_read_b128 v[184:187], v9 offset:1424
	v_add_f32_e32 v158, v157, v158
	s_waitcnt lgkmcnt(0)
	v_mul_f32_e32 v159, v154, v185
	v_fmac_f32_e32 v159, v228, v184
	v_fmac_f32_e32 v159, v155, v186
	v_fmac_f32_e32 v159, v156, v187
	ds_read_b128 v[184:187], v9 offset:1440
	v_add_f32_e32 v158, v158, v159
	s_waitcnt lgkmcnt(0)
	v_mul_f32_e32 v159, v252, v185
	v_fmac_f32_e32 v159, v146, v184
	v_fmac_f32_e32 v159, v253, v186
	v_fmac_f32_e32 v159, v227, v187
	ds_read_b128 v[184:187], v9 offset:1456
	v_add_f32_e32 v158, v158, v159
	s_waitcnt lgkmcnt(0)
	v_mul_f32_e32 v159, v147, v185
	v_fmac_f32_e32 v159, v145, v184
	v_fmac_f32_e32 v159, v230, v186
	v_fmac_f32_e32 v159, v231, v187
	v_add_f32_e32 v158, v158, v159
	v_min_f32_e32 v159, 0, v158
	v_mul_f32_e64 v158, |v158|, s18
	v_exp_f32_e32 v158, v158
	ds_read_b128 v[186:189], v9 offset:1536
	v_add_f32_e32 v158, 1.0, v158
	v_cmp_gt_f32_e32 vcc, s71, v158
	s_nop 1
	v_cndmask_b32_e64 v160, 0, 32, vcc
	v_ldexp_f32 v158, v158, v160
	v_log_f32_e32 v158, v158
	s_nop 0
	v_mul_f32_e32 v160, 0x3f317217, v158
	v_fma_f32 v160, v158, s48, -v160
	v_fmac_f32_e32 v160, 0x3377d1cf, v158
	v_fmac_f32_e32 v160, 0x3f317217, v158
	v_cmp_lt_f32_e64 s[0:1], |v158|, s49
	s_nop 1
	v_cndmask_b32_e64 v158, v158, v160, s[0:1]
	v_cndmask_b32_e32 v160, 0, v233, vcc
	v_sub_f32_e32 v158, v158, v160
	v_sub_f32_e32 v158, v159, v158
	v_mul_f32_e32 v184, 0x3d800000, v158
	v_fmac_f32_e32 v141, 0x3d800000, v158
	s_waitcnt lgkmcnt(0)
	v_mul_f32_e32 v158, v5, v187
	v_fmac_f32_e32 v158, v4, v186
	v_fmac_f32_e32 v158, v6, v188
	v_fmac_f32_e32 v158, v7, v189
	ds_read_b128 v[186:189], v9 offset:1552
	v_add_f32_e32 v158, v157, v158
	s_waitcnt lgkmcnt(0)
	v_mul_f32_e32 v159, v154, v187
	v_fmac_f32_e32 v159, v228, v186
	v_fmac_f32_e32 v159, v155, v188
	v_fmac_f32_e32 v159, v156, v189
	ds_read_b128 v[186:189], v9 offset:1568
	v_add_f32_e32 v158, v158, v159
	s_waitcnt lgkmcnt(0)
	v_mul_f32_e32 v159, v252, v187
	v_fmac_f32_e32 v159, v146, v186
	v_fmac_f32_e32 v159, v253, v188
	v_fmac_f32_e32 v159, v227, v189
	ds_read_b128 v[186:189], v9 offset:1584
	v_add_f32_e32 v158, v158, v159
	s_waitcnt lgkmcnt(0)
	v_mul_f32_e32 v159, v147, v187
	v_fmac_f32_e32 v159, v145, v186
	v_fmac_f32_e32 v159, v230, v188
	v_fmac_f32_e32 v159, v231, v189
	v_add_f32_e32 v158, v158, v159
	v_min_f32_e32 v159, 0, v158
	v_mul_f32_e64 v158, |v158|, s18
	v_exp_f32_e32 v158, v158
	ds_read_b128 v[186:189], v9 offset:1664
	v_add_f32_e32 v158, 1.0, v158
	v_cmp_gt_f32_e32 vcc, s71, v158
	s_nop 1
	v_cndmask_b32_e64 v160, 0, 32, vcc
	v_ldexp_f32 v158, v158, v160
	v_log_f32_e32 v158, v158
	s_nop 0
	v_mul_f32_e32 v160, 0x3f317217, v158
	v_fma_f32 v160, v158, s48, -v160
	v_fmac_f32_e32 v160, 0x3377d1cf, v158
	v_fmac_f32_e32 v160, 0x3f317217, v158
	v_cmp_lt_f32_e64 s[0:1], |v158|, s49
	s_nop 1
	v_cndmask_b32_e64 v158, v158, v160, s[0:1]
	v_cndmask_b32_e32 v160, 0, v233, vcc
	v_sub_f32_e32 v158, v158, v160
	v_sub_f32_e32 v158, v159, v158
	v_mul_f32_e32 v185, 0x3d800000, v158
	v_fmac_f32_e32 v141, 0x3d800000, v158
	s_waitcnt lgkmcnt(0)
	v_mul_f32_e32 v158, v5, v187
	v_fmac_f32_e32 v158, v4, v186
	v_fmac_f32_e32 v158, v6, v188
	v_fmac_f32_e32 v158, v7, v189
	ds_read_b128 v[186:189], v9 offset:1680
	v_add_f32_e32 v158, v157, v158
	s_waitcnt lgkmcnt(0)
	v_mul_f32_e32 v159, v154, v187
	v_fmac_f32_e32 v159, v228, v186
	v_fmac_f32_e32 v159, v155, v188
	v_fmac_f32_e32 v159, v156, v189
	ds_read_b128 v[186:189], v9 offset:1696
	v_add_f32_e32 v158, v158, v159
	s_waitcnt lgkmcnt(0)
	v_mul_f32_e32 v159, v252, v187
	v_fmac_f32_e32 v159, v146, v186
	v_fmac_f32_e32 v159, v253, v188
	v_fmac_f32_e32 v159, v227, v189
	ds_read_b128 v[186:189], v9 offset:1712
	v_add_f32_e32 v158, v158, v159
	s_waitcnt lgkmcnt(0)
	v_mul_f32_e32 v159, v147, v187
	v_fmac_f32_e32 v159, v145, v186
	v_fmac_f32_e32 v159, v230, v188
	v_fmac_f32_e32 v159, v231, v189
	v_add_f32_e32 v158, v158, v159
	v_min_f32_e32 v159, 0, v158
	v_mul_f32_e64 v158, |v158|, s18
	v_exp_f32_e32 v158, v158
	ds_read_b128 v[188:191], v9 offset:1792
	v_add_f32_e32 v158, 1.0, v158
	v_cmp_gt_f32_e32 vcc, s71, v158
	s_nop 1
	v_cndmask_b32_e64 v160, 0, 32, vcc
	v_ldexp_f32 v158, v158, v160
	v_log_f32_e32 v158, v158
	s_nop 0
	v_mul_f32_e32 v160, 0x3f317217, v158
	v_fma_f32 v160, v158, s48, -v160
	v_fmac_f32_e32 v160, 0x3377d1cf, v158
	v_fmac_f32_e32 v160, 0x3f317217, v158
	v_cmp_lt_f32_e64 s[0:1], |v158|, s49
	s_nop 1
	v_cndmask_b32_e64 v158, v158, v160, s[0:1]
	v_cndmask_b32_e32 v160, 0, v233, vcc
	v_sub_f32_e32 v158, v158, v160
	v_sub_f32_e32 v158, v159, v158
	v_mul_f32_e32 v186, 0x3d800000, v158
	v_fmac_f32_e32 v141, 0x3d800000, v158
	s_waitcnt lgkmcnt(0)
	v_mul_f32_e32 v158, v5, v189
	v_fmac_f32_e32 v158, v4, v188
	v_fmac_f32_e32 v158, v6, v190
	v_fmac_f32_e32 v158, v7, v191
	ds_read_b128 v[188:191], v9 offset:1808
	v_add_f32_e32 v158, v157, v158
	s_waitcnt lgkmcnt(0)
	v_mul_f32_e32 v159, v154, v189
	v_fmac_f32_e32 v159, v228, v188
	v_fmac_f32_e32 v159, v155, v190
	v_fmac_f32_e32 v159, v156, v191
	ds_read_b128 v[188:191], v9 offset:1824
	v_add_f32_e32 v158, v158, v159
	s_waitcnt lgkmcnt(0)
	v_mul_f32_e32 v159, v252, v189
	v_fmac_f32_e32 v159, v146, v188
	v_fmac_f32_e32 v159, v253, v190
	v_fmac_f32_e32 v159, v227, v191
	ds_read_b128 v[188:191], v9 offset:1840
	v_add_f32_e32 v158, v158, v159
	s_waitcnt lgkmcnt(0)
	v_mul_f32_e32 v159, v147, v189
	v_fmac_f32_e32 v159, v145, v188
	v_fmac_f32_e32 v159, v230, v190
	v_fmac_f32_e32 v159, v231, v191
	v_add_f32_e32 v158, v158, v159
	v_min_f32_e32 v159, 0, v158
	v_mul_f32_e64 v158, |v158|, s18
	v_exp_f32_e32 v158, v158
	ds_read_b128 v[188:191], v9 offset:1920
	v_add_f32_e32 v158, 1.0, v158
	v_cmp_gt_f32_e32 vcc, s71, v158
	s_nop 1
	v_cndmask_b32_e64 v160, 0, 32, vcc
	v_ldexp_f32 v158, v158, v160
	v_log_f32_e32 v158, v158
	s_nop 0
	v_mul_f32_e32 v160, 0x3f317217, v158
	v_fma_f32 v160, v158, s48, -v160
	v_fmac_f32_e32 v160, 0x3377d1cf, v158
	v_fmac_f32_e32 v160, 0x3f317217, v158
	v_cmp_lt_f32_e64 s[0:1], |v158|, s49
	s_nop 1
	v_cndmask_b32_e64 v158, v158, v160, s[0:1]
	v_cndmask_b32_e32 v160, 0, v233, vcc
	v_sub_f32_e32 v158, v158, v160
	v_sub_f32_e32 v158, v159, v158
	v_mul_f32_e32 v187, 0x3d800000, v158
	v_fmac_f32_e32 v141, 0x3d800000, v158
	s_waitcnt lgkmcnt(0)
	v_mul_f32_e32 v158, v5, v189
	v_fmac_f32_e32 v158, v4, v188
	v_fmac_f32_e32 v158, v6, v190
	v_fmac_f32_e32 v158, v7, v191
	ds_read_b128 v[188:191], v9 offset:1936
	v_add_f32_e32 v158, v157, v158
	s_waitcnt lgkmcnt(0)
	v_mul_f32_e32 v159, v154, v189
	v_fmac_f32_e32 v159, v228, v188
	v_fmac_f32_e32 v159, v155, v190
	v_fmac_f32_e32 v159, v156, v191
	ds_read_b128 v[188:191], v9 offset:1952
	v_add_f32_e32 v158, v158, v159
	s_waitcnt lgkmcnt(0)
	v_mul_f32_e32 v159, v252, v189
	v_fmac_f32_e32 v159, v146, v188
	v_fmac_f32_e32 v159, v253, v190
	v_fmac_f32_e32 v159, v227, v191
	ds_read_b128 v[188:191], v9 offset:1968
	v_add_f32_e32 v158, v158, v159
	s_waitcnt lgkmcnt(0)
	v_mul_f32_e32 v159, v147, v189
	v_fmac_f32_e32 v159, v145, v188
	v_fmac_f32_e32 v159, v230, v190
	v_fmac_f32_e32 v159, v231, v191
	v_add_f32_e32 v158, v158, v159
	v_min_f32_e32 v159, 0, v158
	v_mul_f32_e64 v158, |v158|, s18
	v_exp_f32_e32 v158, v158
	ds_read_b128 v[190:193], v9 offset:2048
	v_add_f32_e32 v158, 1.0, v158
	v_cmp_gt_f32_e32 vcc, s71, v158
	s_nop 1
	v_cndmask_b32_e64 v160, 0, 32, vcc
	v_ldexp_f32 v158, v158, v160
	v_log_f32_e32 v158, v158
	s_nop 0
	v_mul_f32_e32 v160, 0x3f317217, v158
	v_fma_f32 v160, v158, s48, -v160
	v_fmac_f32_e32 v160, 0x3377d1cf, v158
	v_fmac_f32_e32 v160, 0x3f317217, v158
	v_cmp_lt_f32_e64 s[0:1], |v158|, s49
	s_nop 1
	v_cndmask_b32_e64 v158, v158, v160, s[0:1]
	v_cndmask_b32_e32 v160, 0, v233, vcc
	v_sub_f32_e32 v158, v158, v160
	v_sub_f32_e32 v158, v159, v158
	v_mul_f32_e32 v188, 0x3d800000, v158
	v_fmac_f32_e32 v141, 0x3d800000, v158
	s_waitcnt lgkmcnt(0)
	v_mul_f32_e32 v158, v5, v191
	v_fmac_f32_e32 v158, v4, v190
	v_fmac_f32_e32 v158, v6, v192
	v_fmac_f32_e32 v158, v7, v193
	ds_read_b128 v[190:193], v9 offset:2064
	v_add_f32_e32 v158, v157, v158
	s_waitcnt lgkmcnt(0)
	v_mul_f32_e32 v159, v154, v191
	v_fmac_f32_e32 v159, v228, v190
	v_fmac_f32_e32 v159, v155, v192
	v_fmac_f32_e32 v159, v156, v193
	ds_read_b128 v[190:193], v9 offset:2080
	v_add_f32_e32 v158, v158, v159
	s_waitcnt lgkmcnt(0)
	v_mul_f32_e32 v159, v252, v191
	v_fmac_f32_e32 v159, v146, v190
	v_fmac_f32_e32 v159, v253, v192
	v_fmac_f32_e32 v159, v227, v193
	ds_read_b128 v[190:193], v9 offset:2096
	v_add_f32_e32 v158, v158, v159
	s_waitcnt lgkmcnt(0)
	v_mul_f32_e32 v159, v147, v191
	v_fmac_f32_e32 v159, v145, v190
	v_fmac_f32_e32 v159, v230, v192
	v_fmac_f32_e32 v159, v231, v193
	v_add_f32_e32 v158, v158, v159
	v_min_f32_e32 v159, 0, v158
	v_mul_f32_e64 v158, |v158|, s18
	v_exp_f32_e32 v158, v158
	ds_read_b128 v[190:193], v9 offset:2176
	v_add_f32_e32 v158, 1.0, v158
	v_cmp_gt_f32_e32 vcc, s71, v158
	s_nop 1
	v_cndmask_b32_e64 v160, 0, 32, vcc
	v_ldexp_f32 v158, v158, v160
	v_log_f32_e32 v158, v158
	s_nop 0
	v_mul_f32_e32 v160, 0x3f317217, v158
	v_fma_f32 v160, v158, s48, -v160
	v_fmac_f32_e32 v160, 0x3377d1cf, v158
	v_fmac_f32_e32 v160, 0x3f317217, v158
	v_cmp_lt_f32_e64 s[0:1], |v158|, s49
	s_nop 1
	v_cndmask_b32_e64 v158, v158, v160, s[0:1]
	v_cndmask_b32_e32 v160, 0, v233, vcc
	v_sub_f32_e32 v158, v158, v160
	v_sub_f32_e32 v158, v159, v158
	v_mul_f32_e32 v189, 0x3d800000, v158
	v_fmac_f32_e32 v141, 0x3d800000, v158
	s_waitcnt lgkmcnt(0)
	v_mul_f32_e32 v158, v5, v191
	v_fmac_f32_e32 v158, v4, v190
	v_fmac_f32_e32 v158, v6, v192
	v_fmac_f32_e32 v158, v7, v193
	ds_read_b128 v[190:193], v9 offset:2192
	v_add_f32_e32 v158, v157, v158
	s_waitcnt lgkmcnt(0)
	v_mul_f32_e32 v159, v154, v191
	v_fmac_f32_e32 v159, v228, v190
	v_fmac_f32_e32 v159, v155, v192
	v_fmac_f32_e32 v159, v156, v193
	ds_read_b128 v[190:193], v9 offset:2208
	v_add_f32_e32 v158, v158, v159
	s_waitcnt lgkmcnt(0)
	v_mul_f32_e32 v159, v252, v191
	v_fmac_f32_e32 v159, v146, v190
	v_fmac_f32_e32 v159, v253, v192
	v_fmac_f32_e32 v159, v227, v193
	ds_read_b128 v[190:193], v9 offset:2224
	v_add_f32_e32 v158, v158, v159
	s_waitcnt lgkmcnt(0)
	v_mul_f32_e32 v159, v147, v191
	v_fmac_f32_e32 v159, v145, v190
	v_fmac_f32_e32 v159, v230, v192
	v_fmac_f32_e32 v159, v231, v193
	v_add_f32_e32 v158, v158, v159
	v_min_f32_e32 v159, 0, v158
	v_mul_f32_e64 v158, |v158|, s18
	v_exp_f32_e32 v158, v158
	ds_read_b128 v[192:195], v9 offset:2304
	v_add_f32_e32 v158, 1.0, v158
	v_cmp_gt_f32_e32 vcc, s71, v158
	s_nop 1
	v_cndmask_b32_e64 v160, 0, 32, vcc
	v_ldexp_f32 v158, v158, v160
	v_log_f32_e32 v158, v158
	s_nop 0
	v_mul_f32_e32 v160, 0x3f317217, v158
	v_fma_f32 v160, v158, s48, -v160
	v_fmac_f32_e32 v160, 0x3377d1cf, v158
	v_fmac_f32_e32 v160, 0x3f317217, v158
	v_cmp_lt_f32_e64 s[0:1], |v158|, s49
	s_nop 1
	v_cndmask_b32_e64 v158, v158, v160, s[0:1]
	v_cndmask_b32_e32 v160, 0, v233, vcc
	v_sub_f32_e32 v158, v158, v160
	v_sub_f32_e32 v158, v159, v158
	v_mul_f32_e32 v190, 0x3d800000, v158
	v_fmac_f32_e32 v141, 0x3d800000, v158
	s_waitcnt lgkmcnt(0)
	v_mul_f32_e32 v158, v5, v193
	v_fmac_f32_e32 v158, v4, v192
	v_fmac_f32_e32 v158, v6, v194
	v_fmac_f32_e32 v158, v7, v195
	ds_read_b128 v[192:195], v9 offset:2320
	v_add_f32_e32 v158, v157, v158
	s_waitcnt lgkmcnt(0)
	v_mul_f32_e32 v159, v154, v193
	v_fmac_f32_e32 v159, v228, v192
	v_fmac_f32_e32 v159, v155, v194
	v_fmac_f32_e32 v159, v156, v195
	ds_read_b128 v[192:195], v9 offset:2336
	v_add_f32_e32 v158, v158, v159
	s_waitcnt lgkmcnt(0)
	v_mul_f32_e32 v159, v252, v193
	v_fmac_f32_e32 v159, v146, v192
	v_fmac_f32_e32 v159, v253, v194
	v_fmac_f32_e32 v159, v227, v195
	ds_read_b128 v[192:195], v9 offset:2352
	v_add_f32_e32 v158, v158, v159
	s_waitcnt lgkmcnt(0)
	v_mul_f32_e32 v159, v147, v193
	v_fmac_f32_e32 v159, v145, v192
	v_fmac_f32_e32 v159, v230, v194
	v_fmac_f32_e32 v159, v231, v195
	v_add_f32_e32 v158, v158, v159
	v_min_f32_e32 v159, 0, v158
	v_mul_f32_e64 v158, |v158|, s18
	v_exp_f32_e32 v158, v158
	ds_read_b128 v[192:195], v9 offset:2432
	v_add_f32_e32 v158, 1.0, v158
	v_cmp_gt_f32_e32 vcc, s71, v158
	s_nop 1
	v_cndmask_b32_e64 v160, 0, 32, vcc
	v_ldexp_f32 v158, v158, v160
	v_log_f32_e32 v158, v158
	s_nop 0
	v_mul_f32_e32 v160, 0x3f317217, v158
	v_fma_f32 v160, v158, s48, -v160
	v_fmac_f32_e32 v160, 0x3377d1cf, v158
	v_fmac_f32_e32 v160, 0x3f317217, v158
	v_cmp_lt_f32_e64 s[0:1], |v158|, s49
	s_nop 1
	v_cndmask_b32_e64 v158, v158, v160, s[0:1]
	v_cndmask_b32_e32 v160, 0, v233, vcc
	v_sub_f32_e32 v158, v158, v160
	v_sub_f32_e32 v158, v159, v158
	v_mul_f32_e32 v191, 0x3d800000, v158
	v_fmac_f32_e32 v141, 0x3d800000, v158
	s_waitcnt lgkmcnt(0)
	v_mul_f32_e32 v158, v5, v193
	v_fmac_f32_e32 v158, v4, v192
	v_fmac_f32_e32 v158, v6, v194
	v_fmac_f32_e32 v158, v7, v195
	ds_read_b128 v[192:195], v9 offset:2448
	v_add_f32_e32 v158, v157, v158
	s_waitcnt lgkmcnt(0)
	v_mul_f32_e32 v159, v154, v193
	v_fmac_f32_e32 v159, v228, v192
	v_fmac_f32_e32 v159, v155, v194
	v_fmac_f32_e32 v159, v156, v195
	ds_read_b128 v[192:195], v9 offset:2464
	v_add_f32_e32 v158, v158, v159
	s_waitcnt lgkmcnt(0)
	v_mul_f32_e32 v159, v252, v193
	v_fmac_f32_e32 v159, v146, v192
	v_fmac_f32_e32 v159, v253, v194
	v_fmac_f32_e32 v159, v227, v195
	ds_read_b128 v[192:195], v9 offset:2480
	v_add_f32_e32 v158, v158, v159
	s_waitcnt lgkmcnt(0)
	v_mul_f32_e32 v159, v147, v193
	v_fmac_f32_e32 v159, v145, v192
	v_fmac_f32_e32 v159, v230, v194
	v_fmac_f32_e32 v159, v231, v195
	v_add_f32_e32 v158, v158, v159
	v_min_f32_e32 v159, 0, v158
	v_mul_f32_e64 v158, |v158|, s18
	v_exp_f32_e32 v158, v158
	ds_read_b128 v[194:197], v9 offset:2560
	v_add_f32_e32 v158, 1.0, v158
	v_cmp_gt_f32_e32 vcc, s71, v158
	s_nop 1
	v_cndmask_b32_e64 v160, 0, 32, vcc
	v_ldexp_f32 v158, v158, v160
	v_log_f32_e32 v158, v158
	s_nop 0
	v_mul_f32_e32 v160, 0x3f317217, v158
	v_fma_f32 v160, v158, s48, -v160
	v_fmac_f32_e32 v160, 0x3377d1cf, v158
	v_fmac_f32_e32 v160, 0x3f317217, v158
	v_cmp_lt_f32_e64 s[0:1], |v158|, s49
	s_nop 1
	v_cndmask_b32_e64 v158, v158, v160, s[0:1]
	v_cndmask_b32_e32 v160, 0, v233, vcc
	v_sub_f32_e32 v158, v158, v160
	v_sub_f32_e32 v158, v159, v158
	v_mul_f32_e32 v192, 0x3d800000, v158
	v_fmac_f32_e32 v141, 0x3d800000, v158
	s_waitcnt lgkmcnt(0)
	v_mul_f32_e32 v158, v5, v195
	v_fmac_f32_e32 v158, v4, v194
	v_fmac_f32_e32 v158, v6, v196
	v_fmac_f32_e32 v158, v7, v197
	ds_read_b128 v[194:197], v9 offset:2576
	v_add_f32_e32 v158, v157, v158
	s_waitcnt lgkmcnt(0)
	v_mul_f32_e32 v159, v154, v195
	v_fmac_f32_e32 v159, v228, v194
	v_fmac_f32_e32 v159, v155, v196
	v_fmac_f32_e32 v159, v156, v197
	ds_read_b128 v[194:197], v9 offset:2592
	v_add_f32_e32 v158, v158, v159
	s_waitcnt lgkmcnt(0)
	v_mul_f32_e32 v159, v252, v195
	v_fmac_f32_e32 v159, v146, v194
	v_fmac_f32_e32 v159, v253, v196
	v_fmac_f32_e32 v159, v227, v197
	ds_read_b128 v[194:197], v9 offset:2608
	v_add_f32_e32 v158, v158, v159
	s_waitcnt lgkmcnt(0)
	v_mul_f32_e32 v159, v147, v195
	v_fmac_f32_e32 v159, v145, v194
	v_fmac_f32_e32 v159, v230, v196
	v_fmac_f32_e32 v159, v231, v197
	v_add_f32_e32 v158, v158, v159
	v_min_f32_e32 v159, 0, v158
	v_mul_f32_e64 v158, |v158|, s18
	v_exp_f32_e32 v158, v158
	ds_read_b128 v[194:197], v9 offset:2688
	v_add_f32_e32 v158, 1.0, v158
	v_cmp_gt_f32_e32 vcc, s71, v158
	s_nop 1
	v_cndmask_b32_e64 v160, 0, 32, vcc
	v_ldexp_f32 v158, v158, v160
	v_log_f32_e32 v158, v158
	s_nop 0
	v_mul_f32_e32 v160, 0x3f317217, v158
	v_fma_f32 v160, v158, s48, -v160
	v_fmac_f32_e32 v160, 0x3377d1cf, v158
	v_fmac_f32_e32 v160, 0x3f317217, v158
	v_cmp_lt_f32_e64 s[0:1], |v158|, s49
	s_nop 1
	v_cndmask_b32_e64 v158, v158, v160, s[0:1]
	v_cndmask_b32_e32 v160, 0, v233, vcc
	v_sub_f32_e32 v158, v158, v160
	v_sub_f32_e32 v158, v159, v158
	v_mul_f32_e32 v193, 0x3d800000, v158
	v_fmac_f32_e32 v141, 0x3d800000, v158
	s_waitcnt lgkmcnt(0)
	v_mul_f32_e32 v158, v5, v195
	v_fmac_f32_e32 v158, v4, v194
	v_fmac_f32_e32 v158, v6, v196
	v_fmac_f32_e32 v158, v7, v197
	ds_read_b128 v[194:197], v9 offset:2704
	v_add_f32_e32 v158, v157, v158
	s_waitcnt lgkmcnt(0)
	v_mul_f32_e32 v159, v154, v195
	v_fmac_f32_e32 v159, v228, v194
	v_fmac_f32_e32 v159, v155, v196
	v_fmac_f32_e32 v159, v156, v197
	ds_read_b128 v[194:197], v9 offset:2720
	v_add_f32_e32 v158, v158, v159
	s_waitcnt lgkmcnt(0)
	v_mul_f32_e32 v159, v252, v195
	v_fmac_f32_e32 v159, v146, v194
	v_fmac_f32_e32 v159, v253, v196
	v_fmac_f32_e32 v159, v227, v197
	ds_read_b128 v[194:197], v9 offset:2736
	v_add_f32_e32 v158, v158, v159
	s_waitcnt lgkmcnt(0)
	v_mul_f32_e32 v159, v147, v195
	v_fmac_f32_e32 v159, v145, v194
	v_fmac_f32_e32 v159, v230, v196
	v_fmac_f32_e32 v159, v231, v197
	v_add_f32_e32 v158, v158, v159
	v_min_f32_e32 v159, 0, v158
	v_mul_f32_e64 v158, |v158|, s18
	v_exp_f32_e32 v158, v158
	ds_read_b128 v[196:199], v9 offset:2816
	v_add_f32_e32 v158, 1.0, v158
	v_cmp_gt_f32_e32 vcc, s71, v158
	s_nop 1
	v_cndmask_b32_e64 v160, 0, 32, vcc
	v_ldexp_f32 v158, v158, v160
	v_log_f32_e32 v158, v158
	s_nop 0
	v_mul_f32_e32 v160, 0x3f317217, v158
	v_fma_f32 v160, v158, s48, -v160
	v_fmac_f32_e32 v160, 0x3377d1cf, v158
	v_fmac_f32_e32 v160, 0x3f317217, v158
	v_cmp_lt_f32_e64 s[0:1], |v158|, s49
	s_nop 1
	v_cndmask_b32_e64 v158, v158, v160, s[0:1]
	v_cndmask_b32_e32 v160, 0, v233, vcc
	v_sub_f32_e32 v158, v158, v160
	v_sub_f32_e32 v158, v159, v158
	v_mul_f32_e32 v194, 0x3d800000, v158
	v_fmac_f32_e32 v141, 0x3d800000, v158
	s_waitcnt lgkmcnt(0)
	v_mul_f32_e32 v158, v5, v197
	v_fmac_f32_e32 v158, v4, v196
	v_fmac_f32_e32 v158, v6, v198
	v_fmac_f32_e32 v158, v7, v199
	ds_read_b128 v[196:199], v9 offset:2832
	v_add_f32_e32 v158, v157, v158
	s_waitcnt lgkmcnt(0)
	v_mul_f32_e32 v159, v154, v197
	v_fmac_f32_e32 v159, v228, v196
	v_fmac_f32_e32 v159, v155, v198
	v_fmac_f32_e32 v159, v156, v199
	ds_read_b128 v[196:199], v9 offset:2848
	v_add_f32_e32 v158, v158, v159
	s_waitcnt lgkmcnt(0)
	v_mul_f32_e32 v159, v252, v197
	v_fmac_f32_e32 v159, v146, v196
	v_fmac_f32_e32 v159, v253, v198
	v_fmac_f32_e32 v159, v227, v199
	ds_read_b128 v[196:199], v9 offset:2864
	v_add_f32_e32 v158, v158, v159
	s_waitcnt lgkmcnt(0)
	v_mul_f32_e32 v159, v147, v197
	v_fmac_f32_e32 v159, v145, v196
	v_fmac_f32_e32 v159, v230, v198
	v_fmac_f32_e32 v159, v231, v199
	v_add_f32_e32 v158, v158, v159
	v_min_f32_e32 v159, 0, v158
	v_mul_f32_e64 v158, |v158|, s18
	v_exp_f32_e32 v158, v158
	ds_read_b128 v[196:199], v9 offset:2944
	v_add_f32_e32 v158, 1.0, v158
	v_cmp_gt_f32_e32 vcc, s71, v158
	s_nop 1
	v_cndmask_b32_e64 v160, 0, 32, vcc
	v_ldexp_f32 v158, v158, v160
	v_log_f32_e32 v158, v158
	s_nop 0
	v_mul_f32_e32 v160, 0x3f317217, v158
	v_fma_f32 v160, v158, s48, -v160
	v_fmac_f32_e32 v160, 0x3377d1cf, v158
	v_fmac_f32_e32 v160, 0x3f317217, v158
	v_cmp_lt_f32_e64 s[0:1], |v158|, s49
	s_nop 1
	v_cndmask_b32_e64 v158, v158, v160, s[0:1]
	v_cndmask_b32_e32 v160, 0, v233, vcc
	v_sub_f32_e32 v158, v158, v160
	v_sub_f32_e32 v158, v159, v158
	v_mul_f32_e32 v195, 0x3d800000, v158
	v_fmac_f32_e32 v141, 0x3d800000, v158
	s_waitcnt lgkmcnt(0)
	v_mul_f32_e32 v158, v5, v197
	v_fmac_f32_e32 v158, v4, v196
	v_fmac_f32_e32 v158, v6, v198
	v_fmac_f32_e32 v158, v7, v199
	ds_read_b128 v[196:199], v9 offset:2960
	v_add_f32_e32 v158, v157, v158
	s_waitcnt lgkmcnt(0)
	v_mul_f32_e32 v159, v154, v197
	v_fmac_f32_e32 v159, v228, v196
	v_fmac_f32_e32 v159, v155, v198
	v_fmac_f32_e32 v159, v156, v199
	ds_read_b128 v[196:199], v9 offset:2976
	v_add_f32_e32 v158, v158, v159
	s_waitcnt lgkmcnt(0)
	v_mul_f32_e32 v159, v252, v197
	v_fmac_f32_e32 v159, v146, v196
	v_fmac_f32_e32 v159, v253, v198
	v_fmac_f32_e32 v159, v227, v199
	ds_read_b128 v[196:199], v9 offset:2992
	v_add_f32_e32 v158, v158, v159
	s_waitcnt lgkmcnt(0)
	v_mul_f32_e32 v159, v147, v197
	v_fmac_f32_e32 v159, v145, v196
	v_fmac_f32_e32 v159, v230, v198
	v_fmac_f32_e32 v159, v231, v199
	v_add_f32_e32 v158, v158, v159
	v_min_f32_e32 v159, 0, v158
	v_mul_f32_e64 v158, |v158|, s18
	v_exp_f32_e32 v158, v158
	ds_read_b128 v[198:201], v9 offset:3072
	v_add_f32_e32 v158, 1.0, v158
	v_cmp_gt_f32_e32 vcc, s71, v158
	s_nop 1
	v_cndmask_b32_e64 v160, 0, 32, vcc
	v_ldexp_f32 v158, v158, v160
	v_log_f32_e32 v158, v158
	s_nop 0
	v_mul_f32_e32 v160, 0x3f317217, v158
	v_fma_f32 v160, v158, s48, -v160
	v_fmac_f32_e32 v160, 0x3377d1cf, v158
	v_fmac_f32_e32 v160, 0x3f317217, v158
	v_cmp_lt_f32_e64 s[0:1], |v158|, s49
	s_nop 1
	v_cndmask_b32_e64 v158, v158, v160, s[0:1]
	v_cndmask_b32_e32 v160, 0, v233, vcc
	v_sub_f32_e32 v158, v158, v160
	v_sub_f32_e32 v158, v159, v158
	v_mul_f32_e32 v196, 0x3d800000, v158
	v_fmac_f32_e32 v141, 0x3d800000, v158
	s_waitcnt lgkmcnt(0)
	v_mul_f32_e32 v158, v5, v199
	v_fmac_f32_e32 v158, v4, v198
	v_fmac_f32_e32 v158, v6, v200
	v_fmac_f32_e32 v158, v7, v201
	ds_read_b128 v[198:201], v9 offset:3088
	v_add_f32_e32 v158, v157, v158
	s_waitcnt lgkmcnt(0)
	v_mul_f32_e32 v159, v154, v199
	v_fmac_f32_e32 v159, v228, v198
	v_fmac_f32_e32 v159, v155, v200
	v_fmac_f32_e32 v159, v156, v201
	ds_read_b128 v[198:201], v9 offset:3104
	v_add_f32_e32 v158, v158, v159
	s_waitcnt lgkmcnt(0)
	v_mul_f32_e32 v159, v252, v199
	v_fmac_f32_e32 v159, v146, v198
	v_fmac_f32_e32 v159, v253, v200
	v_fmac_f32_e32 v159, v227, v201
	ds_read_b128 v[198:201], v9 offset:3120
	v_add_f32_e32 v158, v158, v159
	s_waitcnt lgkmcnt(0)
	v_mul_f32_e32 v159, v147, v199
	v_fmac_f32_e32 v159, v145, v198
	v_fmac_f32_e32 v159, v230, v200
	v_fmac_f32_e32 v159, v231, v201
	v_add_f32_e32 v158, v158, v159
	v_min_f32_e32 v159, 0, v158
	v_mul_f32_e64 v158, |v158|, s18
	v_exp_f32_e32 v158, v158
	ds_read_b128 v[198:201], v9 offset:3200
	v_add_f32_e32 v158, 1.0, v158
	v_cmp_gt_f32_e32 vcc, s71, v158
	s_nop 1
	v_cndmask_b32_e64 v160, 0, 32, vcc
	v_ldexp_f32 v158, v158, v160
	v_log_f32_e32 v158, v158
	s_nop 0
	v_mul_f32_e32 v160, 0x3f317217, v158
	v_fma_f32 v160, v158, s48, -v160
	v_fmac_f32_e32 v160, 0x3377d1cf, v158
	v_fmac_f32_e32 v160, 0x3f317217, v158
	v_cmp_lt_f32_e64 s[0:1], |v158|, s49
	s_nop 1
	v_cndmask_b32_e64 v158, v158, v160, s[0:1]
	v_cndmask_b32_e32 v160, 0, v233, vcc
	v_sub_f32_e32 v158, v158, v160
	v_sub_f32_e32 v158, v159, v158
	v_mul_f32_e32 v197, 0x3d800000, v158
	v_fmac_f32_e32 v141, 0x3d800000, v158
	s_waitcnt lgkmcnt(0)
	v_mul_f32_e32 v158, v5, v199
	v_fmac_f32_e32 v158, v4, v198
	v_fmac_f32_e32 v158, v6, v200
	v_fmac_f32_e32 v158, v7, v201
	ds_read_b128 v[198:201], v9 offset:3216
	v_add_f32_e32 v158, v157, v158
	s_waitcnt lgkmcnt(0)
	v_mul_f32_e32 v159, v154, v199
	v_fmac_f32_e32 v159, v228, v198
	v_fmac_f32_e32 v159, v155, v200
	v_fmac_f32_e32 v159, v156, v201
	ds_read_b128 v[198:201], v9 offset:3232
	v_add_f32_e32 v158, v158, v159
	s_waitcnt lgkmcnt(0)
	v_mul_f32_e32 v159, v252, v199
	v_fmac_f32_e32 v159, v146, v198
	v_fmac_f32_e32 v159, v253, v200
	v_fmac_f32_e32 v159, v227, v201
	ds_read_b128 v[198:201], v9 offset:3248
	v_add_f32_e32 v158, v158, v159
	s_waitcnt lgkmcnt(0)
	v_mul_f32_e32 v159, v147, v199
	v_fmac_f32_e32 v159, v145, v198
	v_fmac_f32_e32 v159, v230, v200
	v_fmac_f32_e32 v159, v231, v201
	v_add_f32_e32 v158, v158, v159
	v_min_f32_e32 v159, 0, v158
	v_mul_f32_e64 v158, |v158|, s18
	v_exp_f32_e32 v158, v158
	ds_read_b128 v[200:203], v9 offset:3328
	v_add_f32_e32 v158, 1.0, v158
	v_cmp_gt_f32_e32 vcc, s71, v158
	s_nop 1
	v_cndmask_b32_e64 v160, 0, 32, vcc
	v_ldexp_f32 v158, v158, v160
	v_log_f32_e32 v158, v158
	s_nop 0
	v_mul_f32_e32 v160, 0x3f317217, v158
	v_fma_f32 v160, v158, s48, -v160
	v_fmac_f32_e32 v160, 0x3377d1cf, v158
	v_fmac_f32_e32 v160, 0x3f317217, v158
	v_cmp_lt_f32_e64 s[0:1], |v158|, s49
	s_nop 1
	v_cndmask_b32_e64 v158, v158, v160, s[0:1]
	v_cndmask_b32_e32 v160, 0, v233, vcc
	v_sub_f32_e32 v158, v158, v160
	v_sub_f32_e32 v158, v159, v158
	v_mul_f32_e32 v198, 0x3d800000, v158
	v_fmac_f32_e32 v141, 0x3d800000, v158
	s_waitcnt lgkmcnt(0)
	v_mul_f32_e32 v158, v5, v201
	v_fmac_f32_e32 v158, v4, v200
	v_fmac_f32_e32 v158, v6, v202
	v_fmac_f32_e32 v158, v7, v203
	ds_read_b128 v[200:203], v9 offset:3344
	v_add_f32_e32 v158, v157, v158
	s_waitcnt lgkmcnt(0)
	v_mul_f32_e32 v159, v154, v201
	v_fmac_f32_e32 v159, v228, v200
	v_fmac_f32_e32 v159, v155, v202
	v_fmac_f32_e32 v159, v156, v203
	ds_read_b128 v[200:203], v9 offset:3360
	v_add_f32_e32 v158, v158, v159
	s_waitcnt lgkmcnt(0)
	v_mul_f32_e32 v159, v252, v201
	v_fmac_f32_e32 v159, v146, v200
	v_fmac_f32_e32 v159, v253, v202
	v_fmac_f32_e32 v159, v227, v203
	ds_read_b128 v[200:203], v9 offset:3376
	v_add_f32_e32 v158, v158, v159
	s_waitcnt lgkmcnt(0)
	v_mul_f32_e32 v159, v147, v201
	v_fmac_f32_e32 v159, v145, v200
	v_fmac_f32_e32 v159, v230, v202
	v_fmac_f32_e32 v159, v231, v203
	v_add_f32_e32 v158, v158, v159
	v_min_f32_e32 v159, 0, v158
	v_mul_f32_e64 v158, |v158|, s18
	v_exp_f32_e32 v158, v158
	ds_read_b128 v[200:203], v9 offset:3456
	v_add_f32_e32 v158, 1.0, v158
	v_cmp_gt_f32_e32 vcc, s71, v158
	s_nop 1
	v_cndmask_b32_e64 v160, 0, 32, vcc
	v_ldexp_f32 v158, v158, v160
	v_log_f32_e32 v158, v158
	s_nop 0
	v_mul_f32_e32 v160, 0x3f317217, v158
	v_fma_f32 v160, v158, s48, -v160
	v_fmac_f32_e32 v160, 0x3377d1cf, v158
	v_fmac_f32_e32 v160, 0x3f317217, v158
	v_cmp_lt_f32_e64 s[0:1], |v158|, s49
	s_nop 1
	v_cndmask_b32_e64 v158, v158, v160, s[0:1]
	v_cndmask_b32_e32 v160, 0, v233, vcc
	v_sub_f32_e32 v158, v158, v160
	v_sub_f32_e32 v158, v159, v158
	v_mul_f32_e32 v199, 0x3d800000, v158
	v_fmac_f32_e32 v141, 0x3d800000, v158
	s_waitcnt lgkmcnt(0)
	v_mul_f32_e32 v158, v5, v201
	v_fmac_f32_e32 v158, v4, v200
	v_fmac_f32_e32 v158, v6, v202
	v_fmac_f32_e32 v158, v7, v203
	ds_read_b128 v[200:203], v9 offset:3472
	v_add_f32_e32 v158, v157, v158
	s_waitcnt lgkmcnt(0)
	v_mul_f32_e32 v159, v154, v201
	v_fmac_f32_e32 v159, v228, v200
	v_fmac_f32_e32 v159, v155, v202
	v_fmac_f32_e32 v159, v156, v203
	ds_read_b128 v[200:203], v9 offset:3488
	v_add_f32_e32 v158, v158, v159
	s_waitcnt lgkmcnt(0)
	v_mul_f32_e32 v159, v252, v201
	v_fmac_f32_e32 v159, v146, v200
	v_fmac_f32_e32 v159, v253, v202
	v_fmac_f32_e32 v159, v227, v203
	ds_read_b128 v[200:203], v9 offset:3504
	v_add_f32_e32 v158, v158, v159
	s_waitcnt lgkmcnt(0)
	v_mul_f32_e32 v159, v147, v201
	v_fmac_f32_e32 v159, v145, v200
	v_fmac_f32_e32 v159, v230, v202
	v_fmac_f32_e32 v159, v231, v203
	v_add_f32_e32 v158, v158, v159
	v_min_f32_e32 v159, 0, v158
	v_mul_f32_e64 v158, |v158|, s18
	v_exp_f32_e32 v158, v158
	ds_read_b128 v[202:205], v9 offset:3584
	v_add_f32_e32 v158, 1.0, v158
	v_cmp_gt_f32_e32 vcc, s71, v158
	s_nop 1
	v_cndmask_b32_e64 v160, 0, 32, vcc
	v_ldexp_f32 v158, v158, v160
	v_log_f32_e32 v158, v158
	s_nop 0
	v_mul_f32_e32 v160, 0x3f317217, v158
	v_fma_f32 v160, v158, s48, -v160
	v_fmac_f32_e32 v160, 0x3377d1cf, v158
	v_fmac_f32_e32 v160, 0x3f317217, v158
	v_cmp_lt_f32_e64 s[0:1], |v158|, s49
	s_nop 1
	v_cndmask_b32_e64 v158, v158, v160, s[0:1]
	v_cndmask_b32_e32 v160, 0, v233, vcc
	v_sub_f32_e32 v158, v158, v160
	v_sub_f32_e32 v158, v159, v158
	v_mul_f32_e32 v200, 0x3d800000, v158
	v_fmac_f32_e32 v141, 0x3d800000, v158
	s_waitcnt lgkmcnt(0)
	v_mul_f32_e32 v158, v5, v203
	v_fmac_f32_e32 v158, v4, v202
	v_fmac_f32_e32 v158, v6, v204
	v_fmac_f32_e32 v158, v7, v205
	ds_read_b128 v[202:205], v9 offset:3600
	v_add_f32_e32 v158, v157, v158
	s_waitcnt lgkmcnt(0)
	v_mul_f32_e32 v159, v154, v203
	v_fmac_f32_e32 v159, v228, v202
	v_fmac_f32_e32 v159, v155, v204
	v_fmac_f32_e32 v159, v156, v205
	ds_read_b128 v[202:205], v9 offset:3616
	v_add_f32_e32 v158, v158, v159
	s_waitcnt lgkmcnt(0)
	v_mul_f32_e32 v159, v252, v203
	v_fmac_f32_e32 v159, v146, v202
	v_fmac_f32_e32 v159, v253, v204
	v_fmac_f32_e32 v159, v227, v205
	ds_read_b128 v[202:205], v9 offset:3632
	v_add_f32_e32 v158, v158, v159
	s_waitcnt lgkmcnt(0)
	v_mul_f32_e32 v159, v147, v203
	v_fmac_f32_e32 v159, v145, v202
	v_fmac_f32_e32 v159, v230, v204
	v_fmac_f32_e32 v159, v231, v205
	v_add_f32_e32 v158, v158, v159
	v_min_f32_e32 v159, 0, v158
	v_mul_f32_e64 v158, |v158|, s18
	v_exp_f32_e32 v158, v158
	ds_read_b128 v[202:205], v9 offset:3712
	v_add_f32_e32 v158, 1.0, v158
	v_cmp_gt_f32_e32 vcc, s71, v158
	s_nop 1
	v_cndmask_b32_e64 v160, 0, 32, vcc
	v_ldexp_f32 v158, v158, v160
	v_log_f32_e32 v158, v158
	s_nop 0
	v_mul_f32_e32 v160, 0x3f317217, v158
	v_fma_f32 v160, v158, s48, -v160
	v_fmac_f32_e32 v160, 0x3377d1cf, v158
	v_fmac_f32_e32 v160, 0x3f317217, v158
	v_cmp_lt_f32_e64 s[0:1], |v158|, s49
	s_nop 1
	v_cndmask_b32_e64 v158, v158, v160, s[0:1]
	v_cndmask_b32_e32 v160, 0, v233, vcc
	v_sub_f32_e32 v158, v158, v160
	v_sub_f32_e32 v158, v159, v158
	v_mul_f32_e32 v201, 0x3d800000, v158
	v_fmac_f32_e32 v141, 0x3d800000, v158
	s_waitcnt lgkmcnt(0)
	v_mul_f32_e32 v158, v5, v203
	v_fmac_f32_e32 v158, v4, v202
	v_fmac_f32_e32 v158, v6, v204
	v_fmac_f32_e32 v158, v7, v205
	ds_read_b128 v[202:205], v9 offset:3728
	v_add_f32_e32 v158, v157, v158
	s_waitcnt lgkmcnt(0)
	v_mul_f32_e32 v159, v154, v203
	v_fmac_f32_e32 v159, v228, v202
	v_fmac_f32_e32 v159, v155, v204
	v_fmac_f32_e32 v159, v156, v205
	ds_read_b128 v[202:205], v9 offset:3744
	v_add_f32_e32 v158, v158, v159
	s_waitcnt lgkmcnt(0)
	v_mul_f32_e32 v159, v252, v203
	v_fmac_f32_e32 v159, v146, v202
	v_fmac_f32_e32 v159, v253, v204
	v_fmac_f32_e32 v159, v227, v205
	ds_read_b128 v[202:205], v9 offset:3760
	v_add_f32_e32 v158, v158, v159
	s_waitcnt lgkmcnt(0)
	v_mul_f32_e32 v159, v147, v203
	v_fmac_f32_e32 v159, v145, v202
	v_fmac_f32_e32 v159, v230, v204
	v_fmac_f32_e32 v159, v231, v205
	v_add_f32_e32 v158, v158, v159
	v_min_f32_e32 v159, 0, v158
	v_mul_f32_e64 v158, |v158|, s18
	v_exp_f32_e32 v158, v158
	ds_read_b128 v[204:207], v9 offset:3840
	v_add_f32_e32 v158, 1.0, v158
	v_cmp_gt_f32_e32 vcc, s71, v158
	s_nop 1
	v_cndmask_b32_e64 v160, 0, 32, vcc
	v_ldexp_f32 v158, v158, v160
	v_log_f32_e32 v158, v158
	s_nop 0
	v_mul_f32_e32 v160, 0x3f317217, v158
	v_fma_f32 v160, v158, s48, -v160
	v_fmac_f32_e32 v160, 0x3377d1cf, v158
	v_fmac_f32_e32 v160, 0x3f317217, v158
	v_cmp_lt_f32_e64 s[0:1], |v158|, s49
	s_nop 1
	v_cndmask_b32_e64 v158, v158, v160, s[0:1]
	v_cndmask_b32_e32 v160, 0, v233, vcc
	v_sub_f32_e32 v158, v158, v160
	v_sub_f32_e32 v158, v159, v158
	v_mul_f32_e32 v202, 0x3d800000, v158
	v_fmac_f32_e32 v141, 0x3d800000, v158
	s_waitcnt lgkmcnt(0)
	v_mul_f32_e32 v158, v5, v205
	v_fmac_f32_e32 v158, v4, v204
	v_fmac_f32_e32 v158, v6, v206
	v_fmac_f32_e32 v158, v7, v207
	ds_read_b128 v[204:207], v9 offset:3856
	v_add_f32_e32 v158, v157, v158
	s_waitcnt lgkmcnt(0)
	v_mul_f32_e32 v159, v154, v205
	v_fmac_f32_e32 v159, v228, v204
	v_fmac_f32_e32 v159, v155, v206
	v_fmac_f32_e32 v159, v156, v207
	ds_read_b128 v[204:207], v9 offset:3872
	v_add_f32_e32 v158, v158, v159
	s_waitcnt lgkmcnt(0)
	v_mul_f32_e32 v159, v252, v205
	v_fmac_f32_e32 v159, v146, v204
	v_fmac_f32_e32 v159, v253, v206
	v_fmac_f32_e32 v159, v227, v207
	ds_read_b128 v[204:207], v9 offset:3888
	v_add_f32_e32 v158, v158, v159
	s_waitcnt lgkmcnt(0)
	v_mul_f32_e32 v159, v147, v205
	v_fmac_f32_e32 v159, v145, v204
	v_fmac_f32_e32 v159, v230, v206
	v_fmac_f32_e32 v159, v231, v207
	v_add_f32_e32 v158, v158, v159
	v_min_f32_e32 v159, 0, v158
	v_mul_f32_e64 v158, |v158|, s18
	v_exp_f32_e32 v158, v158
	ds_read_b128 v[204:207], v9 offset:3968
	v_add_f32_e32 v158, 1.0, v158
	v_cmp_gt_f32_e32 vcc, s71, v158
	s_nop 1
	v_cndmask_b32_e64 v160, 0, 32, vcc
	v_ldexp_f32 v158, v158, v160
	v_log_f32_e32 v158, v158
	s_nop 0
	v_mul_f32_e32 v160, 0x3f317217, v158
	v_fma_f32 v160, v158, s48, -v160
	v_fmac_f32_e32 v160, 0x3377d1cf, v158
	v_fmac_f32_e32 v160, 0x3f317217, v158
	v_cmp_lt_f32_e64 s[0:1], |v158|, s49
	s_nop 1
	v_cndmask_b32_e64 v158, v158, v160, s[0:1]
	v_cndmask_b32_e32 v160, 0, v233, vcc
	v_sub_f32_e32 v158, v158, v160
	v_sub_f32_e32 v158, v159, v158
	v_mul_f32_e32 v203, 0x3d800000, v158
	v_fmac_f32_e32 v141, 0x3d800000, v158
	s_waitcnt lgkmcnt(0)
	v_mul_f32_e32 v158, v5, v205
	v_fmac_f32_e32 v158, v4, v204
	v_fmac_f32_e32 v158, v6, v206
	v_fmac_f32_e32 v158, v7, v207
	ds_read_b128 v[204:207], v9 offset:3984
	v_add_f32_e32 v158, v157, v158
	s_waitcnt lgkmcnt(0)
	v_mul_f32_e32 v159, v154, v205
	v_fmac_f32_e32 v159, v228, v204
	v_fmac_f32_e32 v159, v155, v206
	v_fmac_f32_e32 v159, v156, v207
	ds_read_b128 v[204:207], v9 offset:4000
	v_add_f32_e32 v158, v158, v159
	s_waitcnt lgkmcnt(0)
	v_mul_f32_e32 v159, v252, v205
	v_fmac_f32_e32 v159, v146, v204
	v_fmac_f32_e32 v159, v253, v206
	v_fmac_f32_e32 v159, v227, v207
	ds_read_b128 v[204:207], v9 offset:4016
	v_add_f32_e32 v158, v158, v159
	s_waitcnt lgkmcnt(0)
	v_mul_f32_e32 v159, v147, v205
	v_fmac_f32_e32 v159, v145, v204
	v_fmac_f32_e32 v159, v230, v206
	v_fmac_f32_e32 v159, v231, v207
	v_add_f32_e32 v158, v158, v159
	v_min_f32_e32 v159, 0, v158
	v_mul_f32_e64 v158, |v158|, s18
	v_exp_f32_e32 v158, v158
	ds_read_b128 v[206:209], v9 offset:4096
	v_add_f32_e32 v158, 1.0, v158
	v_cmp_gt_f32_e32 vcc, s71, v158
	s_nop 1
	v_cndmask_b32_e64 v160, 0, 32, vcc
	v_ldexp_f32 v158, v158, v160
	v_log_f32_e32 v158, v158
	s_nop 0
	v_mul_f32_e32 v160, 0x3f317217, v158
	v_fma_f32 v160, v158, s48, -v160
	v_fmac_f32_e32 v160, 0x3377d1cf, v158
	v_fmac_f32_e32 v160, 0x3f317217, v158
	v_cmp_lt_f32_e64 s[0:1], |v158|, s49
	s_nop 1
	v_cndmask_b32_e64 v158, v158, v160, s[0:1]
	v_cndmask_b32_e32 v160, 0, v233, vcc
	v_sub_f32_e32 v158, v158, v160
	v_sub_f32_e32 v158, v159, v158
	v_mul_f32_e32 v204, 0x3d800000, v158
	v_fmac_f32_e32 v141, 0x3d800000, v158
	s_waitcnt lgkmcnt(0)
	v_mul_f32_e32 v158, v5, v207
	v_fmac_f32_e32 v158, v4, v206
	v_fmac_f32_e32 v158, v6, v208
	v_fmac_f32_e32 v158, v7, v209
	ds_read_b128 v[206:209], v9 offset:4112
	v_add_f32_e32 v158, v157, v158
	s_waitcnt lgkmcnt(0)
	v_mul_f32_e32 v159, v154, v207
	v_fmac_f32_e32 v159, v228, v206
	v_fmac_f32_e32 v159, v155, v208
	v_fmac_f32_e32 v159, v156, v209
	ds_read_b128 v[206:209], v9 offset:4128
	v_add_f32_e32 v158, v158, v159
	s_waitcnt lgkmcnt(0)
	v_mul_f32_e32 v159, v252, v207
	v_fmac_f32_e32 v159, v146, v206
	v_fmac_f32_e32 v159, v253, v208
	v_fmac_f32_e32 v159, v227, v209
	ds_read_b128 v[206:209], v9 offset:4144
	v_add_f32_e32 v158, v158, v159
	s_waitcnt lgkmcnt(0)
	v_mul_f32_e32 v159, v147, v207
	v_fmac_f32_e32 v159, v145, v206
	v_fmac_f32_e32 v159, v230, v208
	v_fmac_f32_e32 v159, v231, v209
	v_add_f32_e32 v158, v158, v159
	v_min_f32_e32 v159, 0, v158
	v_mul_f32_e64 v158, |v158|, s18
	v_exp_f32_e32 v158, v158
	ds_read_b128 v[206:209], v9 offset:4224
	v_add_f32_e32 v158, 1.0, v158
	v_cmp_gt_f32_e32 vcc, s71, v158
	s_nop 1
	v_cndmask_b32_e64 v160, 0, 32, vcc
	v_ldexp_f32 v158, v158, v160
	v_log_f32_e32 v158, v158
	s_nop 0
	v_mul_f32_e32 v160, 0x3f317217, v158
	v_fma_f32 v160, v158, s48, -v160
	v_fmac_f32_e32 v160, 0x3377d1cf, v158
	v_fmac_f32_e32 v160, 0x3f317217, v158
	v_cmp_lt_f32_e64 s[0:1], |v158|, s49
	s_nop 1
	v_cndmask_b32_e64 v158, v158, v160, s[0:1]
	v_cndmask_b32_e32 v160, 0, v233, vcc
	v_sub_f32_e32 v158, v158, v160
	v_sub_f32_e32 v158, v159, v158
	v_mul_f32_e32 v205, 0x3d800000, v158
	v_fmac_f32_e32 v141, 0x3d800000, v158
	s_waitcnt lgkmcnt(0)
	v_mul_f32_e32 v158, v5, v207
	v_fmac_f32_e32 v158, v4, v206
	v_fmac_f32_e32 v158, v6, v208
	v_fmac_f32_e32 v158, v7, v209
	ds_read_b128 v[206:209], v9 offset:4240
	v_add_f32_e32 v158, v157, v158
	s_waitcnt lgkmcnt(0)
	v_mul_f32_e32 v159, v154, v207
	v_fmac_f32_e32 v159, v228, v206
	v_fmac_f32_e32 v159, v155, v208
	v_fmac_f32_e32 v159, v156, v209
	ds_read_b128 v[206:209], v9 offset:4256
	v_add_f32_e32 v158, v158, v159
	s_waitcnt lgkmcnt(0)
	v_mul_f32_e32 v159, v252, v207
	v_fmac_f32_e32 v159, v146, v206
	v_fmac_f32_e32 v159, v253, v208
	v_fmac_f32_e32 v159, v227, v209
	ds_read_b128 v[206:209], v9 offset:4272
	v_add_f32_e32 v158, v158, v159
	s_waitcnt lgkmcnt(0)
	v_mul_f32_e32 v159, v147, v207
	v_fmac_f32_e32 v159, v145, v206
	v_fmac_f32_e32 v159, v230, v208
	v_fmac_f32_e32 v159, v231, v209
	v_add_f32_e32 v158, v158, v159
	v_min_f32_e32 v159, 0, v158
	v_mul_f32_e64 v158, |v158|, s18
	v_exp_f32_e32 v158, v158
	ds_read_b128 v[208:211], v9 offset:4352
	v_add_f32_e32 v158, 1.0, v158
	v_cmp_gt_f32_e32 vcc, s71, v158
	s_nop 1
	v_cndmask_b32_e64 v160, 0, 32, vcc
	v_ldexp_f32 v158, v158, v160
	v_log_f32_e32 v158, v158
	s_nop 0
	v_mul_f32_e32 v160, 0x3f317217, v158
	v_fma_f32 v160, v158, s48, -v160
	v_fmac_f32_e32 v160, 0x3377d1cf, v158
	v_fmac_f32_e32 v160, 0x3f317217, v158
	v_cmp_lt_f32_e64 s[0:1], |v158|, s49
	s_nop 1
	v_cndmask_b32_e64 v158, v158, v160, s[0:1]
	v_cndmask_b32_e32 v160, 0, v233, vcc
	v_sub_f32_e32 v158, v158, v160
	v_sub_f32_e32 v158, v159, v158
	v_mul_f32_e32 v207, 0x3d800000, v158
	v_fmac_f32_e32 v141, 0x3d800000, v158
	s_waitcnt lgkmcnt(0)
	v_mul_f32_e32 v158, v5, v209
	v_fmac_f32_e32 v158, v4, v208
	v_fmac_f32_e32 v158, v6, v210
	v_fmac_f32_e32 v158, v7, v211
	ds_read_b128 v[208:211], v9 offset:4368
	v_add_f32_e32 v158, v157, v158
	s_waitcnt lgkmcnt(0)
	v_mul_f32_e32 v159, v154, v209
	v_fmac_f32_e32 v159, v228, v208
	v_fmac_f32_e32 v159, v155, v210
	v_fmac_f32_e32 v159, v156, v211
	ds_read_b128 v[208:211], v9 offset:4384
	v_add_f32_e32 v158, v158, v159
	s_waitcnt lgkmcnt(0)
	v_mul_f32_e32 v159, v252, v209
	v_fmac_f32_e32 v159, v146, v208
	v_fmac_f32_e32 v159, v253, v210
	v_fmac_f32_e32 v159, v227, v211
	ds_read_b128 v[208:211], v9 offset:4400
	v_add_f32_e32 v158, v158, v159
	s_waitcnt lgkmcnt(0)
	v_mul_f32_e32 v159, v147, v209
	v_fmac_f32_e32 v159, v145, v208
	v_fmac_f32_e32 v159, v230, v210
	v_fmac_f32_e32 v159, v231, v211
	v_add_f32_e32 v158, v158, v159
	v_min_f32_e32 v159, 0, v158
	v_mul_f32_e64 v158, |v158|, s18
	v_exp_f32_e32 v158, v158
	s_nop 0
	v_add_f32_e32 v158, 1.0, v158
	v_cmp_gt_f32_e32 vcc, s71, v158
	s_nop 1
	v_cndmask_b32_e64 v160, 0, 32, vcc
	v_ldexp_f32 v158, v158, v160
	v_log_f32_e32 v158, v158
	s_nop 0
	v_mul_f32_e32 v160, 0x3f317217, v158
	v_fma_f32 v160, v158, s48, -v160
	v_fmac_f32_e32 v160, 0x3377d1cf, v158
	v_fmac_f32_e32 v160, 0x3f317217, v158
	v_cmp_lt_f32_e64 s[0:1], |v158|, s49
	s_nop 1
	v_cndmask_b32_e64 v158, v158, v160, s[0:1]
	v_cndmask_b32_e32 v160, 0, v233, vcc
	v_sub_f32_e32 v158, v158, v160
	v_sub_f32_e32 v158, v159, v158
	v_mul_f32_e32 v210, 0x3d800000, v158
	v_fmac_f32_e32 v141, 0x3d800000, v158
	v_mul_f32_e32 v158, v5, v213
	v_fmac_f32_e32 v158, v4, v212
	v_fmac_f32_e32 v158, v6, v214
	v_fmac_f32_e32 v158, v7, v215
	ds_read_b128 v[212:215], v9 offset:4496
	v_add_f32_e32 v158, v157, v158
	s_waitcnt lgkmcnt(0)
	v_mul_f32_e32 v159, v154, v213
	v_fmac_f32_e32 v159, v228, v212
	v_fmac_f32_e32 v159, v155, v214
	v_fmac_f32_e32 v159, v156, v215
	ds_read_b128 v[212:215], v9 offset:4512
	v_add_f32_e32 v158, v158, v159
	s_waitcnt lgkmcnt(0)
	v_mul_f32_e32 v159, v252, v213
	v_fmac_f32_e32 v159, v146, v212
	v_fmac_f32_e32 v159, v253, v214
	v_fmac_f32_e32 v159, v227, v215
	ds_read_b128 v[212:215], v9 offset:4528
	v_add_f32_e32 v158, v158, v159
	s_waitcnt lgkmcnt(0)
	v_mul_f32_e32 v159, v147, v213
	v_fmac_f32_e32 v159, v145, v212
	v_fmac_f32_e32 v159, v230, v214
	v_fmac_f32_e32 v159, v231, v215
	v_add_f32_e32 v158, v158, v159
	v_min_f32_e32 v159, 0, v158
	v_mul_f32_e64 v158, |v158|, s18
	v_exp_f32_e32 v158, v158
	ds_read_b128 v[214:217], v9 offset:4608
	v_add_f32_e32 v158, 1.0, v158
	v_cmp_gt_f32_e32 vcc, s71, v158
	s_nop 1
	v_cndmask_b32_e64 v160, 0, 32, vcc
	v_ldexp_f32 v158, v158, v160
	v_log_f32_e32 v158, v158
	s_nop 0
	v_mul_f32_e32 v160, 0x3f317217, v158
	v_fma_f32 v160, v158, s48, -v160
	v_fmac_f32_e32 v160, 0x3377d1cf, v158
	v_fmac_f32_e32 v160, 0x3f317217, v158
	v_cmp_lt_f32_e64 s[0:1], |v158|, s49
	s_nop 1
	v_cndmask_b32_e64 v158, v158, v160, s[0:1]
	v_cndmask_b32_e32 v160, 0, v233, vcc
	v_sub_f32_e32 v158, v158, v160
	v_sub_f32_e32 v158, v159, v158
	v_mul_f32_e32 v212, 0x3d800000, v158
	v_fmac_f32_e32 v141, 0x3d800000, v158
	s_waitcnt lgkmcnt(0)
	v_mul_f32_e32 v158, v5, v215
	v_fmac_f32_e32 v158, v4, v214
	v_fmac_f32_e32 v158, v6, v216
	v_fmac_f32_e32 v158, v7, v217
	ds_read_b128 v[214:217], v9 offset:4624
	v_add_f32_e32 v158, v157, v158
	s_waitcnt lgkmcnt(0)
	v_mul_f32_e32 v159, v154, v215
	v_fmac_f32_e32 v159, v228, v214
	v_fmac_f32_e32 v159, v155, v216
	v_fmac_f32_e32 v159, v156, v217
	ds_read_b128 v[214:217], v9 offset:4640
	v_add_f32_e32 v158, v158, v159
	s_waitcnt lgkmcnt(0)
	v_mul_f32_e32 v159, v252, v215
	v_fmac_f32_e32 v159, v146, v214
	v_fmac_f32_e32 v159, v253, v216
	v_fmac_f32_e32 v159, v227, v217
	ds_read_b128 v[214:217], v9 offset:4656
	v_add_f32_e32 v158, v158, v159
	s_waitcnt lgkmcnt(0)
	v_mul_f32_e32 v159, v147, v215
	v_fmac_f32_e32 v159, v145, v214
	v_fmac_f32_e32 v159, v230, v216
	v_fmac_f32_e32 v159, v231, v217
	v_add_f32_e32 v158, v158, v159
	v_min_f32_e32 v159, 0, v158
	v_mul_f32_e64 v158, |v158|, s18
	v_exp_f32_e32 v158, v158
	ds_read_b128 v[214:217], v9 offset:4736
	v_add_f32_e32 v158, 1.0, v158
	v_cmp_gt_f32_e32 vcc, s71, v158
	s_nop 1
	v_cndmask_b32_e64 v160, 0, 32, vcc
	v_ldexp_f32 v158, v158, v160
	v_log_f32_e32 v158, v158
	s_nop 0
	v_mul_f32_e32 v160, 0x3f317217, v158
	v_fma_f32 v160, v158, s48, -v160
	v_fmac_f32_e32 v160, 0x3377d1cf, v158
	v_fmac_f32_e32 v160, 0x3f317217, v158
	v_cmp_lt_f32_e64 s[0:1], |v158|, s49
	s_nop 1
	v_cndmask_b32_e64 v158, v158, v160, s[0:1]
	v_cndmask_b32_e32 v160, 0, v233, vcc
	v_sub_f32_e32 v158, v158, v160
	v_sub_f32_e32 v158, v159, v158
	v_mul_f32_e32 v206, 0x3d800000, v158
	v_fmac_f32_e32 v141, 0x3d800000, v158
	s_waitcnt lgkmcnt(0)
	v_mul_f32_e32 v158, v5, v215
	v_fmac_f32_e32 v158, v4, v214
	v_fmac_f32_e32 v158, v6, v216
	v_fmac_f32_e32 v158, v7, v217
	ds_read_b128 v[214:217], v9 offset:4752
	v_add_f32_e32 v158, v157, v158
	s_waitcnt lgkmcnt(0)
	v_mul_f32_e32 v159, v154, v215
	v_fmac_f32_e32 v159, v228, v214
	v_fmac_f32_e32 v159, v155, v216
	v_fmac_f32_e32 v159, v156, v217
	ds_read_b128 v[214:217], v9 offset:4768
	v_add_f32_e32 v158, v158, v159
	s_waitcnt lgkmcnt(0)
	v_mul_f32_e32 v159, v252, v215
	v_fmac_f32_e32 v159, v146, v214
	v_fmac_f32_e32 v159, v253, v216
	v_fmac_f32_e32 v159, v227, v217
	ds_read_b128 v[214:217], v9 offset:4784
	v_add_f32_e32 v158, v158, v159
	s_waitcnt lgkmcnt(0)
	v_mul_f32_e32 v159, v147, v215
	v_fmac_f32_e32 v159, v145, v214
	v_fmac_f32_e32 v159, v230, v216
	v_fmac_f32_e32 v159, v231, v217
	v_add_f32_e32 v158, v158, v159
	v_min_f32_e32 v159, 0, v158
	v_mul_f32_e64 v158, |v158|, s18
	v_exp_f32_e32 v158, v158
	ds_read_b128 v[214:217], v9 offset:4864
	v_add_f32_e32 v158, 1.0, v158
	v_cmp_gt_f32_e32 vcc, s71, v158
	s_nop 1
	v_cndmask_b32_e64 v160, 0, 32, vcc
	v_ldexp_f32 v158, v158, v160
	v_log_f32_e32 v158, v158
	s_nop 0
	v_mul_f32_e32 v160, 0x3f317217, v158
	v_fma_f32 v160, v158, s48, -v160
	v_fmac_f32_e32 v160, 0x3377d1cf, v158
	v_fmac_f32_e32 v160, 0x3f317217, v158
	v_cmp_lt_f32_e64 s[0:1], |v158|, s49
	s_nop 1
	v_cndmask_b32_e64 v158, v158, v160, s[0:1]
	v_cndmask_b32_e32 v160, 0, v233, vcc
	v_sub_f32_e32 v158, v158, v160
	v_sub_f32_e32 v158, v159, v158
	v_mul_f32_e32 v209, 0x3d800000, v158
	v_fmac_f32_e32 v141, 0x3d800000, v158
	s_waitcnt lgkmcnt(0)
	v_mul_f32_e32 v158, v5, v215
	v_fmac_f32_e32 v158, v4, v214
	v_fmac_f32_e32 v158, v6, v216
	v_fmac_f32_e32 v158, v7, v217
	ds_read_b128 v[214:217], v9 offset:4880
	v_add_f32_e32 v158, v157, v158
	s_waitcnt lgkmcnt(0)
	v_mul_f32_e32 v159, v154, v215
	v_fmac_f32_e32 v159, v228, v214
	v_fmac_f32_e32 v159, v155, v216
	v_fmac_f32_e32 v159, v156, v217
	ds_read_b128 v[214:217], v9 offset:4896
	v_add_f32_e32 v158, v158, v159
	s_waitcnt lgkmcnt(0)
	v_mul_f32_e32 v159, v252, v215
	v_fmac_f32_e32 v159, v146, v214
	v_fmac_f32_e32 v159, v253, v216
	v_fmac_f32_e32 v159, v227, v217
	ds_read_b128 v[214:217], v9 offset:4912
	v_add_f32_e32 v158, v158, v159
	s_waitcnt lgkmcnt(0)
	v_mul_f32_e32 v159, v147, v215
	v_fmac_f32_e32 v159, v145, v214
	v_fmac_f32_e32 v159, v230, v216
	v_fmac_f32_e32 v159, v231, v217
	v_add_f32_e32 v158, v158, v159
	v_min_f32_e32 v159, 0, v158
	v_mul_f32_e64 v158, |v158|, s18
	v_exp_f32_e32 v158, v158
	s_nop 0
	v_add_f32_e32 v158, 1.0, v158
	v_cmp_gt_f32_e32 vcc, s71, v158
	s_nop 1
	v_cndmask_b32_e64 v160, 0, 32, vcc
	v_ldexp_f32 v158, v158, v160
	v_log_f32_e32 v158, v158
	s_nop 0
	v_mul_f32_e32 v160, 0x3f317217, v158
	v_fma_f32 v160, v158, s48, -v160
	v_fmac_f32_e32 v160, 0x3377d1cf, v158
	v_fmac_f32_e32 v160, 0x3f317217, v158
	v_cmp_lt_f32_e64 s[0:1], |v158|, s49
	s_nop 1
	v_cndmask_b32_e64 v158, v158, v160, s[0:1]
	v_cndmask_b32_e32 v160, 0, v233, vcc
	v_sub_f32_e32 v158, v158, v160
	v_sub_f32_e32 v158, v159, v158
	v_mul_f32_e32 v214, 0x3d800000, v158
	v_fmac_f32_e32 v141, 0x3d800000, v158
	v_mul_f32_e32 v158, v5, v235
	v_fmac_f32_e32 v158, v4, v234
	v_fmac_f32_e32 v158, v6, v236
	v_fmac_f32_e32 v158, v7, v237
	ds_read_b128 v[234:237], v9 offset:5008
	v_add_f32_e32 v158, v157, v158
	s_waitcnt lgkmcnt(0)
	v_mul_f32_e32 v159, v154, v235
	v_fmac_f32_e32 v159, v228, v234
	v_fmac_f32_e32 v159, v155, v236
	v_fmac_f32_e32 v159, v156, v237
	ds_read_b128 v[234:237], v9 offset:5024
	v_add_f32_e32 v158, v158, v159
	s_waitcnt lgkmcnt(0)
	v_mul_f32_e32 v159, v252, v235
	v_fmac_f32_e32 v159, v146, v234
	v_fmac_f32_e32 v159, v253, v236
	v_fmac_f32_e32 v159, v227, v237
	ds_read_b128 v[234:237], v9 offset:5040
	v_add_f32_e32 v158, v158, v159
	s_waitcnt lgkmcnt(0)
	v_mul_f32_e32 v159, v147, v235
	v_fmac_f32_e32 v159, v145, v234
	v_fmac_f32_e32 v159, v230, v236
	v_fmac_f32_e32 v159, v231, v237
	v_add_f32_e32 v158, v158, v159
	v_min_f32_e32 v159, 0, v158
	v_mul_f32_e64 v158, |v158|, s18
	v_exp_f32_e32 v158, v158
	ds_read_b128 v[234:237], v9 offset:5120
	v_add_f32_e32 v158, 1.0, v158
	v_cmp_gt_f32_e32 vcc, s71, v158
	s_nop 1
	v_cndmask_b32_e64 v160, 0, 32, vcc
	v_ldexp_f32 v158, v158, v160
	v_log_f32_e32 v158, v158
	s_nop 0
	v_mul_f32_e32 v160, 0x3f317217, v158
	v_fma_f32 v160, v158, s48, -v160
	v_fmac_f32_e32 v160, 0x3377d1cf, v158
	v_fmac_f32_e32 v160, 0x3f317217, v158
	v_cmp_lt_f32_e64 s[0:1], |v158|, s49
	s_nop 1
	v_cndmask_b32_e64 v158, v158, v160, s[0:1]
	v_cndmask_b32_e32 v160, 0, v233, vcc
	v_sub_f32_e32 v158, v158, v160
	v_sub_f32_e32 v158, v159, v158
	v_mul_f32_e32 v216, 0x3d800000, v158
	v_fmac_f32_e32 v141, 0x3d800000, v158
	s_waitcnt lgkmcnt(0)
	v_mul_f32_e32 v158, v5, v235
	v_fmac_f32_e32 v158, v4, v234
	v_fmac_f32_e32 v158, v6, v236
	v_fmac_f32_e32 v158, v7, v237
	ds_read_b128 v[234:237], v9 offset:5136
	v_add_f32_e32 v158, v157, v158
	s_waitcnt lgkmcnt(0)
	v_mul_f32_e32 v159, v154, v235
	v_fmac_f32_e32 v159, v228, v234
	v_fmac_f32_e32 v159, v155, v236
	v_fmac_f32_e32 v159, v156, v237
	ds_read_b128 v[234:237], v9 offset:5152
	v_add_f32_e32 v158, v158, v159
	s_waitcnt lgkmcnt(0)
	v_mul_f32_e32 v159, v252, v235
	v_fmac_f32_e32 v159, v146, v234
	v_fmac_f32_e32 v159, v253, v236
	v_fmac_f32_e32 v159, v227, v237
	ds_read_b128 v[234:237], v9 offset:5168
	v_add_f32_e32 v158, v158, v159
	s_waitcnt lgkmcnt(0)
	v_mul_f32_e32 v159, v147, v235
	v_fmac_f32_e32 v159, v145, v234
	v_fmac_f32_e32 v159, v230, v236
	v_fmac_f32_e32 v159, v231, v237
	v_add_f32_e32 v158, v158, v159
	v_min_f32_e32 v159, 0, v158
	v_mul_f32_e64 v158, |v158|, s18
	v_exp_f32_e32 v158, v158
	ds_read_b128 v[234:237], v9 offset:5248
	v_add_f32_e32 v158, 1.0, v158
	v_cmp_gt_f32_e32 vcc, s71, v158
	s_nop 1
	v_cndmask_b32_e64 v160, 0, 32, vcc
	v_ldexp_f32 v158, v158, v160
	v_log_f32_e32 v158, v158
	s_nop 0
	v_mul_f32_e32 v160, 0x3f317217, v158
	v_fma_f32 v160, v158, s48, -v160
	v_fmac_f32_e32 v160, 0x3377d1cf, v158
	v_fmac_f32_e32 v160, 0x3f317217, v158
	v_cmp_lt_f32_e64 s[0:1], |v158|, s49
	s_nop 1
	v_cndmask_b32_e64 v158, v158, v160, s[0:1]
	v_cndmask_b32_e32 v160, 0, v233, vcc
	v_sub_f32_e32 v158, v158, v160
	v_sub_f32_e32 v158, v159, v158
	v_mul_f32_e32 v208, 0x3d800000, v158
	v_fmac_f32_e32 v141, 0x3d800000, v158
	s_waitcnt lgkmcnt(0)
	v_mul_f32_e32 v158, v5, v235
	v_fmac_f32_e32 v158, v4, v234
	v_fmac_f32_e32 v158, v6, v236
	v_fmac_f32_e32 v158, v7, v237
	ds_read_b128 v[234:237], v9 offset:5264
	v_add_f32_e32 v158, v157, v158
	s_waitcnt lgkmcnt(0)
	v_mul_f32_e32 v159, v154, v235
	v_fmac_f32_e32 v159, v228, v234
	v_fmac_f32_e32 v159, v155, v236
	v_fmac_f32_e32 v159, v156, v237
	ds_read_b128 v[234:237], v9 offset:5280
	v_add_f32_e32 v158, v158, v159
	s_waitcnt lgkmcnt(0)
	v_mul_f32_e32 v159, v252, v235
	v_fmac_f32_e32 v159, v146, v234
	v_fmac_f32_e32 v159, v253, v236
	v_fmac_f32_e32 v159, v227, v237
	ds_read_b128 v[234:237], v9 offset:5296
	v_add_f32_e32 v158, v158, v159
	s_waitcnt lgkmcnt(0)
	v_mul_f32_e32 v159, v147, v235
	v_fmac_f32_e32 v159, v145, v234
	v_fmac_f32_e32 v159, v230, v236
	v_fmac_f32_e32 v159, v231, v237
	v_add_f32_e32 v158, v158, v159
	v_min_f32_e32 v159, 0, v158
	v_mul_f32_e64 v158, |v158|, s18
	v_exp_f32_e32 v158, v158
	ds_read_b128 v[234:237], v9 offset:5376
	v_add_f32_e32 v158, 1.0, v158
	v_cmp_gt_f32_e32 vcc, s71, v158
	s_nop 1
	v_cndmask_b32_e64 v160, 0, 32, vcc
	v_ldexp_f32 v158, v158, v160
	v_log_f32_e32 v158, v158
	s_nop 0
	v_mul_f32_e32 v160, 0x3f317217, v158
	v_fma_f32 v160, v158, s48, -v160
	v_fmac_f32_e32 v160, 0x3377d1cf, v158
	v_fmac_f32_e32 v160, 0x3f317217, v158
	v_cmp_lt_f32_e64 s[0:1], |v158|, s49
	s_nop 1
	v_cndmask_b32_e64 v158, v158, v160, s[0:1]
	v_cndmask_b32_e32 v160, 0, v233, vcc
	v_sub_f32_e32 v158, v158, v160
	v_sub_f32_e32 v158, v159, v158
	v_mul_f32_e32 v213, 0x3d800000, v158
	v_fmac_f32_e32 v141, 0x3d800000, v158
	s_waitcnt lgkmcnt(0)
	v_mul_f32_e32 v158, v5, v235
	v_fmac_f32_e32 v158, v4, v234
	v_fmac_f32_e32 v158, v6, v236
	v_fmac_f32_e32 v158, v7, v237
	ds_read_b128 v[234:237], v9 offset:5392
	v_add_f32_e32 v158, v157, v158
	s_waitcnt lgkmcnt(0)
	v_mul_f32_e32 v159, v154, v235
	v_fmac_f32_e32 v159, v228, v234
	v_fmac_f32_e32 v159, v155, v236
	v_fmac_f32_e32 v159, v156, v237
	ds_read_b128 v[234:237], v9 offset:5408
	v_add_f32_e32 v158, v158, v159
	s_waitcnt lgkmcnt(0)
	v_mul_f32_e32 v159, v252, v235
	v_fmac_f32_e32 v159, v146, v234
	v_fmac_f32_e32 v159, v253, v236
	v_fmac_f32_e32 v159, v227, v237
	ds_read_b128 v[234:237], v9 offset:5424
	v_add_f32_e32 v158, v158, v159
	s_waitcnt lgkmcnt(0)
	v_mul_f32_e32 v159, v147, v235
	v_fmac_f32_e32 v159, v145, v234
	v_fmac_f32_e32 v159, v230, v236
	v_fmac_f32_e32 v159, v231, v237
	v_add_f32_e32 v158, v158, v159
	v_min_f32_e32 v159, 0, v158
	v_mul_f32_e64 v158, |v158|, s18
	v_exp_f32_e32 v158, v158
	ds_read_b128 v[236:239], v9 offset:5504
	v_add_f32_e32 v158, 1.0, v158
	v_cmp_gt_f32_e32 vcc, s71, v158
	s_nop 1
	v_cndmask_b32_e64 v160, 0, 32, vcc
	v_ldexp_f32 v158, v158, v160
	v_log_f32_e32 v158, v158
	s_nop 0
	v_mul_f32_e32 v160, 0x3f317217, v158
	v_fma_f32 v160, v158, s48, -v160
	v_fmac_f32_e32 v160, 0x3377d1cf, v158
	v_fmac_f32_e32 v160, 0x3f317217, v158
	v_cmp_lt_f32_e64 s[0:1], |v158|, s49
	s_nop 1
	v_cndmask_b32_e64 v158, v158, v160, s[0:1]
	v_cndmask_b32_e32 v160, 0, v233, vcc
	v_sub_f32_e32 v158, v158, v160
	v_sub_f32_e32 v158, v159, v158
	v_mul_f32_e32 v234, 0x3d800000, v158
	v_fmac_f32_e32 v141, 0x3d800000, v158
	s_waitcnt lgkmcnt(0)
	v_mul_f32_e32 v158, v5, v237
	v_fmac_f32_e32 v158, v4, v236
	v_fmac_f32_e32 v158, v6, v238
	v_fmac_f32_e32 v158, v7, v239
	ds_read_b128 v[236:239], v9 offset:5520
	v_add_f32_e32 v158, v157, v158
	s_waitcnt lgkmcnt(0)
	v_mul_f32_e32 v159, v154, v237
	v_fmac_f32_e32 v159, v228, v236
	v_fmac_f32_e32 v159, v155, v238
	v_fmac_f32_e32 v159, v156, v239
	ds_read_b128 v[236:239], v9 offset:5536
	v_add_f32_e32 v158, v158, v159
	s_waitcnt lgkmcnt(0)
	v_mul_f32_e32 v159, v252, v237
	v_fmac_f32_e32 v159, v146, v236
	v_fmac_f32_e32 v159, v253, v238
	v_fmac_f32_e32 v159, v227, v239
	ds_read_b128 v[236:239], v9 offset:5552
	v_add_f32_e32 v158, v158, v159
	s_waitcnt lgkmcnt(0)
	v_mul_f32_e32 v159, v147, v237
	v_fmac_f32_e32 v159, v145, v236
	v_fmac_f32_e32 v159, v230, v238
	v_fmac_f32_e32 v159, v231, v239
	v_add_f32_e32 v158, v158, v159
	v_min_f32_e32 v159, 0, v158
	v_mul_f32_e64 v158, |v158|, s18
	v_exp_f32_e32 v158, v158
	ds_read_b128 v[238:241], v9 offset:5632
	v_add_f32_e32 v158, 1.0, v158
	v_cmp_gt_f32_e32 vcc, s71, v158
	s_nop 1
	v_cndmask_b32_e64 v160, 0, 32, vcc
	v_ldexp_f32 v158, v158, v160
	v_log_f32_e32 v158, v158
	s_nop 0
	v_mul_f32_e32 v160, 0x3f317217, v158
	v_fma_f32 v160, v158, s48, -v160
	v_fmac_f32_e32 v160, 0x3377d1cf, v158
	v_fmac_f32_e32 v160, 0x3f317217, v158
	v_cmp_lt_f32_e64 s[0:1], |v158|, s49
	s_nop 1
	v_cndmask_b32_e64 v158, v158, v160, s[0:1]
	v_cndmask_b32_e32 v160, 0, v233, vcc
	v_sub_f32_e32 v158, v158, v160
	v_sub_f32_e32 v158, v159, v158
	v_mul_f32_e32 v236, 0x3d800000, v158
	v_fmac_f32_e32 v141, 0x3d800000, v158
	s_waitcnt lgkmcnt(0)
	v_mul_f32_e32 v158, v5, v239
	v_fmac_f32_e32 v158, v4, v238
	v_fmac_f32_e32 v158, v6, v240
	v_fmac_f32_e32 v158, v7, v241
	ds_read_b128 v[238:241], v9 offset:5648
	v_add_f32_e32 v158, v157, v158
	s_waitcnt lgkmcnt(0)
	v_mul_f32_e32 v159, v154, v239
	v_fmac_f32_e32 v159, v228, v238
	v_fmac_f32_e32 v159, v155, v240
	v_fmac_f32_e32 v159, v156, v241
	ds_read_b128 v[238:241], v9 offset:5664
	v_add_f32_e32 v158, v158, v159
	s_waitcnt lgkmcnt(0)
	v_mul_f32_e32 v159, v252, v239
	v_fmac_f32_e32 v159, v146, v238
	v_fmac_f32_e32 v159, v253, v240
	v_fmac_f32_e32 v159, v227, v241
	ds_read_b128 v[238:241], v9 offset:5680
	v_add_f32_e32 v158, v158, v159
	s_waitcnt lgkmcnt(0)
	v_mul_f32_e32 v159, v147, v239
	v_fmac_f32_e32 v159, v145, v238
	v_fmac_f32_e32 v159, v230, v240
	v_fmac_f32_e32 v159, v231, v241
	v_add_f32_e32 v158, v158, v159
	v_min_f32_e32 v159, 0, v158
	v_mul_f32_e64 v158, |v158|, s18
	v_exp_f32_e32 v158, v158
	ds_read_b128 v[238:241], v9 offset:5760
	v_add_f32_e32 v158, 1.0, v158
	v_cmp_gt_f32_e32 vcc, s71, v158
	s_nop 1
	v_cndmask_b32_e64 v160, 0, 32, vcc
	v_ldexp_f32 v158, v158, v160
	v_log_f32_e32 v158, v158
	s_nop 0
	v_mul_f32_e32 v160, 0x3f317217, v158
	v_fma_f32 v160, v158, s48, -v160
	v_fmac_f32_e32 v160, 0x3377d1cf, v158
	v_fmac_f32_e32 v160, 0x3f317217, v158
	v_cmp_lt_f32_e64 s[0:1], |v158|, s49
	s_nop 1
	v_cndmask_b32_e64 v158, v158, v160, s[0:1]
	v_cndmask_b32_e32 v160, 0, v233, vcc
	v_sub_f32_e32 v158, v158, v160
	v_sub_f32_e32 v158, v159, v158
	v_mul_f32_e32 v211, 0x3d800000, v158
	v_fmac_f32_e32 v141, 0x3d800000, v158
	s_waitcnt lgkmcnt(0)
	v_mul_f32_e32 v158, v5, v239
	v_fmac_f32_e32 v158, v4, v238
	v_fmac_f32_e32 v158, v6, v240
	v_fmac_f32_e32 v158, v7, v241
	ds_read_b128 v[238:241], v9 offset:5776
	v_add_f32_e32 v158, v157, v158
	s_waitcnt lgkmcnt(0)
	v_mul_f32_e32 v159, v154, v239
	v_fmac_f32_e32 v159, v228, v238
	v_fmac_f32_e32 v159, v155, v240
	v_fmac_f32_e32 v159, v156, v241
	ds_read_b128 v[238:241], v9 offset:5792
	v_add_f32_e32 v158, v158, v159
	s_waitcnt lgkmcnt(0)
	v_mul_f32_e32 v159, v252, v239
	v_fmac_f32_e32 v159, v146, v238
	v_fmac_f32_e32 v159, v253, v240
	v_fmac_f32_e32 v159, v227, v241
	ds_read_b128 v[238:241], v9 offset:5808
	v_add_f32_e32 v158, v158, v159
	s_waitcnt lgkmcnt(0)
	v_mul_f32_e32 v159, v147, v239
	v_fmac_f32_e32 v159, v145, v238
	v_fmac_f32_e32 v159, v230, v240
	v_fmac_f32_e32 v159, v231, v241
	v_add_f32_e32 v158, v158, v159
	v_min_f32_e32 v159, 0, v158
	v_mul_f32_e64 v158, |v158|, s18
	v_exp_f32_e32 v158, v158
	ds_read_b128 v[238:241], v9 offset:5888
	v_add_f32_e32 v158, 1.0, v158
	v_cmp_gt_f32_e32 vcc, s71, v158
	s_nop 1
	v_cndmask_b32_e64 v160, 0, 32, vcc
	v_ldexp_f32 v158, v158, v160
	v_log_f32_e32 v158, v158
	s_nop 0
	v_mul_f32_e32 v160, 0x3f317217, v158
	v_fma_f32 v160, v158, s48, -v160
	v_fmac_f32_e32 v160, 0x3377d1cf, v158
	v_fmac_f32_e32 v160, 0x3f317217, v158
	v_cmp_lt_f32_e64 s[0:1], |v158|, s49
	s_nop 1
	v_cndmask_b32_e64 v158, v158, v160, s[0:1]
	v_cndmask_b32_e32 v160, 0, v233, vcc
	v_sub_f32_e32 v158, v158, v160
	v_sub_f32_e32 v158, v159, v158
	v_mul_f32_e32 v217, 0x3d800000, v158
	v_fmac_f32_e32 v141, 0x3d800000, v158
	s_waitcnt lgkmcnt(0)
	v_mul_f32_e32 v158, v5, v239
	v_fmac_f32_e32 v158, v4, v238
	v_fmac_f32_e32 v158, v6, v240
	v_fmac_f32_e32 v158, v7, v241
	ds_read_b128 v[238:241], v9 offset:5904
	v_add_f32_e32 v158, v157, v158
	s_waitcnt lgkmcnt(0)
	v_mul_f32_e32 v159, v154, v239
	v_fmac_f32_e32 v159, v228, v238
	v_fmac_f32_e32 v159, v155, v240
	v_fmac_f32_e32 v159, v156, v241
	ds_read_b128 v[238:241], v9 offset:5920
	v_add_f32_e32 v158, v158, v159
	s_waitcnt lgkmcnt(0)
	v_mul_f32_e32 v159, v252, v239
	v_fmac_f32_e32 v159, v146, v238
	v_fmac_f32_e32 v159, v253, v240
	v_fmac_f32_e32 v159, v227, v241
	ds_read_b128 v[238:241], v9 offset:5936
	v_add_f32_e32 v158, v158, v159
	s_waitcnt lgkmcnt(0)
	v_mul_f32_e32 v159, v147, v239
	v_fmac_f32_e32 v159, v145, v238
	v_fmac_f32_e32 v159, v230, v240
	v_fmac_f32_e32 v159, v231, v241
	v_add_f32_e32 v158, v158, v159
	v_min_f32_e32 v159, 0, v158
	v_mul_f32_e64 v158, |v158|, s18
	v_exp_f32_e32 v158, v158
	ds_read_b128 v[240:243], v9 offset:6016
	v_add_f32_e32 v158, 1.0, v158
	v_cmp_gt_f32_e32 vcc, s71, v158
	s_nop 1
	v_cndmask_b32_e64 v160, 0, 32, vcc
	v_ldexp_f32 v158, v158, v160
	v_log_f32_e32 v158, v158
	s_nop 0
	v_mul_f32_e32 v160, 0x3f317217, v158
	v_fma_f32 v160, v158, s48, -v160
	v_fmac_f32_e32 v160, 0x3377d1cf, v158
	v_fmac_f32_e32 v160, 0x3f317217, v158
	v_cmp_lt_f32_e64 s[0:1], |v158|, s49
	s_nop 1
	v_cndmask_b32_e64 v158, v158, v160, s[0:1]
	v_cndmask_b32_e32 v160, 0, v233, vcc
	v_sub_f32_e32 v158, v158, v160
	v_sub_f32_e32 v158, v159, v158
	v_mul_f32_e32 v238, 0x3d800000, v158
	v_fmac_f32_e32 v141, 0x3d800000, v158
	s_waitcnt lgkmcnt(0)
	v_mul_f32_e32 v158, v5, v241
	v_fmac_f32_e32 v158, v4, v240
	v_fmac_f32_e32 v158, v6, v242
	v_fmac_f32_e32 v158, v7, v243
	ds_read_b128 v[240:243], v9 offset:6032
	v_add_f32_e32 v158, v157, v158
	s_waitcnt lgkmcnt(0)
	v_mul_f32_e32 v159, v154, v241
	v_fmac_f32_e32 v159, v228, v240
	v_fmac_f32_e32 v159, v155, v242
	v_fmac_f32_e32 v159, v156, v243
	ds_read_b128 v[240:243], v9 offset:6048
	v_add_f32_e32 v158, v158, v159
	s_waitcnt lgkmcnt(0)
	v_mul_f32_e32 v159, v252, v241
	v_fmac_f32_e32 v159, v146, v240
	v_fmac_f32_e32 v159, v253, v242
	v_fmac_f32_e32 v159, v227, v243
	ds_read_b128 v[240:243], v9 offset:6064
	v_add_f32_e32 v158, v158, v159
	s_waitcnt lgkmcnt(0)
	v_mul_f32_e32 v159, v147, v241
	v_fmac_f32_e32 v159, v145, v240
	v_fmac_f32_e32 v159, v230, v242
	v_fmac_f32_e32 v159, v231, v243
	v_add_f32_e32 v158, v158, v159
	v_min_f32_e32 v159, 0, v158
	v_mul_f32_e64 v158, |v158|, s18
	v_exp_f32_e32 v158, v158
	ds_read_b128 v[242:245], v9 offset:6144
	v_add_f32_e32 v158, 1.0, v158
	v_cmp_gt_f32_e32 vcc, s71, v158
	s_nop 1
	v_cndmask_b32_e64 v160, 0, 32, vcc
	v_ldexp_f32 v158, v158, v160
	v_log_f32_e32 v158, v158
	s_nop 0
	v_mul_f32_e32 v160, 0x3f317217, v158
	v_fma_f32 v160, v158, s48, -v160
	v_fmac_f32_e32 v160, 0x3377d1cf, v158
	v_fmac_f32_e32 v160, 0x3f317217, v158
	v_cmp_lt_f32_e64 s[0:1], |v158|, s49
	s_nop 1
	v_cndmask_b32_e64 v158, v158, v160, s[0:1]
	v_cndmask_b32_e32 v160, 0, v233, vcc
	v_sub_f32_e32 v158, v158, v160
	v_sub_f32_e32 v158, v159, v158
	v_mul_f32_e32 v240, 0x3d800000, v158
	v_fmac_f32_e32 v141, 0x3d800000, v158
	s_waitcnt lgkmcnt(0)
	v_mul_f32_e32 v158, v5, v243
	v_fmac_f32_e32 v158, v4, v242
	v_fmac_f32_e32 v158, v6, v244
	v_fmac_f32_e32 v158, v7, v245
	ds_read_b128 v[242:245], v9 offset:6160
	v_add_f32_e32 v158, v157, v158
	s_waitcnt lgkmcnt(0)
	v_mul_f32_e32 v159, v154, v243
	v_fmac_f32_e32 v159, v228, v242
	v_fmac_f32_e32 v159, v155, v244
	v_fmac_f32_e32 v159, v156, v245
	ds_read_b128 v[242:245], v9 offset:6176
	v_add_f32_e32 v158, v158, v159
	s_waitcnt lgkmcnt(0)
	v_mul_f32_e32 v159, v252, v243
	v_fmac_f32_e32 v159, v146, v242
	v_fmac_f32_e32 v159, v253, v244
	v_fmac_f32_e32 v159, v227, v245
	ds_read_b128 v[242:245], v9 offset:6192
	v_add_f32_e32 v158, v158, v159
	s_waitcnt lgkmcnt(0)
	v_mul_f32_e32 v159, v147, v243
	v_fmac_f32_e32 v159, v145, v242
	v_fmac_f32_e32 v159, v230, v244
	v_fmac_f32_e32 v159, v231, v245
	v_add_f32_e32 v158, v158, v159
	v_min_f32_e32 v159, 0, v158
	v_mul_f32_e64 v158, |v158|, s18
	v_exp_f32_e32 v158, v158
	ds_read_b128 v[242:245], v9 offset:6272
	v_add_f32_e32 v158, 1.0, v158
	v_cmp_gt_f32_e32 vcc, s71, v158
	s_nop 1
	v_cndmask_b32_e64 v160, 0, 32, vcc
	v_ldexp_f32 v158, v158, v160
	v_log_f32_e32 v158, v158
	s_nop 0
	v_mul_f32_e32 v160, 0x3f317217, v158
	v_fma_f32 v160, v158, s48, -v160
	v_fmac_f32_e32 v160, 0x3377d1cf, v158
	v_fmac_f32_e32 v160, 0x3f317217, v158
	v_cmp_lt_f32_e64 s[0:1], |v158|, s49
	s_nop 1
	v_cndmask_b32_e64 v158, v158, v160, s[0:1]
	v_cndmask_b32_e32 v160, 0, v233, vcc
	v_sub_f32_e32 v158, v158, v160
	v_sub_f32_e32 v158, v159, v158
	v_mul_f32_e32 v215, 0x3d800000, v158
	v_fmac_f32_e32 v141, 0x3d800000, v158
	s_waitcnt lgkmcnt(0)
	v_mul_f32_e32 v158, v5, v243
	v_fmac_f32_e32 v158, v4, v242
	v_fmac_f32_e32 v158, v6, v244
	v_fmac_f32_e32 v158, v7, v245
	ds_read_b128 v[242:245], v9 offset:6288
	v_add_f32_e32 v158, v157, v158
	s_waitcnt lgkmcnt(0)
	v_mul_f32_e32 v159, v154, v243
	v_fmac_f32_e32 v159, v228, v242
	v_fmac_f32_e32 v159, v155, v244
	v_fmac_f32_e32 v159, v156, v245
	ds_read_b128 v[242:245], v9 offset:6304
	v_add_f32_e32 v158, v158, v159
	s_waitcnt lgkmcnt(0)
	v_mul_f32_e32 v159, v252, v243
	v_fmac_f32_e32 v159, v146, v242
	v_fmac_f32_e32 v159, v253, v244
	v_fmac_f32_e32 v159, v227, v245
	ds_read_b128 v[242:245], v9 offset:6320
	v_add_f32_e32 v158, v158, v159
	s_waitcnt lgkmcnt(0)
	v_mul_f32_e32 v159, v147, v243
	v_fmac_f32_e32 v159, v145, v242
	v_fmac_f32_e32 v159, v230, v244
	v_fmac_f32_e32 v159, v231, v245
	v_add_f32_e32 v158, v158, v159
	v_min_f32_e32 v159, 0, v158
	v_mul_f32_e64 v158, |v158|, s18
	v_exp_f32_e32 v158, v158
	ds_read_b128 v[242:245], v9 offset:6400
	v_add_f32_e32 v158, 1.0, v158
	v_cmp_gt_f32_e32 vcc, s71, v158
	s_nop 1
	v_cndmask_b32_e64 v160, 0, 32, vcc
	v_ldexp_f32 v158, v158, v160
	v_log_f32_e32 v158, v158
	s_nop 0
	v_mul_f32_e32 v160, 0x3f317217, v158
	v_fma_f32 v160, v158, s48, -v160
	v_fmac_f32_e32 v160, 0x3377d1cf, v158
	v_fmac_f32_e32 v160, 0x3f317217, v158
	v_cmp_lt_f32_e64 s[0:1], |v158|, s49
	s_nop 1
	v_cndmask_b32_e64 v158, v158, v160, s[0:1]
	v_cndmask_b32_e32 v160, 0, v233, vcc
	v_sub_f32_e32 v158, v158, v160
	v_sub_f32_e32 v158, v159, v158
	v_mul_f32_e32 v237, 0x3d800000, v158
	v_fmac_f32_e32 v141, 0x3d800000, v158
	s_waitcnt lgkmcnt(0)
	v_mul_f32_e32 v158, v5, v243
	v_fmac_f32_e32 v158, v4, v242
	v_fmac_f32_e32 v158, v6, v244
	v_fmac_f32_e32 v158, v7, v245
	ds_read_b128 v[242:245], v9 offset:6416
	v_add_f32_e32 v158, v157, v158
	s_waitcnt lgkmcnt(0)
	v_mul_f32_e32 v159, v154, v243
	v_fmac_f32_e32 v159, v228, v242
	v_fmac_f32_e32 v159, v155, v244
	v_fmac_f32_e32 v159, v156, v245
	ds_read_b128 v[242:245], v9 offset:6432
	v_add_f32_e32 v158, v158, v159
	s_waitcnt lgkmcnt(0)
	v_mul_f32_e32 v159, v252, v243
	v_fmac_f32_e32 v159, v146, v242
	v_fmac_f32_e32 v159, v253, v244
	v_fmac_f32_e32 v159, v227, v245
	ds_read_b128 v[242:245], v9 offset:6448
	v_add_f32_e32 v158, v158, v159
	s_waitcnt lgkmcnt(0)
	v_mul_f32_e32 v159, v147, v243
	v_fmac_f32_e32 v159, v145, v242
	v_fmac_f32_e32 v159, v230, v244
	v_fmac_f32_e32 v159, v231, v245
	v_add_f32_e32 v158, v158, v159
	v_min_f32_e32 v159, 0, v158
	v_mul_f32_e64 v158, |v158|, s18
	v_exp_f32_e32 v158, v158
	ds_read_b128 v[244:247], v9 offset:6528
	v_add_f32_e32 v158, 1.0, v158
	v_cmp_gt_f32_e32 vcc, s71, v158
	s_nop 1
	v_cndmask_b32_e64 v160, 0, 32, vcc
	v_ldexp_f32 v158, v158, v160
	v_log_f32_e32 v158, v158
	s_nop 0
	v_mul_f32_e32 v160, 0x3f317217, v158
	v_fma_f32 v160, v158, s48, -v160
	v_fmac_f32_e32 v160, 0x3377d1cf, v158
	v_fmac_f32_e32 v160, 0x3f317217, v158
	v_cmp_lt_f32_e64 s[0:1], |v158|, s49
	s_nop 1
	v_cndmask_b32_e64 v158, v158, v160, s[0:1]
	v_cndmask_b32_e32 v160, 0, v233, vcc
	v_sub_f32_e32 v158, v158, v160
	v_sub_f32_e32 v158, v159, v158
	v_mul_f32_e32 v242, 0x3d800000, v158
	v_fmac_f32_e32 v141, 0x3d800000, v158
	s_waitcnt lgkmcnt(0)
	v_mul_f32_e32 v158, v5, v245
	v_fmac_f32_e32 v158, v4, v244
	v_fmac_f32_e32 v158, v6, v246
	v_fmac_f32_e32 v158, v7, v247
	ds_read_b128 v[244:247], v9 offset:6544
	v_add_f32_e32 v158, v157, v158
	s_waitcnt lgkmcnt(0)
	v_mul_f32_e32 v159, v154, v245
	v_fmac_f32_e32 v159, v228, v244
	v_fmac_f32_e32 v159, v155, v246
	v_fmac_f32_e32 v159, v156, v247
	ds_read_b128 v[244:247], v9 offset:6560
	v_add_f32_e32 v158, v158, v159
	s_waitcnt lgkmcnt(0)
	v_mul_f32_e32 v159, v252, v245
	v_fmac_f32_e32 v159, v146, v244
	v_fmac_f32_e32 v159, v253, v246
	v_fmac_f32_e32 v159, v227, v247
	ds_read_b128 v[244:247], v9 offset:6576
	v_add_f32_e32 v158, v158, v159
	s_waitcnt lgkmcnt(0)
	v_mul_f32_e32 v159, v147, v245
	v_fmac_f32_e32 v159, v145, v244
	v_fmac_f32_e32 v159, v230, v246
	v_fmac_f32_e32 v159, v231, v247
	v_add_f32_e32 v158, v158, v159
	v_min_f32_e32 v159, 0, v158
	v_mul_f32_e64 v158, |v158|, s18
	v_exp_f32_e32 v158, v158
	ds_read_b128 v[246:249], v9 offset:6656
	v_add_f32_e32 v158, 1.0, v158
	v_cmp_gt_f32_e32 vcc, s71, v158
	s_nop 1
	v_cndmask_b32_e64 v160, 0, 32, vcc
	v_ldexp_f32 v158, v158, v160
	v_log_f32_e32 v158, v158
	s_nop 0
	v_mul_f32_e32 v160, 0x3f317217, v158
	v_fma_f32 v160, v158, s48, -v160
	v_fmac_f32_e32 v160, 0x3377d1cf, v158
	v_fmac_f32_e32 v160, 0x3f317217, v158
	v_cmp_lt_f32_e64 s[0:1], |v158|, s49
	s_nop 1
	v_cndmask_b32_e64 v158, v158, v160, s[0:1]
	v_cndmask_b32_e32 v160, 0, v233, vcc
	v_sub_f32_e32 v158, v158, v160
	v_sub_f32_e32 v158, v159, v158
	v_mul_f32_e32 v244, 0x3d800000, v158
	v_fmac_f32_e32 v141, 0x3d800000, v158
	s_waitcnt lgkmcnt(0)
	v_mul_f32_e32 v158, v5, v247
	v_fmac_f32_e32 v158, v4, v246
	v_fmac_f32_e32 v158, v6, v248
	v_fmac_f32_e32 v158, v7, v249
	ds_read_b128 v[246:249], v9 offset:6672
	v_add_f32_e32 v158, v157, v158
	s_waitcnt lgkmcnt(0)
	v_mul_f32_e32 v159, v154, v247
	v_fmac_f32_e32 v159, v228, v246
	v_fmac_f32_e32 v159, v155, v248
	v_fmac_f32_e32 v159, v156, v249
	ds_read_b128 v[246:249], v9 offset:6688
	v_add_f32_e32 v158, v158, v159
	s_waitcnt lgkmcnt(0)
	v_mul_f32_e32 v159, v252, v247
	v_fmac_f32_e32 v159, v146, v246
	v_fmac_f32_e32 v159, v253, v248
	v_fmac_f32_e32 v159, v227, v249
	ds_read_b128 v[246:249], v9 offset:6704
	v_add_f32_e32 v158, v158, v159
	s_waitcnt lgkmcnt(0)
	v_mul_f32_e32 v159, v147, v247
	v_fmac_f32_e32 v159, v145, v246
	v_fmac_f32_e32 v159, v230, v248
	v_fmac_f32_e32 v159, v231, v249
	v_add_f32_e32 v158, v158, v159
	v_min_f32_e32 v159, 0, v158
	v_mul_f32_e64 v158, |v158|, s18
	v_exp_f32_e32 v158, v158
	ds_read_b128 v[246:249], v9 offset:6784
	v_add_f32_e32 v158, 1.0, v158
	v_cmp_gt_f32_e32 vcc, s71, v158
	s_nop 1
	v_cndmask_b32_e64 v160, 0, 32, vcc
	v_ldexp_f32 v158, v158, v160
	v_log_f32_e32 v158, v158
	s_nop 0
	v_mul_f32_e32 v160, 0x3f317217, v158
	v_fma_f32 v160, v158, s48, -v160
	v_fmac_f32_e32 v160, 0x3377d1cf, v158
	v_fmac_f32_e32 v160, 0x3f317217, v158
	v_cmp_lt_f32_e64 s[0:1], |v158|, s49
	s_nop 1
	v_cndmask_b32_e64 v158, v158, v160, s[0:1]
	v_cndmask_b32_e32 v160, 0, v233, vcc
	v_sub_f32_e32 v158, v158, v160
	v_sub_f32_e32 v158, v159, v158
	v_mul_f32_e32 v235, 0x3d800000, v158
	v_fmac_f32_e32 v141, 0x3d800000, v158
	s_waitcnt lgkmcnt(0)
	v_mul_f32_e32 v158, v5, v247
	v_fmac_f32_e32 v158, v4, v246
	v_fmac_f32_e32 v158, v6, v248
	v_fmac_f32_e32 v158, v7, v249
	ds_read_b128 v[246:249], v9 offset:6800
	v_add_f32_e32 v158, v157, v158
	s_waitcnt lgkmcnt(0)
	v_mul_f32_e32 v159, v154, v247
	v_fmac_f32_e32 v159, v228, v246
	v_fmac_f32_e32 v159, v155, v248
	v_fmac_f32_e32 v159, v156, v249
	ds_read_b128 v[246:249], v9 offset:6816
	v_add_f32_e32 v158, v158, v159
	s_waitcnt lgkmcnt(0)
	v_mul_f32_e32 v159, v252, v247
	v_fmac_f32_e32 v159, v146, v246
	v_fmac_f32_e32 v159, v253, v248
	v_fmac_f32_e32 v159, v227, v249
	ds_read_b128 v[246:249], v9 offset:6832
	v_add_f32_e32 v158, v158, v159
	s_waitcnt lgkmcnt(0)
	v_mul_f32_e32 v159, v147, v247
	v_fmac_f32_e32 v159, v145, v246
	v_fmac_f32_e32 v159, v230, v248
	v_fmac_f32_e32 v159, v231, v249
	v_add_f32_e32 v158, v158, v159
	v_min_f32_e32 v159, 0, v158
	v_mul_f32_e64 v158, |v158|, s18
	v_exp_f32_e32 v158, v158
	ds_read_b128 v[246:249], v9 offset:6912
	v_add_f32_e32 v158, 1.0, v158
	v_cmp_gt_f32_e32 vcc, s71, v158
	s_nop 1
	v_cndmask_b32_e64 v160, 0, 32, vcc
	v_ldexp_f32 v158, v158, v160
	v_log_f32_e32 v158, v158
	s_nop 0
	v_mul_f32_e32 v160, 0x3f317217, v158
	v_fma_f32 v160, v158, s48, -v160
	v_fmac_f32_e32 v160, 0x3377d1cf, v158
	v_fmac_f32_e32 v160, 0x3f317217, v158
	v_cmp_lt_f32_e64 s[0:1], |v158|, s49
	s_nop 1
	v_cndmask_b32_e64 v158, v158, v160, s[0:1]
	v_cndmask_b32_e32 v160, 0, v233, vcc
	v_sub_f32_e32 v158, v158, v160
	v_sub_f32_e32 v158, v159, v158
	v_mul_f32_e32 v241, 0x3d800000, v158
	v_fmac_f32_e32 v141, 0x3d800000, v158
	s_waitcnt lgkmcnt(0)
	v_mul_f32_e32 v158, v5, v247
	v_fmac_f32_e32 v158, v4, v246
	v_fmac_f32_e32 v158, v6, v248
	v_fmac_f32_e32 v158, v7, v249
	ds_read_b128 v[246:249], v9 offset:6928
	v_add_f32_e32 v158, v157, v158
	s_waitcnt lgkmcnt(0)
	v_mul_f32_e32 v159, v154, v247
	v_fmac_f32_e32 v159, v228, v246
	v_fmac_f32_e32 v159, v155, v248
	v_fmac_f32_e32 v159, v156, v249
	ds_read_b128 v[246:249], v9 offset:6944
	v_add_f32_e32 v158, v158, v159
	s_waitcnt lgkmcnt(0)
	v_mul_f32_e32 v159, v252, v247
	v_fmac_f32_e32 v159, v146, v246
	v_fmac_f32_e32 v159, v253, v248
	v_fmac_f32_e32 v159, v227, v249
	ds_read_b128 v[246:249], v9 offset:6960
	v_add_f32_e32 v158, v158, v159
	s_waitcnt lgkmcnt(0)
	v_mul_f32_e32 v159, v147, v247
	v_fmac_f32_e32 v159, v145, v246
	v_fmac_f32_e32 v159, v230, v248
	v_fmac_f32_e32 v159, v231, v249
	v_add_f32_e32 v158, v158, v159
	v_min_f32_e32 v159, 0, v158
	v_mul_f32_e64 v158, |v158|, s18
	v_exp_f32_e32 v158, v158
	ds_read_b128 v[248:251], v9 offset:7040
	v_add_f32_e32 v158, 1.0, v158
	v_cmp_gt_f32_e32 vcc, s71, v158
	s_nop 1
	v_cndmask_b32_e64 v160, 0, 32, vcc
	v_ldexp_f32 v158, v158, v160
	v_log_f32_e32 v158, v158
	s_nop 0
	v_mul_f32_e32 v160, 0x3f317217, v158
	v_fma_f32 v160, v158, s48, -v160
	v_fmac_f32_e32 v160, 0x3377d1cf, v158
	v_fmac_f32_e32 v160, 0x3f317217, v158
	v_cmp_lt_f32_e64 s[0:1], |v158|, s49
	s_nop 1
	v_cndmask_b32_e64 v158, v158, v160, s[0:1]
	v_cndmask_b32_e32 v160, 0, v233, vcc
	v_sub_f32_e32 v158, v158, v160
	v_sub_f32_e32 v158, v159, v158
	v_mul_f32_e32 v246, 0x3d800000, v158
	v_fmac_f32_e32 v141, 0x3d800000, v158
	s_waitcnt lgkmcnt(0)
	v_mul_f32_e32 v158, v5, v249
	v_fmac_f32_e32 v158, v4, v248
	v_fmac_f32_e32 v158, v6, v250
	v_fmac_f32_e32 v158, v7, v251
	ds_read_b128 v[248:251], v9 offset:7056
	v_add_f32_e32 v158, v157, v158
	s_waitcnt lgkmcnt(0)
	v_mul_f32_e32 v159, v154, v249
	v_fmac_f32_e32 v159, v228, v248
	v_fmac_f32_e32 v159, v155, v250
	v_fmac_f32_e32 v159, v156, v251
	ds_read_b128 v[248:251], v9 offset:7072
	v_add_f32_e32 v158, v158, v159
	s_waitcnt lgkmcnt(0)
	v_mul_f32_e32 v159, v252, v249
	v_fmac_f32_e32 v159, v146, v248
	v_fmac_f32_e32 v159, v253, v250
	v_fmac_f32_e32 v159, v227, v251
	ds_read_b128 v[248:251], v9 offset:7088
	v_add_f32_e32 v158, v158, v159
	s_waitcnt lgkmcnt(0)
	v_mul_f32_e32 v159, v147, v249
	v_fmac_f32_e32 v159, v145, v248
	v_fmac_f32_e32 v159, v230, v250
	v_fmac_f32_e32 v159, v231, v251
	v_add_f32_e32 v158, v158, v159
	v_min_f32_e32 v159, 0, v158
	v_mul_f32_e64 v158, |v158|, s18
	v_exp_f32_e32 v158, v158
	ds_read_b128 v[248:251], v9 offset:7168
	v_add_f32_e32 v158, 1.0, v158
	v_cmp_gt_f32_e32 vcc, s71, v158
	s_nop 1
	v_cndmask_b32_e64 v160, 0, 32, vcc
	v_ldexp_f32 v158, v158, v160
	v_log_f32_e32 v158, v158
	s_nop 0
	v_mul_f32_e32 v160, 0x3f317217, v158
	v_fma_f32 v160, v158, s48, -v160
	v_fmac_f32_e32 v160, 0x3377d1cf, v158
	v_fmac_f32_e32 v160, 0x3f317217, v158
	v_cmp_lt_f32_e64 s[0:1], |v158|, s49
	s_nop 1
	v_cndmask_b32_e64 v158, v158, v160, s[0:1]
	v_cndmask_b32_e32 v160, 0, v233, vcc
	v_sub_f32_e32 v158, v158, v160
	v_sub_f32_e32 v158, v159, v158
	v_mul_f32_e32 v247, 0x3d800000, v158
	v_fmac_f32_e32 v141, 0x3d800000, v158
	s_waitcnt lgkmcnt(0)
	v_mul_f32_e32 v158, v5, v249
	v_fmac_f32_e32 v158, v4, v248
	v_fmac_f32_e32 v158, v6, v250
	v_fmac_f32_e32 v158, v7, v251
	ds_read_b128 v[248:251], v9 offset:7184
	v_add_f32_e32 v158, v157, v158
	s_waitcnt lgkmcnt(0)
	v_mul_f32_e32 v159, v154, v249
	v_fmac_f32_e32 v159, v228, v248
	v_fmac_f32_e32 v159, v155, v250
	v_fmac_f32_e32 v159, v156, v251
	ds_read_b128 v[248:251], v9 offset:7200
	v_add_f32_e32 v158, v158, v159
	s_waitcnt lgkmcnt(0)
	v_mul_f32_e32 v159, v252, v249
	v_fmac_f32_e32 v159, v146, v248
	v_fmac_f32_e32 v159, v253, v250
	v_fmac_f32_e32 v159, v227, v251
	ds_read_b128 v[248:251], v9 offset:7216
	v_add_f32_e32 v158, v158, v159
	s_waitcnt lgkmcnt(0)
	v_mul_f32_e32 v159, v147, v249
	v_fmac_f32_e32 v159, v145, v248
	v_fmac_f32_e32 v159, v230, v250
	v_fmac_f32_e32 v159, v231, v251
	v_add_f32_e32 v158, v158, v159
	v_min_f32_e32 v159, 0, v158
	v_mul_f32_e64 v158, |v158|, s18
	v_exp_f32_e32 v158, v158
	ds_read_b128 v[248:251], v9 offset:7296
	v_add_f32_e32 v158, 1.0, v158
	v_cmp_gt_f32_e32 vcc, s71, v158
	s_nop 1
	v_cndmask_b32_e64 v160, 0, 32, vcc
	v_ldexp_f32 v158, v158, v160
	v_log_f32_e32 v158, v158
	s_nop 0
	v_mul_f32_e32 v160, 0x3f317217, v158
	v_fma_f32 v160, v158, s48, -v160
	v_fmac_f32_e32 v160, 0x3377d1cf, v158
	v_fmac_f32_e32 v160, 0x3f317217, v158
	v_cmp_lt_f32_e64 s[0:1], |v158|, s49
	s_nop 1
	v_cndmask_b32_e64 v158, v158, v160, s[0:1]
	v_cndmask_b32_e32 v160, 0, v233, vcc
	v_sub_f32_e32 v158, v158, v160
	v_sub_f32_e32 v158, v159, v158
	v_mul_f32_e32 v239, 0x3d800000, v158
	v_fmac_f32_e32 v141, 0x3d800000, v158
	s_waitcnt lgkmcnt(0)
	v_mul_f32_e32 v158, v5, v249
	v_fmac_f32_e32 v158, v4, v248
	v_fmac_f32_e32 v158, v6, v250
	v_fmac_f32_e32 v158, v7, v251
	ds_read_b128 v[248:251], v9 offset:7312
	v_add_f32_e32 v158, v157, v158
	s_waitcnt lgkmcnt(0)
	v_mul_f32_e32 v159, v154, v249
	v_fmac_f32_e32 v159, v228, v248
	v_fmac_f32_e32 v159, v155, v250
	v_fmac_f32_e32 v159, v156, v251
	ds_read_b128 v[248:251], v9 offset:7328
	v_add_f32_e32 v158, v158, v159
	s_waitcnt lgkmcnt(0)
	v_mul_f32_e32 v159, v252, v249
	v_fmac_f32_e32 v159, v146, v248
	v_fmac_f32_e32 v159, v253, v250
	v_fmac_f32_e32 v159, v227, v251
	ds_read_b128 v[248:251], v9 offset:7344
	v_add_f32_e32 v158, v158, v159
	s_waitcnt lgkmcnt(0)
	v_mul_f32_e32 v159, v147, v249
	v_fmac_f32_e32 v159, v145, v248
	v_fmac_f32_e32 v159, v230, v250
	v_fmac_f32_e32 v159, v231, v251
	v_add_f32_e32 v158, v158, v159
	v_min_f32_e32 v159, 0, v158
	v_mul_f32_e64 v158, |v158|, s18
	v_exp_f32_e32 v158, v158
	ds_read_b128 v[248:251], v9 offset:7424
	v_add_f32_e32 v158, 1.0, v158
	v_cmp_gt_f32_e32 vcc, s71, v158
	s_nop 1
	v_cndmask_b32_e64 v160, 0, 32, vcc
	v_ldexp_f32 v158, v158, v160
	v_log_f32_e32 v158, v158
	s_nop 0
	v_mul_f32_e32 v160, 0x3f317217, v158
	v_fma_f32 v160, v158, s48, -v160
	v_fmac_f32_e32 v160, 0x3377d1cf, v158
	v_fmac_f32_e32 v160, 0x3f317217, v158
	v_cmp_lt_f32_e64 s[0:1], |v158|, s49
	s_nop 1
	v_cndmask_b32_e64 v158, v158, v160, s[0:1]
	v_cndmask_b32_e32 v160, 0, v233, vcc
	v_sub_f32_e32 v158, v158, v160
	v_sub_f32_e32 v158, v159, v158
	v_mul_f32_e32 v245, 0x3d800000, v158
	v_fmac_f32_e32 v141, 0x3d800000, v158
	s_waitcnt lgkmcnt(0)
	v_mul_f32_e32 v158, v5, v249
	v_fmac_f32_e32 v158, v4, v248
	v_fmac_f32_e32 v158, v6, v250
	v_fmac_f32_e32 v158, v7, v251
	ds_read_b128 v[248:251], v9 offset:7440
	v_add_f32_e32 v158, v157, v158
	s_waitcnt lgkmcnt(0)
	v_mul_f32_e32 v159, v154, v249
	v_fmac_f32_e32 v159, v228, v248
	v_fmac_f32_e32 v159, v155, v250
	v_fmac_f32_e32 v159, v156, v251
	ds_read_b128 v[248:251], v9 offset:7456
	v_add_f32_e32 v158, v158, v159
	s_waitcnt lgkmcnt(0)
	v_mul_f32_e32 v159, v252, v249
	v_fmac_f32_e32 v159, v146, v248
	v_fmac_f32_e32 v159, v253, v250
	v_fmac_f32_e32 v159, v227, v251
	ds_read_b128 v[248:251], v9 offset:7472
	v_add_f32_e32 v158, v158, v159
	s_waitcnt lgkmcnt(0)
	v_mul_f32_e32 v159, v147, v249
	v_fmac_f32_e32 v159, v145, v248
	v_fmac_f32_e32 v159, v230, v250
	v_fmac_f32_e32 v159, v231, v251
	v_add_f32_e32 v158, v158, v159
	v_min_f32_e32 v159, 0, v158
	v_mul_f32_e64 v158, |v158|, s18
	v_exp_f32_e32 v158, v158
	s_nop 0
	v_add_f32_e32 v158, 1.0, v158
	v_cmp_gt_f32_e32 vcc, s71, v158
	s_nop 1
	v_cndmask_b32_e64 v160, 0, 32, vcc
	v_ldexp_f32 v158, v158, v160
	v_log_f32_e32 v158, v158
	s_nop 0
	v_mul_f32_e32 v160, 0x3f317217, v158
	v_fma_f32 v160, v158, s48, -v160
	v_fmac_f32_e32 v160, 0x3377d1cf, v158
	v_fmac_f32_e32 v160, 0x3f317217, v158
	v_cmp_lt_f32_e64 s[0:1], |v158|, s49
	s_nop 1
	v_cndmask_b32_e64 v158, v158, v160, s[0:1]
	v_cndmask_b32_e32 v160, 0, v233, vcc
	v_sub_f32_e32 v158, v158, v160
	v_sub_f32_e32 v158, v159, v158
	v_mul_f32_e32 v249, 0x3d800000, v158
	v_fmac_f32_e32 v141, 0x3d800000, v158
	ds_read_b128 v[158:161], v9 offset:7552
	s_waitcnt lgkmcnt(0)
	v_mul_f32_e32 v159, v5, v159
	v_fmac_f32_e32 v159, v4, v158
	v_fmac_f32_e32 v159, v6, v160
	v_fmac_f32_e32 v159, v7, v161
	v_add_f32_e32 v243, v157, v159
	ds_read_b128 v[158:161], v9 offset:7568
	s_waitcnt lgkmcnt(0)
	v_mul_f32_e32 v159, v154, v159
	v_fmac_f32_e32 v159, v228, v158
	v_fmac_f32_e32 v159, v155, v160
	v_fmac_f32_e32 v159, v156, v161
	v_add_f32_e32 v243, v243, v159
	ds_read_b128 v[158:161], v9 offset:7584
	s_waitcnt lgkmcnt(0)
	v_mul_f32_e32 v159, v252, v159
	v_fmac_f32_e32 v159, v146, v158
	v_fmac_f32_e32 v159, v253, v160
	v_fmac_f32_e32 v159, v227, v161
	v_add_f32_e32 v243, v243, v159
	ds_read_b128 v[158:161], v9 offset:7600
	s_waitcnt lgkmcnt(0)
	v_mul_f32_e32 v159, v147, v159
	v_fmac_f32_e32 v159, v145, v158
	v_fmac_f32_e32 v159, v230, v160
	v_fmac_f32_e32 v159, v231, v161
	v_add_f32_e32 v158, v243, v159
	v_min_f32_e32 v159, 0, v158
	v_mul_f32_e64 v158, |v158|, s18
	v_exp_f32_e32 v158, v158
	s_nop 0
	v_add_f32_e32 v158, 1.0, v158
	v_cmp_gt_f32_e32 vcc, s71, v158
	s_nop 1
	v_cndmask_b32_e64 v160, 0, 32, vcc
	v_ldexp_f32 v158, v158, v160
	v_log_f32_e32 v158, v158
	s_nop 0
	v_mul_f32_e32 v160, 0x3f317217, v158
	v_fma_f32 v160, v158, s48, -v160
	v_fmac_f32_e32 v160, 0x3377d1cf, v158
	v_fmac_f32_e32 v160, 0x3f317217, v158
	v_cmp_lt_f32_e64 s[0:1], |v158|, s49
	s_nop 1
	v_cndmask_b32_e64 v158, v158, v160, s[0:1]
	v_cndmask_b32_e32 v160, 0, v233, vcc
	v_sub_f32_e32 v158, v158, v160
	v_sub_f32_e32 v158, v159, v158
	v_mul_f32_e32 v250, 0x3d800000, v158
	v_fmac_f32_e32 v141, 0x3d800000, v158
	ds_read_b128 v[158:161], v9 offset:7680
	s_waitcnt lgkmcnt(0)
	v_mul_f32_e32 v159, v5, v159
	v_fmac_f32_e32 v159, v4, v158
	v_fmac_f32_e32 v159, v6, v160
	v_fmac_f32_e32 v159, v7, v161
	v_add_f32_e32 v243, v157, v159
	ds_read_b128 v[158:161], v9 offset:7696
	s_waitcnt lgkmcnt(0)
	v_mul_f32_e32 v159, v154, v159
	v_fmac_f32_e32 v159, v228, v158
	v_fmac_f32_e32 v159, v155, v160
	v_fmac_f32_e32 v159, v156, v161
	v_add_f32_e32 v243, v243, v159
	ds_read_b128 v[158:161], v9 offset:7712
	s_waitcnt lgkmcnt(0)
	v_mul_f32_e32 v159, v252, v159
	v_fmac_f32_e32 v159, v146, v158
	v_fmac_f32_e32 v159, v253, v160
	v_fmac_f32_e32 v159, v227, v161
	v_add_f32_e32 v243, v243, v159
	ds_read_b128 v[158:161], v9 offset:7728
	s_waitcnt lgkmcnt(0)
	v_mul_f32_e32 v159, v147, v159
	v_fmac_f32_e32 v159, v145, v158
	v_fmac_f32_e32 v159, v230, v160
	v_fmac_f32_e32 v159, v231, v161
	v_add_f32_e32 v158, v243, v159
	v_min_f32_e32 v159, 0, v158
	v_mul_f32_e64 v158, |v158|, s18
	v_exp_f32_e32 v158, v158
	s_nop 0
	v_add_f32_e32 v158, 1.0, v158
	v_cmp_gt_f32_e32 vcc, s71, v158
	s_nop 1
	v_cndmask_b32_e64 v160, 0, 32, vcc
	v_ldexp_f32 v158, v158, v160
	v_log_f32_e32 v158, v158
	s_nop 0
	v_mul_f32_e32 v160, 0x3f317217, v158
	v_fma_f32 v160, v158, s48, -v160
	v_fmac_f32_e32 v160, 0x3377d1cf, v158
	v_fmac_f32_e32 v160, 0x3f317217, v158
	v_cmp_lt_f32_e64 s[0:1], |v158|, s49
	s_nop 1
	v_cndmask_b32_e64 v158, v158, v160, s[0:1]
	v_cndmask_b32_e32 v160, 0, v233, vcc
	v_sub_f32_e32 v158, v158, v160
	v_sub_f32_e32 v158, v159, v158
	v_mul_f32_e32 v243, 0x3d800000, v158
	v_fmac_f32_e32 v141, 0x3d800000, v158
	ds_read_b128 v[158:161], v9 offset:7808
	s_waitcnt lgkmcnt(0)
	v_mul_f32_e32 v159, v5, v159
	v_fmac_f32_e32 v159, v4, v158
	v_fmac_f32_e32 v159, v6, v160
	v_fmac_f32_e32 v159, v7, v161
	v_add_f32_e32 v248, v157, v159
	ds_read_b128 v[158:161], v9 offset:7824
	s_waitcnt lgkmcnt(0)
	v_mul_f32_e32 v159, v154, v159
	v_fmac_f32_e32 v159, v228, v158
	v_fmac_f32_e32 v159, v155, v160
	v_fmac_f32_e32 v159, v156, v161
	v_add_f32_e32 v248, v248, v159
	ds_read_b128 v[158:161], v9 offset:7840
	s_waitcnt lgkmcnt(0)
	v_mul_f32_e32 v159, v252, v159
	v_fmac_f32_e32 v159, v146, v158
	v_fmac_f32_e32 v159, v253, v160
	v_fmac_f32_e32 v159, v227, v161
	v_add_f32_e32 v248, v248, v159
	ds_read_b128 v[158:161], v9 offset:7856
	s_waitcnt lgkmcnt(0)
	v_mul_f32_e32 v159, v147, v159
	v_fmac_f32_e32 v159, v145, v158
	v_fmac_f32_e32 v159, v230, v160
	v_fmac_f32_e32 v159, v231, v161
	v_add_f32_e32 v158, v248, v159
	v_min_f32_e32 v159, 0, v158
	v_mul_f32_e64 v158, |v158|, s18
	v_exp_f32_e32 v158, v158
	s_nop 0
	v_add_f32_e32 v158, 1.0, v158
	v_cmp_gt_f32_e32 vcc, s71, v158
	s_nop 1
	v_cndmask_b32_e64 v160, 0, 32, vcc
	v_ldexp_f32 v158, v158, v160
	v_log_f32_e32 v158, v158
	s_nop 0
	v_mul_f32_e32 v160, 0x3f317217, v158
	v_fma_f32 v160, v158, s48, -v160
	v_fmac_f32_e32 v160, 0x3377d1cf, v158
	v_fmac_f32_e32 v160, 0x3f317217, v158
	v_cmp_lt_f32_e64 s[0:1], |v158|, s49
	s_nop 1
	v_cndmask_b32_e64 v158, v158, v160, s[0:1]
	v_cndmask_b32_e32 v160, 0, v233, vcc
	v_sub_f32_e32 v158, v158, v160
	v_sub_f32_e32 v158, v159, v158
	v_mul_f32_e32 v248, 0x3d800000, v158
	v_fmac_f32_e32 v141, 0x3d800000, v158
	ds_read_b128 v[158:161], v9 offset:7936
	s_waitcnt lgkmcnt(0)
	v_mul_f32_e32 v159, v5, v159
	v_fmac_f32_e32 v159, v4, v158
	v_fmac_f32_e32 v159, v6, v160
	v_fmac_f32_e32 v159, v7, v161
	v_add_f32_e32 v251, v157, v159
	ds_read_b128 v[158:161], v9 offset:7952
	s_waitcnt lgkmcnt(0)
	v_mul_f32_e32 v159, v154, v159
	v_fmac_f32_e32 v159, v228, v158
	v_fmac_f32_e32 v159, v155, v160
	v_fmac_f32_e32 v159, v156, v161
	v_add_f32_e32 v251, v251, v159
	ds_read_b128 v[158:161], v9 offset:7968
	s_waitcnt lgkmcnt(0)
	v_mul_f32_e32 v159, v252, v159
	v_fmac_f32_e32 v159, v146, v158
	v_fmac_f32_e32 v159, v253, v160
	v_fmac_f32_e32 v159, v227, v161
	v_add_f32_e32 v251, v251, v159
	ds_read_b128 v[158:161], v9 offset:7984
	s_waitcnt lgkmcnt(0)
	v_mul_f32_e32 v159, v147, v159
	v_fmac_f32_e32 v159, v145, v158
	v_fmac_f32_e32 v159, v230, v160
	v_fmac_f32_e32 v159, v231, v161
	v_add_f32_e32 v158, v251, v159
	v_min_f32_e32 v159, 0, v158
	v_mul_f32_e64 v158, |v158|, s18
	v_exp_f32_e32 v158, v158
	s_nop 0
	v_add_f32_e32 v158, 1.0, v158
	v_cmp_gt_f32_e32 vcc, s71, v158
	s_nop 1
	v_cndmask_b32_e64 v160, 0, 32, vcc
	v_ldexp_f32 v158, v158, v160
	v_log_f32_e32 v158, v158
	s_nop 0
	v_mul_f32_e32 v160, 0x3f317217, v158
	v_fma_f32 v160, v158, s48, -v160
	v_fmac_f32_e32 v160, 0x3377d1cf, v158
	v_fmac_f32_e32 v160, 0x3f317217, v158
	v_cmp_lt_f32_e64 s[0:1], |v158|, s49
	s_nop 1
	v_cndmask_b32_e64 v158, v158, v160, s[0:1]
	v_cndmask_b32_e32 v160, 0, v233, vcc
	v_sub_f32_e32 v158, v158, v160
	v_sub_f32_e32 v158, v159, v158
	v_mul_f32_e32 v251, 0x3d800000, v158
	v_fmac_f32_e32 v141, 0x3d800000, v158
	ds_read_b128 v[158:161], v9 offset:8064
	s_waitcnt lgkmcnt(0)
	v_mul_f32_e32 v5, v5, v159
	v_fmac_f32_e32 v5, v4, v158
	v_fmac_f32_e32 v5, v6, v160
	v_fmac_f32_e32 v5, v7, v161
	v_add_f32_e32 v157, v157, v5
	ds_read_b128 v[4:7], v9 offset:8080
	s_waitcnt lgkmcnt(0)
	v_mul_f32_e32 v5, v154, v5
	v_fmac_f32_e32 v5, v228, v4
	v_fmac_f32_e32 v5, v155, v6
	v_fmac_f32_e32 v5, v156, v7
	v_add_f32_e32 v4, v157, v5
	ds_read_b128 v[154:157], v9 offset:8096
	s_waitcnt lgkmcnt(0)
	v_mul_f32_e32 v5, v252, v155
	v_fmac_f32_e32 v5, v146, v154
	v_fmac_f32_e32 v5, v253, v156
	v_fmac_f32_e32 v5, v227, v157
	v_add_f32_e32 v146, v4, v5
	ds_read_b128 v[4:7], v9 offset:8112
	s_waitcnt lgkmcnt(0)
	v_mul_f32_e32 v5, v147, v5
	v_fmac_f32_e32 v5, v145, v4
	v_fmac_f32_e32 v5, v230, v6
	v_fmac_f32_e32 v5, v231, v7
	v_add_f32_e32 v4, v146, v5
	v_min_f32_e32 v5, 0, v4
	v_mul_f32_e64 v4, |v4|, s18
	v_exp_f32_e32 v4, v4
	v_ashrrev_i32_e32 v145, 31, v144
	v_mov_b32_e32 v147, v3
	v_add_f32_e32 v4, 1.0, v4
	v_cmp_gt_f32_e32 vcc, s71, v4
	s_nop 1
	v_cndmask_b32_e64 v6, 0, 32, vcc
	v_ldexp_f32 v4, v4, v6
	v_log_f32_e32 v4, v4
	s_nop 0
	v_mul_f32_e32 v6, 0x3f317217, v4
	v_fma_f32 v6, v4, s48, -v6
	v_fmac_f32_e32 v6, 0x3377d1cf, v4
	v_fmac_f32_e32 v6, 0x3f317217, v4
	v_cmp_lt_f32_e64 s[0:1], |v4|, s49
	s_nop 1
	v_cndmask_b32_e64 v4, v4, v6, s[0:1]
	v_cndmask_b32_e32 v6, 0, v233, vcc
	v_sub_f32_e32 v4, v4, v6
	v_sub_f32_e32 v4, v5, v4
	v_lshlrev_b64 v[6:7], 7, v[144:145]
	ds_read_u16 v145, v41 offset:24576
	v_mul_f32_e32 v252, 0x3d800000, v4
	v_cndmask_b32_e64 v144, v252, v173, s[4:5]
	v_add_f32_e32 v156, 0, v144
	ds_read_u16 v144, v41 offset:8192
	s_waitcnt lgkmcnt(1)
	v_lshlrev_b32_e32 v157, 16, v145
	v_mul_f32_e32 v145, 0x3fb8aa3b, v156
	v_exp_f32_e32 v145, v145
	v_fmac_f32_e32 v141, 0x3d800000, v4
	s_waitcnt lgkmcnt(0)
	v_lshlrev_b32_e32 v144, 16, v144
	v_or_b32_e32 v4, v143, v11
	v_mul_f32_e32 v144, 0x3db504f3, v144
	v_lshlrev_b32_e32 v146, 13, v4
	v_ashrrev_i32_e32 v143, 31, v142
	v_mul_f32_e32 v144, v144, v145
	v_lshl_add_u64 v[142:143], v[146:147], 0, v[142:143]
	v_cvt_pk_bf16_f32 v158, v144, v144
	v_or_b32_e32 v144, v142, v10
	v_mov_b32_e32 v145, v143
	v_lshlrev_b64 v[146:147], 8, v[144:145]
	v_mul_f32_e32 v145, 0xbfb8aa3b, v156
	v_exp_f32_e32 v145, v145
	v_lshlrev_b32_e32 v144, 1, v8
	v_or_b32_e32 v146, v146, v144
	v_lshl_add_u64 v[154:155], s[36:37], 0, v[146:147]
	v_mul_f32_e32 v145, v145, v157
	v_and_b32_e32 v227, 0xff, v0
	v_lshrrev_b32_e32 v228, 8, v0
	v_lshlrev_b32_e32 v227, 2, v227
	v_lshl_add_u32 v227, v228, 16, v227
	ds_write_b32 v227, v218 offset:40960
	ds_write_b32 v227, v219 offset:41984
	ds_write_b32 v227, v220 offset:43008
	ds_write_b32 v227, v221 offset:44032
	ds_write_b32 v227, v222 offset:45056
	ds_write_b32 v227, v223 offset:46080
	ds_write_b32 v227, v224 offset:47104
	ds_write_b32 v227, v225 offset:48128
	ds_write_b32 v227, v226 offset:49152
	v_cndmask_b32_e64 v224, 0, -14, s[4:5]
	v_cndmask_b32_e64 v225, 0, -1, s[4:5]
	s_mov_b32 s98, 0xffff0000
	global_store_short_d16_hi v[154:155], v158, off
	v_cvt_pk_bf16_f32 v145, v145, v145
	v_lshl_add_u64 v[146:147], s[38:39], 0, v[146:147]
	global_store_short_d16_hi v[146:147], v145, off
	v_sub_f32_e32 v145, v141, v156
	v_mul_f32_e32 v145, 0x3fb8aa3b, v145
	v_exp_f32_e32 v145, v145
	v_lshlrev_b32_e32 v4, 14, v4
	v_mov_b32_e32 v5, v3
	v_lshl_add_u64 v[4:5], v[4:5], 0, v[6:7]
	v_or_b32_e32 v4, v4, v8
	v_mul_f32_e32 v145, v145, v157
	v_lshlrev_b64 v[6:7], 7, v[4:5]
	v_lshl_add_u64 v[6:7], s[54:55], 0, v[6:7]
	v_cvt_pk_bf16_f32 v145, v145, v145
	v_lshlrev_b32_e32 v146, 1, v10
	v_mov_b32_e32 v147, v3
	v_lshl_add_u64 v[146:147], v[6:7], 0, v[146:147]
	v_lshrrev_b32_e32 v220, 16, v145
	ds_read_u16 v146, v43 offset:8192
	ds_read_u16 v147, v43 offset:24576
	v_cndmask_b32_e64 v145, v251, v174, s[4:5]
	v_add_f32_e32 v145, v145, v156
	s_movk_i32 s0, 0x1ff
	s_waitcnt lgkmcnt(1)
	v_lshlrev_b32_e32 v146, 16, v146
	s_waitcnt lgkmcnt(0)
	v_lshlrev_b32_e32 v156, 16, v147
	v_mul_f32_e32 v147, 0x3fb8aa3b, v145
	v_exp_f32_e32 v147, v147
	v_mul_f32_e32 v146, 0x3db504f3, v146
	v_cmp_lt_i32_e32 vcc, s0, v1
	v_lshl_add_u64 v[4:5], v[4:5], 2, s[50:51]
	v_mul_f32_e32 v146, v146, v147
	v_cvt_pk_bf16_f32 v157, v146, v146
	v_or_b32_e32 v146, v142, v12
	v_mov_b32_e32 v147, v143
	v_lshlrev_b64 v[146:147], 8, v[146:147]
	v_or_b32_e32 v146, v146, v144
	v_lshl_add_u64 v[154:155], s[36:37], 0, v[146:147]
	global_store_short_d16_hi v[154:155], v157, off
	v_mul_f32_e32 v154, 0xbfb8aa3b, v145
	v_exp_f32_e32 v154, v154
	v_lshl_add_u64 v[146:147], s[38:39], 0, v[146:147]
	s_or_b64 s[12:13], vcc, s[12:13]
	v_mul_f32_e32 v154, v154, v156
	v_cvt_pk_bf16_f32 v154, v154, v154
	global_store_short_d16_hi v[146:147], v154, off
	v_sub_f32_e32 v146, v141, v145
	v_mul_f32_e32 v146, 0x3fb8aa3b, v146
	v_exp_f32_e32 v146, v146
	s_nop 0
	v_mul_f32_e32 v146, v146, v156
	v_cvt_pk_bf16_f32 v154, v146, v146
	v_lshlrev_b32_e32 v146, 1, v12
	v_mov_b32_e32 v147, v3
	v_lshl_add_u64 v[146:147], v[6:7], 0, v[146:147]
	v_and_or_b32 v220, v154, s98, v220
	ds_read_u16 v147, v45 offset:24576
	v_cndmask_b32_e64 v146, v248, v175, s[4:5]
	v_add_f32_e32 v145, v146, v145
	ds_read_u16 v146, v45 offset:8192
	s_waitcnt lgkmcnt(1)
	v_lshlrev_b32_e32 v156, 16, v147
	v_mul_f32_e32 v147, 0x3fb8aa3b, v145
	v_exp_f32_e32 v147, v147
	s_waitcnt lgkmcnt(0)
	v_lshlrev_b32_e32 v146, 16, v146
	v_mul_f32_e32 v146, 0x3db504f3, v146
	v_mul_f32_e32 v146, v146, v147
	v_cvt_pk_bf16_f32 v157, v146, v146
	v_or_b32_e32 v146, v142, v14
	v_mov_b32_e32 v147, v143
	v_lshlrev_b64 v[146:147], 8, v[146:147]
	v_or_b32_e32 v146, v146, v144
	v_lshl_add_u64 v[154:155], s[36:37], 0, v[146:147]
	global_store_short_d16_hi v[154:155], v157, off
	v_mul_f32_e32 v154, 0xbfb8aa3b, v145
	v_exp_f32_e32 v154, v154
	v_lshl_add_u64 v[146:147], s[38:39], 0, v[146:147]
	v_mul_f32_e32 v154, v154, v156
	v_cvt_pk_bf16_f32 v154, v154, v154
	global_store_short_d16_hi v[146:147], v154, off
	v_sub_f32_e32 v146, v141, v145
	v_mul_f32_e32 v146, 0x3fb8aa3b, v146
	v_exp_f32_e32 v146, v146
	v_mov_b32_e32 v155, v143
	v_mul_f32_e32 v146, v146, v156
	v_cvt_pk_bf16_f32 v154, v146, v146
	v_lshlrev_b32_e32 v146, 1, v14
	v_mov_b32_e32 v147, v3
	v_lshl_add_u64 v[146:147], v[6:7], 0, v[146:147]
	v_lshrrev_b32_e32 v221, 16, v154
	v_cndmask_b32_e64 v146, v243, v176, s[4:5]
	v_add_f32_e32 v145, v146, v145
	ds_read_u16 v146, v47 offset:8192
	v_mul_f32_e32 v154, 0x3fb8aa3b, v145
	v_exp_f32_e32 v154, v154
	s_waitcnt lgkmcnt(0)
	v_lshlrev_b32_e32 v147, 16, v146
	v_mul_f32_e32 v147, 0x3db504f3, v147
	v_mul_f32_e32 v147, v154, v147
	v_cvt_pk_bf16_f32 v147, v147, v147
	v_or_b32_e32 v154, v142, v16
	v_lshlrev_b64 v[154:155], 8, v[154:155]
	v_or_b32_e32 v154, v154, v144
	ds_read_u16 v146, v47 offset:24576
	v_lshl_add_u64 v[156:157], s[36:37], 0, v[154:155]
	global_store_short_d16_hi v[156:157], v147, off
	v_mul_f32_e32 v147, 0xbfb8aa3b, v145
	v_exp_f32_e32 v147, v147
	s_waitcnt lgkmcnt(0)
	v_lshlrev_b32_e32 v146, 16, v146
	v_lshl_add_u64 v[154:155], s[38:39], 0, v[154:155]
	v_mul_f32_e32 v147, v147, v146
	v_cvt_pk_bf16_f32 v147, v147, v147
	global_store_short_d16_hi v[154:155], v147, off
	v_sub_f32_e32 v147, v141, v145
	v_mul_f32_e32 v147, 0x3fb8aa3b, v147
	v_exp_f32_e32 v147, v147
	s_nop 0
	v_mul_f32_e32 v146, v147, v146
	v_cvt_pk_bf16_f32 v154, v146, v146
	v_lshlrev_b32_e32 v146, 1, v16
	v_mov_b32_e32 v147, v3
	v_lshl_add_u64 v[146:147], v[6:7], 0, v[146:147]
	v_and_or_b32 v221, v154, s98, v221
	ds_read_u16 v147, v49 offset:24576
	v_cndmask_b32_e64 v146, v250, v177, s[4:5]
	v_add_f32_e32 v145, v146, v145
	ds_read_u16 v146, v49 offset:8192
	s_waitcnt lgkmcnt(1)
	v_lshlrev_b32_e32 v156, 16, v147
	v_mul_f32_e32 v147, 0x3fb8aa3b, v145
	v_exp_f32_e32 v147, v147
	s_waitcnt lgkmcnt(0)
	v_lshlrev_b32_e32 v146, 16, v146
	v_mul_f32_e32 v146, 0x3db504f3, v146
	v_mul_f32_e32 v146, v147, v146
	v_cvt_pk_bf16_f32 v157, v146, v146
	v_or_b32_e32 v146, v142, v18
	v_mov_b32_e32 v147, v143
	v_lshlrev_b64 v[146:147], 8, v[146:147]
	v_or_b32_e32 v146, v146, v144
	v_lshl_add_u64 v[154:155], s[36:37], 0, v[146:147]
	global_store_short_d16_hi v[154:155], v157, off
	v_mul_f32_e32 v154, 0xbfb8aa3b, v145
	v_exp_f32_e32 v154, v154
	v_lshl_add_u64 v[146:147], s[38:39], 0, v[146:147]
	v_mul_f32_e32 v154, v154, v156
	v_cvt_pk_bf16_f32 v154, v154, v154
	global_store_short_d16_hi v[146:147], v154, off
	v_sub_f32_e32 v146, v141, v145
	v_mul_f32_e32 v146, 0x3fb8aa3b, v146
	v_exp_f32_e32 v146, v146
	s_nop 0
	v_mul_f32_e32 v146, v146, v156
	v_cvt_pk_bf16_f32 v154, v146, v146
	v_lshlrev_b32_e32 v146, 1, v18
	v_mov_b32_e32 v147, v3
	v_lshl_add_u64 v[146:147], v[6:7], 0, v[146:147]
	v_lshrrev_b32_e32 v222, 16, v154
	ds_read_u16 v147, v51 offset:24576
	v_cndmask_b32_e64 v146, v249, v178, s[4:5]
	v_add_f32_e32 v145, v146, v145
	ds_read_u16 v146, v51 offset:8192
	s_waitcnt lgkmcnt(1)
	v_lshlrev_b32_e32 v156, 16, v147
	v_mul_f32_e32 v147, 0x3fb8aa3b, v145
	v_exp_f32_e32 v147, v147
	s_waitcnt lgkmcnt(0)
	v_lshlrev_b32_e32 v146, 16, v146
	v_mul_f32_e32 v146, 0x3db504f3, v146
	v_mul_f32_e32 v146, v147, v146
	v_cvt_pk_bf16_f32 v157, v146, v146
	v_or_b32_e32 v146, v142, v20
	v_mov_b32_e32 v147, v143
	v_lshlrev_b64 v[146:147], 8, v[146:147]
	v_or_b32_e32 v146, v146, v144
	v_lshl_add_u64 v[154:155], s[36:37], 0, v[146:147]
	global_store_short_d16_hi v[154:155], v157, off
	v_mul_f32_e32 v154, 0xbfb8aa3b, v145
	v_exp_f32_e32 v154, v154
	v_lshl_add_u64 v[146:147], s[38:39], 0, v[146:147]
	v_mul_f32_e32 v154, v154, v156
	v_cvt_pk_bf16_f32 v154, v154, v154
	global_store_short_d16_hi v[146:147], v154, off
	v_sub_f32_e32 v146, v141, v145
	v_mul_f32_e32 v146, 0x3fb8aa3b, v146
	v_exp_f32_e32 v146, v146
	s_nop 0
	v_mul_f32_e32 v146, v146, v156
	v_cvt_pk_bf16_f32 v154, v146, v146
	v_lshlrev_b32_e32 v146, 1, v20
	v_mov_b32_e32 v147, v3
	v_lshl_add_u64 v[146:147], v[6:7], 0, v[146:147]
	v_and_or_b32 v222, v154, s98, v222
	ds_read_u16 v147, v53 offset:24576
	v_cndmask_b32_e64 v146, v245, v179, s[4:5]
	v_add_f32_e32 v145, v146, v145
	ds_read_u16 v146, v53 offset:8192
	s_waitcnt lgkmcnt(1)
	v_lshlrev_b32_e32 v156, 16, v147
	v_mul_f32_e32 v147, 0x3fb8aa3b, v145
	v_exp_f32_e32 v147, v147
	s_waitcnt lgkmcnt(0)
	v_lshlrev_b32_e32 v146, 16, v146
	v_mul_f32_e32 v146, 0x3db504f3, v146
	v_mul_f32_e32 v146, v147, v146
	v_cvt_pk_bf16_f32 v157, v146, v146
	v_or_b32_e32 v146, v142, v22
	v_mov_b32_e32 v147, v143
	v_lshlrev_b64 v[146:147], 8, v[146:147]
	v_or_b32_e32 v146, v146, v144
	v_lshl_add_u64 v[154:155], s[36:37], 0, v[146:147]
	global_store_short_d16_hi v[154:155], v157, off
	v_mul_f32_e32 v154, 0xbfb8aa3b, v145
	v_exp_f32_e32 v154, v154
	v_lshl_add_u64 v[146:147], s[38:39], 0, v[146:147]
	v_mul_f32_e32 v154, v154, v156
	v_cvt_pk_bf16_f32 v154, v154, v154
	global_store_short_d16_hi v[146:147], v154, off
	v_sub_f32_e32 v146, v141, v145
	v_mul_f32_e32 v146, 0x3fb8aa3b, v146
	v_exp_f32_e32 v146, v146
	s_nop 0
	v_mul_f32_e32 v146, v146, v156
	v_cvt_pk_bf16_f32 v154, v146, v146
	v_lshlrev_b32_e32 v146, 1, v22
	v_mov_b32_e32 v147, v3
	v_lshl_add_u64 v[146:147], v[6:7], 0, v[146:147]
	v_lshrrev_b32_e32 v223, 16, v154
	ds_read_u16 v147, v55 offset:24576
	v_cndmask_b32_e64 v146, v239, v180, s[4:5]
	v_add_f32_e32 v145, v146, v145
	ds_read_u16 v146, v55 offset:8192
	s_waitcnt lgkmcnt(1)
	v_lshlrev_b32_e32 v156, 16, v147
	v_mul_f32_e32 v147, 0x3fb8aa3b, v145
	v_exp_f32_e32 v147, v147
	s_waitcnt lgkmcnt(0)
	v_lshlrev_b32_e32 v146, 16, v146
	v_mul_f32_e32 v146, 0x3db504f3, v146
	v_mul_f32_e32 v146, v147, v146
	v_cvt_pk_bf16_f32 v157, v146, v146
	v_or_b32_e32 v146, v142, v24
	v_mov_b32_e32 v147, v143
	v_lshlrev_b64 v[146:147], 8, v[146:147]
	v_or_b32_e32 v146, v146, v144
	v_lshl_add_u64 v[154:155], s[36:37], 0, v[146:147]
	global_store_short_d16_hi v[154:155], v157, off
	v_mul_f32_e32 v154, 0xbfb8aa3b, v145
	v_exp_f32_e32 v154, v154
	v_lshl_add_u64 v[146:147], s[38:39], 0, v[146:147]
	v_mul_f32_e32 v154, v154, v156
	v_cvt_pk_bf16_f32 v154, v154, v154
	global_store_short_d16_hi v[146:147], v154, off
	v_sub_f32_e32 v146, v141, v145
	v_mul_f32_e32 v146, 0x3fb8aa3b, v146
	v_exp_f32_e32 v146, v146
	s_nop 0
	v_mul_f32_e32 v146, v146, v156
	v_cvt_pk_bf16_f32 v154, v146, v146
	v_lshlrev_b32_e32 v146, 1, v24
	v_mov_b32_e32 v147, v3
	v_lshl_add_u64 v[146:147], v[6:7], 0, v[146:147]
	v_and_or_b32 v223, v154, s98, v223
	v_alignbit_b32 v226, v223, v223, 16
	v_alignbit_b32 v218, v220, v220, 16
	v_cndmask_b32_e64 v220, v226, v220, s[4:5]
	v_cndmask_b32_e64 v223, v218, v223, s[4:5]
	v_alignbit_b32 v226, v222, v222, 16
	v_alignbit_b32 v218, v221, v221, 16
	v_cndmask_b32_e64 v221, v226, v221, s[4:5]
	v_cndmask_b32_e64 v222, v218, v222, s[4:5]
	v_lshl_add_u64 v[218:219], v[146:147], 0, v[224:225]
	global_store_dwordx4 v[218:219], v[220:223], off
	s_nop 1
	ds_read_u16 v147, v57 offset:24576
	v_cndmask_b32_e64 v146, v247, v181, s[4:5]
	v_add_f32_e32 v145, v146, v145
	ds_read_u16 v146, v57 offset:8192
	s_waitcnt lgkmcnt(1)
	v_lshlrev_b32_e32 v156, 16, v147
	v_mul_f32_e32 v147, 0x3fb8aa3b, v145
	v_exp_f32_e32 v147, v147
	s_waitcnt lgkmcnt(0)
	v_lshlrev_b32_e32 v146, 16, v146
	v_mul_f32_e32 v146, 0x3db504f3, v146
	v_mul_f32_e32 v146, v147, v146
	v_cvt_pk_bf16_f32 v157, v146, v146
	v_or_b32_e32 v146, v142, v26
	v_mov_b32_e32 v147, v143
	v_lshlrev_b64 v[146:147], 8, v[146:147]
	v_or_b32_e32 v146, v146, v144
	v_lshl_add_u64 v[154:155], s[36:37], 0, v[146:147]
	global_store_short_d16_hi v[154:155], v157, off
	v_mul_f32_e32 v154, 0xbfb8aa3b, v145
	v_exp_f32_e32 v154, v154
	v_lshl_add_u64 v[146:147], s[38:39], 0, v[146:147]
	v_mul_f32_e32 v154, v154, v156
	v_cvt_pk_bf16_f32 v154, v154, v154
	global_store_short_d16_hi v[146:147], v154, off
	v_sub_f32_e32 v146, v141, v145
	v_mul_f32_e32 v146, 0x3fb8aa3b, v146
	v_exp_f32_e32 v146, v146
	s_nop 0
	v_mul_f32_e32 v146, v146, v156
	v_cvt_pk_bf16_f32 v154, v146, v146
	v_lshlrev_b32_e32 v146, 1, v26
	v_mov_b32_e32 v147, v3
	v_lshl_add_u64 v[146:147], v[6:7], 0, v[146:147]
	v_lshrrev_b32_e32 v220, 16, v154
	ds_read_u16 v147, v59 offset:24576
	v_cndmask_b32_e64 v146, v246, v182, s[4:5]
	v_add_f32_e32 v145, v146, v145
	ds_read_u16 v146, v59 offset:8192
	s_waitcnt lgkmcnt(1)
	v_lshlrev_b32_e32 v156, 16, v147
	v_mul_f32_e32 v147, 0x3fb8aa3b, v145
	v_exp_f32_e32 v147, v147
	s_waitcnt lgkmcnt(0)
	v_lshlrev_b32_e32 v146, 16, v146
	v_mul_f32_e32 v146, 0x3db504f3, v146
	v_mul_f32_e32 v146, v147, v146
	v_cvt_pk_bf16_f32 v157, v146, v146
	v_or_b32_e32 v146, v142, v28
	v_mov_b32_e32 v147, v143
	v_lshlrev_b64 v[146:147], 8, v[146:147]
	v_or_b32_e32 v146, v146, v144
	v_lshl_add_u64 v[154:155], s[36:37], 0, v[146:147]
	global_store_short_d16_hi v[154:155], v157, off
	v_mul_f32_e32 v154, 0xbfb8aa3b, v145
	v_exp_f32_e32 v154, v154
	v_lshl_add_u64 v[146:147], s[38:39], 0, v[146:147]
	v_mul_f32_e32 v154, v154, v156
	v_cvt_pk_bf16_f32 v154, v154, v154
	global_store_short_d16_hi v[146:147], v154, off
	v_sub_f32_e32 v146, v141, v145
	v_mul_f32_e32 v146, 0x3fb8aa3b, v146
	v_exp_f32_e32 v146, v146
	s_nop 0
	v_mul_f32_e32 v146, v146, v156
	v_cvt_pk_bf16_f32 v154, v146, v146
	v_lshlrev_b32_e32 v146, 1, v28
	v_mov_b32_e32 v147, v3
	v_lshl_add_u64 v[146:147], v[6:7], 0, v[146:147]
	v_and_or_b32 v220, v154, s98, v220
	ds_read_u16 v147, v61 offset:24576
	v_cndmask_b32_e64 v146, v241, v183, s[4:5]
	v_add_f32_e32 v145, v146, v145
	ds_read_u16 v146, v61 offset:8192
	s_waitcnt lgkmcnt(1)
	v_lshlrev_b32_e32 v156, 16, v147
	v_mul_f32_e32 v147, 0x3fb8aa3b, v145
	v_exp_f32_e32 v147, v147
	s_waitcnt lgkmcnt(0)
	v_lshlrev_b32_e32 v146, 16, v146
	v_mul_f32_e32 v146, 0x3db504f3, v146
	v_mul_f32_e32 v146, v147, v146
	v_cvt_pk_bf16_f32 v157, v146, v146
	v_or_b32_e32 v146, v142, v30
	v_mov_b32_e32 v147, v143
	v_lshlrev_b64 v[146:147], 8, v[146:147]
	v_or_b32_e32 v146, v146, v144
	v_lshl_add_u64 v[154:155], s[36:37], 0, v[146:147]
	global_store_short_d16_hi v[154:155], v157, off
	v_mul_f32_e32 v154, 0xbfb8aa3b, v145
	v_exp_f32_e32 v154, v154
	v_lshl_add_u64 v[146:147], s[38:39], 0, v[146:147]
	v_mul_f32_e32 v154, v154, v156
	v_cvt_pk_bf16_f32 v154, v154, v154
	global_store_short_d16_hi v[146:147], v154, off
	v_sub_f32_e32 v146, v141, v145
	v_mul_f32_e32 v146, 0x3fb8aa3b, v146
	v_exp_f32_e32 v146, v146
	s_nop 0
	v_mul_f32_e32 v146, v146, v156
	v_cvt_pk_bf16_f32 v154, v146, v146
	v_lshlrev_b32_e32 v146, 1, v30
	v_mov_b32_e32 v147, v3
	v_lshl_add_u64 v[146:147], v[6:7], 0, v[146:147]
	v_lshrrev_b32_e32 v221, 16, v154
	ds_read_u16 v147, v63 offset:24576
	v_cndmask_b32_e64 v146, v235, v184, s[4:5]
	v_add_f32_e32 v145, v146, v145
	ds_read_u16 v146, v63 offset:8192
	s_waitcnt lgkmcnt(1)
	v_lshlrev_b32_e32 v156, 16, v147
	v_mul_f32_e32 v147, 0x3fb8aa3b, v145
	v_exp_f32_e32 v147, v147
	s_waitcnt lgkmcnt(0)
	v_lshlrev_b32_e32 v146, 16, v146
	v_mul_f32_e32 v146, 0x3db504f3, v146
	v_mul_f32_e32 v146, v147, v146
	v_cvt_pk_bf16_f32 v157, v146, v146
	v_or_b32_e32 v146, v142, v32
	v_mov_b32_e32 v147, v143
	v_lshlrev_b64 v[146:147], 8, v[146:147]
	v_or_b32_e32 v146, v146, v144
	v_lshl_add_u64 v[154:155], s[36:37], 0, v[146:147]
	global_store_short_d16_hi v[154:155], v157, off
	v_mul_f32_e32 v154, 0xbfb8aa3b, v145
	v_exp_f32_e32 v154, v154
	v_lshl_add_u64 v[146:147], s[38:39], 0, v[146:147]
	v_mul_f32_e32 v154, v154, v156
	v_cvt_pk_bf16_f32 v154, v154, v154
	global_store_short_d16_hi v[146:147], v154, off
	v_sub_f32_e32 v146, v141, v145
	v_mul_f32_e32 v146, 0x3fb8aa3b, v146
	v_exp_f32_e32 v146, v146
	s_nop 0
	v_mul_f32_e32 v146, v146, v156
	v_cvt_pk_bf16_f32 v154, v146, v146
	v_lshlrev_b32_e32 v146, 1, v32
	v_mov_b32_e32 v147, v3
	v_lshl_add_u64 v[146:147], v[6:7], 0, v[146:147]
	v_and_or_b32 v221, v154, s98, v221
	ds_read_u16 v147, v65 offset:24576
	v_cndmask_b32_e64 v146, v244, v185, s[4:5]
	v_add_f32_e32 v145, v146, v145
	ds_read_u16 v146, v65 offset:8192
	s_waitcnt lgkmcnt(1)
	v_lshlrev_b32_e32 v156, 16, v147
	v_mul_f32_e32 v147, 0x3fb8aa3b, v145
	v_exp_f32_e32 v147, v147
	s_waitcnt lgkmcnt(0)
	v_lshlrev_b32_e32 v146, 16, v146
	v_mul_f32_e32 v146, 0x3db504f3, v146
	v_mul_f32_e32 v146, v147, v146
	v_cvt_pk_bf16_f32 v157, v146, v146
	v_or_b32_e32 v146, v142, v34
	v_mov_b32_e32 v147, v143
	v_lshlrev_b64 v[146:147], 8, v[146:147]
	v_or_b32_e32 v146, v146, v144
	v_lshl_add_u64 v[154:155], s[36:37], 0, v[146:147]
	global_store_short_d16_hi v[154:155], v157, off
	v_mul_f32_e32 v154, 0xbfb8aa3b, v145
	v_exp_f32_e32 v154, v154
	v_lshl_add_u64 v[146:147], s[38:39], 0, v[146:147]
	v_mul_f32_e32 v154, v154, v156
	v_cvt_pk_bf16_f32 v154, v154, v154
	global_store_short_d16_hi v[146:147], v154, off
	v_sub_f32_e32 v146, v141, v145
	v_mul_f32_e32 v146, 0x3fb8aa3b, v146
	v_exp_f32_e32 v146, v146
	s_nop 0
	v_mul_f32_e32 v146, v146, v156
	v_cvt_pk_bf16_f32 v154, v146, v146
	v_lshlrev_b32_e32 v146, 1, v34
	v_mov_b32_e32 v147, v3
	v_lshl_add_u64 v[146:147], v[6:7], 0, v[146:147]
	v_lshrrev_b32_e32 v222, 16, v154
	ds_read_u16 v147, v67 offset:24576
	v_cndmask_b32_e64 v146, v242, v186, s[4:5]
	v_add_f32_e32 v145, v146, v145
	ds_read_u16 v146, v67 offset:8192
	s_waitcnt lgkmcnt(1)
	v_lshlrev_b32_e32 v156, 16, v147
	v_mul_f32_e32 v147, 0x3fb8aa3b, v145
	v_exp_f32_e32 v147, v147
	s_waitcnt lgkmcnt(0)
	v_lshlrev_b32_e32 v146, 16, v146
	v_mul_f32_e32 v146, 0x3db504f3, v146
	v_mul_f32_e32 v146, v147, v146
	v_cvt_pk_bf16_f32 v157, v146, v146
	v_or_b32_e32 v146, v142, v38
	v_mov_b32_e32 v147, v143
	v_lshlrev_b64 v[146:147], 8, v[146:147]
	v_or_b32_e32 v146, v146, v144
	v_lshl_add_u64 v[154:155], s[36:37], 0, v[146:147]
	global_store_short_d16_hi v[154:155], v157, off
	v_mul_f32_e32 v154, 0xbfb8aa3b, v145
	v_exp_f32_e32 v154, v154
	v_lshl_add_u64 v[146:147], s[38:39], 0, v[146:147]
	v_mul_f32_e32 v154, v154, v156
	v_cvt_pk_bf16_f32 v154, v154, v154
	global_store_short_d16_hi v[146:147], v154, off
	v_sub_f32_e32 v146, v141, v145
	v_mul_f32_e32 v146, 0x3fb8aa3b, v146
	v_exp_f32_e32 v146, v146
	s_nop 0
	v_mul_f32_e32 v146, v146, v156
	v_cvt_pk_bf16_f32 v154, v146, v146
	v_lshlrev_b32_e32 v146, 1, v38
	v_mov_b32_e32 v147, v3
	v_lshl_add_u64 v[146:147], v[6:7], 0, v[146:147]
	v_and_or_b32 v222, v154, s98, v222
	ds_read_u16 v147, v69 offset:24576
	v_cndmask_b32_e64 v146, v237, v187, s[4:5]
	v_add_f32_e32 v145, v146, v145
	ds_read_u16 v146, v69 offset:8192
	s_waitcnt lgkmcnt(1)
	v_lshlrev_b32_e32 v156, 16, v147
	v_mul_f32_e32 v147, 0x3fb8aa3b, v145
	v_exp_f32_e32 v147, v147
	s_waitcnt lgkmcnt(0)
	v_lshlrev_b32_e32 v146, 16, v146
	v_mul_f32_e32 v146, 0x3db504f3, v146
	v_mul_f32_e32 v146, v147, v146
	v_cvt_pk_bf16_f32 v157, v146, v146
	v_or_b32_e32 v146, v142, v40
	v_mov_b32_e32 v147, v143
	v_lshlrev_b64 v[146:147], 8, v[146:147]
	v_or_b32_e32 v146, v146, v144
	v_lshl_add_u64 v[154:155], s[36:37], 0, v[146:147]
	global_store_short_d16_hi v[154:155], v157, off
	v_mul_f32_e32 v154, 0xbfb8aa3b, v145
	v_exp_f32_e32 v154, v154
	v_lshl_add_u64 v[146:147], s[38:39], 0, v[146:147]
	v_mul_f32_e32 v154, v154, v156
	v_cvt_pk_bf16_f32 v154, v154, v154
	global_store_short_d16_hi v[146:147], v154, off
	v_sub_f32_e32 v146, v141, v145
	v_mul_f32_e32 v146, 0x3fb8aa3b, v146
	v_exp_f32_e32 v146, v146
	s_nop 0
	v_mul_f32_e32 v146, v146, v156
	v_cvt_pk_bf16_f32 v154, v146, v146
	v_lshlrev_b32_e32 v146, 1, v40
	v_mov_b32_e32 v147, v3
	v_lshl_add_u64 v[146:147], v[6:7], 0, v[146:147]
	v_lshrrev_b32_e32 v223, 16, v154
	ds_read_u16 v147, v71 offset:24576
	v_cndmask_b32_e64 v146, v215, v188, s[4:5]
	v_add_f32_e32 v145, v146, v145
	ds_read_u16 v146, v71 offset:8192
	s_waitcnt lgkmcnt(1)
	v_lshlrev_b32_e32 v156, 16, v147
	v_mul_f32_e32 v147, 0x3fb8aa3b, v145
	v_exp_f32_e32 v147, v147
	s_waitcnt lgkmcnt(0)
	v_lshlrev_b32_e32 v146, 16, v146
	v_mul_f32_e32 v146, 0x3db504f3, v146
	v_mul_f32_e32 v146, v147, v146
	v_cvt_pk_bf16_f32 v157, v146, v146
	v_or_b32_e32 v146, v142, v42
	v_mov_b32_e32 v147, v143
	v_lshlrev_b64 v[146:147], 8, v[146:147]
	v_or_b32_e32 v146, v146, v144
	v_lshl_add_u64 v[154:155], s[36:37], 0, v[146:147]
	global_store_short_d16_hi v[154:155], v157, off
	v_mul_f32_e32 v154, 0xbfb8aa3b, v145
	v_exp_f32_e32 v154, v154
	v_lshl_add_u64 v[146:147], s[38:39], 0, v[146:147]
	v_mul_f32_e32 v154, v154, v156
	v_cvt_pk_bf16_f32 v154, v154, v154
	global_store_short_d16_hi v[146:147], v154, off
	v_sub_f32_e32 v146, v141, v145
	v_mul_f32_e32 v146, 0x3fb8aa3b, v146
	v_exp_f32_e32 v146, v146
	s_nop 0
	v_mul_f32_e32 v146, v146, v156
	v_cvt_pk_bf16_f32 v154, v146, v146
	v_lshlrev_b32_e32 v146, 1, v42
	v_mov_b32_e32 v147, v3
	v_lshl_add_u64 v[146:147], v[6:7], 0, v[146:147]
	v_and_or_b32 v223, v154, s98, v223
	v_alignbit_b32 v226, v223, v223, 16
	v_alignbit_b32 v218, v220, v220, 16
	v_cndmask_b32_e64 v220, v226, v220, s[4:5]
	v_cndmask_b32_e64 v223, v218, v223, s[4:5]
	v_alignbit_b32 v226, v222, v222, 16
	v_alignbit_b32 v218, v221, v221, 16
	v_cndmask_b32_e64 v221, v226, v221, s[4:5]
	v_cndmask_b32_e64 v222, v218, v222, s[4:5]
	v_lshl_add_u64 v[218:219], v[146:147], 0, v[224:225]
	global_store_dwordx4 v[218:219], v[220:223], off
	s_nop 1
	ds_read_u16 v147, v73 offset:24576
	v_cndmask_b32_e64 v146, v240, v189, s[4:5]
	v_add_f32_e32 v145, v146, v145
	ds_read_u16 v146, v73 offset:8192
	s_waitcnt lgkmcnt(1)
	v_lshlrev_b32_e32 v156, 16, v147
	v_mul_f32_e32 v147, 0x3fb8aa3b, v145
	v_exp_f32_e32 v147, v147
	s_waitcnt lgkmcnt(0)
	v_lshlrev_b32_e32 v146, 16, v146
	v_mul_f32_e32 v146, 0x3db504f3, v146
	v_mul_f32_e32 v146, v147, v146
	v_cvt_pk_bf16_f32 v157, v146, v146
	v_or_b32_e32 v146, v142, v44
	v_mov_b32_e32 v147, v143
	v_lshlrev_b64 v[146:147], 8, v[146:147]
	v_or_b32_e32 v146, v146, v144
	v_lshl_add_u64 v[154:155], s[36:37], 0, v[146:147]
	global_store_short_d16_hi v[154:155], v157, off
	v_mul_f32_e32 v154, 0xbfb8aa3b, v145
	v_exp_f32_e32 v154, v154
	v_lshl_add_u64 v[146:147], s[38:39], 0, v[146:147]
	v_mul_f32_e32 v154, v154, v156
	v_cvt_pk_bf16_f32 v154, v154, v154
	global_store_short_d16_hi v[146:147], v154, off
	v_sub_f32_e32 v146, v141, v145
	v_mul_f32_e32 v146, 0x3fb8aa3b, v146
	v_exp_f32_e32 v146, v146
	s_nop 0
	v_mul_f32_e32 v146, v146, v156
	v_cvt_pk_bf16_f32 v154, v146, v146
	v_lshlrev_b32_e32 v146, 1, v44
	v_mov_b32_e32 v147, v3
	v_lshl_add_u64 v[146:147], v[6:7], 0, v[146:147]
	v_lshrrev_b32_e32 v220, 16, v154
	ds_read_u16 v147, v75 offset:24576
	v_cndmask_b32_e64 v146, v238, v190, s[4:5]
	v_add_f32_e32 v145, v146, v145
	ds_read_u16 v146, v75 offset:8192
	s_waitcnt lgkmcnt(1)
	v_lshlrev_b32_e32 v156, 16, v147
	v_mul_f32_e32 v147, 0x3fb8aa3b, v145
	v_exp_f32_e32 v147, v147
	s_waitcnt lgkmcnt(0)
	v_lshlrev_b32_e32 v146, 16, v146
	v_mul_f32_e32 v146, 0x3db504f3, v146
	v_mul_f32_e32 v146, v147, v146
	v_cvt_pk_bf16_f32 v157, v146, v146
	v_or_b32_e32 v146, v142, v46
	v_mov_b32_e32 v147, v143
	v_lshlrev_b64 v[146:147], 8, v[146:147]
	v_or_b32_e32 v146, v146, v144
	v_lshl_add_u64 v[154:155], s[36:37], 0, v[146:147]
	global_store_short_d16_hi v[154:155], v157, off
	v_mul_f32_e32 v154, 0xbfb8aa3b, v145
	v_exp_f32_e32 v154, v154
	v_lshl_add_u64 v[146:147], s[38:39], 0, v[146:147]
	v_mul_f32_e32 v154, v154, v156
	v_cvt_pk_bf16_f32 v154, v154, v154
	global_store_short_d16_hi v[146:147], v154, off
	v_sub_f32_e32 v146, v141, v145
	v_mul_f32_e32 v146, 0x3fb8aa3b, v146
	v_exp_f32_e32 v146, v146
	s_nop 0
	v_mul_f32_e32 v146, v146, v156
	v_cvt_pk_bf16_f32 v154, v146, v146
	v_lshlrev_b32_e32 v146, 1, v46
	v_mov_b32_e32 v147, v3
	v_lshl_add_u64 v[146:147], v[6:7], 0, v[146:147]
	v_and_or_b32 v220, v154, s98, v220
	ds_read_u16 v147, v77 offset:24576
	v_cndmask_b32_e64 v146, v217, v191, s[4:5]
	v_add_f32_e32 v145, v146, v145
	ds_read_u16 v146, v77 offset:8192
	s_waitcnt lgkmcnt(1)
	v_lshlrev_b32_e32 v156, 16, v147
	v_mul_f32_e32 v147, 0x3fb8aa3b, v145
	v_exp_f32_e32 v147, v147
	s_waitcnt lgkmcnt(0)
	v_lshlrev_b32_e32 v146, 16, v146
	v_mul_f32_e32 v146, 0x3db504f3, v146
	v_mul_f32_e32 v146, v147, v146
	v_cvt_pk_bf16_f32 v157, v146, v146
	v_or_b32_e32 v146, v142, v48
	v_mov_b32_e32 v147, v143
	v_lshlrev_b64 v[146:147], 8, v[146:147]
	v_or_b32_e32 v146, v146, v144
	v_lshl_add_u64 v[154:155], s[36:37], 0, v[146:147]
	global_store_short_d16_hi v[154:155], v157, off
	v_mul_f32_e32 v154, 0xbfb8aa3b, v145
	v_exp_f32_e32 v154, v154
	v_lshl_add_u64 v[146:147], s[38:39], 0, v[146:147]
	v_mul_f32_e32 v154, v154, v156
	v_cvt_pk_bf16_f32 v154, v154, v154
	global_store_short_d16_hi v[146:147], v154, off
	v_sub_f32_e32 v146, v141, v145
	v_mul_f32_e32 v146, 0x3fb8aa3b, v146
	v_exp_f32_e32 v146, v146
	s_nop 0
	v_mul_f32_e32 v146, v146, v156
	v_cvt_pk_bf16_f32 v154, v146, v146
	v_lshlrev_b32_e32 v146, 1, v48
	v_mov_b32_e32 v147, v3
	v_lshl_add_u64 v[146:147], v[6:7], 0, v[146:147]
	v_lshrrev_b32_e32 v221, 16, v154
	ds_read_u16 v147, v79 offset:24576
	v_cndmask_b32_e64 v146, v211, v192, s[4:5]
	v_add_f32_e32 v145, v146, v145
	ds_read_u16 v146, v79 offset:8192
	s_waitcnt lgkmcnt(1)
	v_lshlrev_b32_e32 v156, 16, v147
	v_mul_f32_e32 v147, 0x3fb8aa3b, v145
	v_exp_f32_e32 v147, v147
	s_waitcnt lgkmcnt(0)
	v_lshlrev_b32_e32 v146, 16, v146
	v_mul_f32_e32 v146, 0x3db504f3, v146
	v_mul_f32_e32 v146, v147, v146
	v_cvt_pk_bf16_f32 v157, v146, v146
	v_or_b32_e32 v146, v142, v50
	v_mov_b32_e32 v147, v143
	v_lshlrev_b64 v[146:147], 8, v[146:147]
	v_or_b32_e32 v146, v146, v144
	v_lshl_add_u64 v[154:155], s[36:37], 0, v[146:147]
	global_store_short_d16_hi v[154:155], v157, off
	v_mul_f32_e32 v154, 0xbfb8aa3b, v145
	v_exp_f32_e32 v154, v154
	v_lshl_add_u64 v[146:147], s[38:39], 0, v[146:147]
	v_mul_f32_e32 v154, v154, v156
	v_cvt_pk_bf16_f32 v154, v154, v154
	global_store_short_d16_hi v[146:147], v154, off
	v_sub_f32_e32 v146, v141, v145
	v_mul_f32_e32 v146, 0x3fb8aa3b, v146
	v_exp_f32_e32 v146, v146
	s_nop 0
	v_mul_f32_e32 v146, v146, v156
	v_cvt_pk_bf16_f32 v154, v146, v146
	v_lshlrev_b32_e32 v146, 1, v50
	v_mov_b32_e32 v147, v3
	v_lshl_add_u64 v[146:147], v[6:7], 0, v[146:147]
	v_and_or_b32 v221, v154, s98, v221
	ds_read_u16 v147, v81 offset:24576
	v_cndmask_b32_e64 v146, v236, v193, s[4:5]
	v_add_f32_e32 v145, v146, v145
	ds_read_u16 v146, v81 offset:8192
	s_waitcnt lgkmcnt(1)
	v_lshlrev_b32_e32 v156, 16, v147
	v_mul_f32_e32 v147, 0x3fb8aa3b, v145
	v_exp_f32_e32 v147, v147
	s_waitcnt lgkmcnt(0)
	v_lshlrev_b32_e32 v146, 16, v146
	v_mul_f32_e32 v146, 0x3db504f3, v146
	v_mul_f32_e32 v146, v147, v146
	v_cvt_pk_bf16_f32 v157, v146, v146
	v_or_b32_e32 v146, v142, v52
	v_mov_b32_e32 v147, v143
	v_lshlrev_b64 v[146:147], 8, v[146:147]
	v_or_b32_e32 v146, v146, v144
	v_lshl_add_u64 v[154:155], s[36:37], 0, v[146:147]
	global_store_short_d16_hi v[154:155], v157, off
	v_mul_f32_e32 v154, 0xbfb8aa3b, v145
	v_exp_f32_e32 v154, v154
	v_lshl_add_u64 v[146:147], s[38:39], 0, v[146:147]
	v_mul_f32_e32 v154, v154, v156
	v_cvt_pk_bf16_f32 v154, v154, v154
	global_store_short_d16_hi v[146:147], v154, off
	v_sub_f32_e32 v146, v141, v145
	v_mul_f32_e32 v146, 0x3fb8aa3b, v146
	v_exp_f32_e32 v146, v146
	s_nop 0
	v_mul_f32_e32 v146, v146, v156
	v_cvt_pk_bf16_f32 v154, v146, v146
	v_lshlrev_b32_e32 v146, 1, v52
	v_mov_b32_e32 v147, v3
	v_lshl_add_u64 v[146:147], v[6:7], 0, v[146:147]
	v_lshrrev_b32_e32 v222, 16, v154
	ds_read_u16 v147, v83 offset:24576
	v_cndmask_b32_e64 v146, v234, v194, s[4:5]
	v_add_f32_e32 v145, v146, v145
	ds_read_u16 v146, v83 offset:8192
	s_waitcnt lgkmcnt(1)
	v_lshlrev_b32_e32 v156, 16, v147
	v_mul_f32_e32 v147, 0x3fb8aa3b, v145
	v_exp_f32_e32 v147, v147
	s_waitcnt lgkmcnt(0)
	v_lshlrev_b32_e32 v146, 16, v146
	v_mul_f32_e32 v146, 0x3db504f3, v146
	v_mul_f32_e32 v146, v147, v146
	v_cvt_pk_bf16_f32 v157, v146, v146
	v_or_b32_e32 v146, v142, v54
	v_mov_b32_e32 v147, v143
	v_lshlrev_b64 v[146:147], 8, v[146:147]
	v_or_b32_e32 v146, v146, v144
	v_lshl_add_u64 v[154:155], s[36:37], 0, v[146:147]
	global_store_short_d16_hi v[154:155], v157, off
	v_mul_f32_e32 v154, 0xbfb8aa3b, v145
	v_exp_f32_e32 v154, v154
	v_lshl_add_u64 v[146:147], s[38:39], 0, v[146:147]
	v_mul_f32_e32 v154, v154, v156
	v_cvt_pk_bf16_f32 v154, v154, v154
	global_store_short_d16_hi v[146:147], v154, off
	v_sub_f32_e32 v146, v141, v145
	v_mul_f32_e32 v146, 0x3fb8aa3b, v146
	v_exp_f32_e32 v146, v146
	s_nop 0
	v_mul_f32_e32 v146, v146, v156
	v_cvt_pk_bf16_f32 v154, v146, v146
	v_lshlrev_b32_e32 v146, 1, v54
	v_mov_b32_e32 v147, v3
	v_lshl_add_u64 v[146:147], v[6:7], 0, v[146:147]
	v_and_or_b32 v222, v154, s98, v222
	ds_read_u16 v147, v85 offset:24576
	v_cndmask_b32_e64 v146, v213, v195, s[4:5]
	v_add_f32_e32 v145, v146, v145
	ds_read_u16 v146, v85 offset:8192
	s_waitcnt lgkmcnt(1)
	v_lshlrev_b32_e32 v156, 16, v147
	v_mul_f32_e32 v147, 0x3fb8aa3b, v145
	v_exp_f32_e32 v147, v147
	s_waitcnt lgkmcnt(0)
	v_lshlrev_b32_e32 v146, 16, v146
	v_mul_f32_e32 v146, 0x3db504f3, v146
	v_mul_f32_e32 v146, v147, v146
	v_cvt_pk_bf16_f32 v157, v146, v146
	v_or_b32_e32 v146, v142, v56
	v_mov_b32_e32 v147, v143
	v_lshlrev_b64 v[146:147], 8, v[146:147]
	v_or_b32_e32 v146, v146, v144
	v_lshl_add_u64 v[154:155], s[36:37], 0, v[146:147]
	global_store_short_d16_hi v[154:155], v157, off
	v_mul_f32_e32 v154, 0xbfb8aa3b, v145
	v_exp_f32_e32 v154, v154
	v_lshl_add_u64 v[146:147], s[38:39], 0, v[146:147]
	v_mul_f32_e32 v154, v154, v156
	v_cvt_pk_bf16_f32 v154, v154, v154
	global_store_short_d16_hi v[146:147], v154, off
	v_sub_f32_e32 v146, v141, v145
	v_mul_f32_e32 v146, 0x3fb8aa3b, v146
	v_exp_f32_e32 v146, v146
	s_nop 0
	v_mul_f32_e32 v146, v146, v156
	v_cvt_pk_bf16_f32 v154, v146, v146
	v_lshlrev_b32_e32 v146, 1, v56
	v_mov_b32_e32 v147, v3
	v_lshl_add_u64 v[146:147], v[6:7], 0, v[146:147]
	v_lshrrev_b32_e32 v223, 16, v154
	ds_read_u16 v147, v87 offset:24576
	v_cndmask_b32_e64 v146, v208, v196, s[4:5]
	v_add_f32_e32 v145, v146, v145
	ds_read_u16 v146, v87 offset:8192
	s_waitcnt lgkmcnt(1)
	v_lshlrev_b32_e32 v156, 16, v147
	v_mul_f32_e32 v147, 0x3fb8aa3b, v145
	v_exp_f32_e32 v147, v147
	s_waitcnt lgkmcnt(0)
	v_lshlrev_b32_e32 v146, 16, v146
	v_mul_f32_e32 v146, 0x3db504f3, v146
	v_mul_f32_e32 v146, v147, v146
	v_cvt_pk_bf16_f32 v157, v146, v146
	v_or_b32_e32 v146, v142, v58
	v_mov_b32_e32 v147, v143
	v_lshlrev_b64 v[146:147], 8, v[146:147]
	v_or_b32_e32 v146, v146, v144
	v_lshl_add_u64 v[154:155], s[36:37], 0, v[146:147]
	global_store_short_d16_hi v[154:155], v157, off
	v_mul_f32_e32 v154, 0xbfb8aa3b, v145
	v_exp_f32_e32 v154, v154
	v_lshl_add_u64 v[146:147], s[38:39], 0, v[146:147]
	v_mul_f32_e32 v154, v154, v156
	v_cvt_pk_bf16_f32 v154, v154, v154
	global_store_short_d16_hi v[146:147], v154, off
	v_sub_f32_e32 v146, v141, v145
	v_mul_f32_e32 v146, 0x3fb8aa3b, v146
	v_exp_f32_e32 v146, v146
	s_nop 0
	v_mul_f32_e32 v146, v146, v156
	v_cvt_pk_bf16_f32 v154, v146, v146
	v_lshlrev_b32_e32 v146, 1, v58
	v_mov_b32_e32 v147, v3
	v_lshl_add_u64 v[146:147], v[6:7], 0, v[146:147]
	v_and_or_b32 v223, v154, s98, v223
	v_alignbit_b32 v226, v223, v223, 16
	v_alignbit_b32 v218, v220, v220, 16
	v_cndmask_b32_e64 v220, v226, v220, s[4:5]
	v_cndmask_b32_e64 v223, v218, v223, s[4:5]
	v_alignbit_b32 v226, v222, v222, 16
	v_alignbit_b32 v218, v221, v221, 16
	v_cndmask_b32_e64 v221, v226, v221, s[4:5]
	v_cndmask_b32_e64 v222, v218, v222, s[4:5]
	v_lshl_add_u64 v[218:219], v[146:147], 0, v[224:225]
	global_store_dwordx4 v[218:219], v[220:223], off
	s_nop 1
	ds_read_u16 v147, v89 offset:24576
	v_cndmask_b32_e64 v146, v216, v197, s[4:5]
	v_add_f32_e32 v145, v146, v145
	ds_read_u16 v146, v89 offset:8192
	s_waitcnt lgkmcnt(1)
	v_lshlrev_b32_e32 v156, 16, v147
	v_mul_f32_e32 v147, 0x3fb8aa3b, v145
	v_exp_f32_e32 v147, v147
	s_waitcnt lgkmcnt(0)
	v_lshlrev_b32_e32 v146, 16, v146
	v_mul_f32_e32 v146, 0x3db504f3, v146
	v_mul_f32_e32 v146, v147, v146
	v_cvt_pk_bf16_f32 v157, v146, v146
	v_or_b32_e32 v146, v142, v60
	v_mov_b32_e32 v147, v143
	v_lshlrev_b64 v[146:147], 8, v[146:147]
	v_or_b32_e32 v146, v146, v144
	v_lshl_add_u64 v[154:155], s[36:37], 0, v[146:147]
	global_store_short_d16_hi v[154:155], v157, off
	v_mul_f32_e32 v154, 0xbfb8aa3b, v145
	v_exp_f32_e32 v154, v154
	v_lshl_add_u64 v[146:147], s[38:39], 0, v[146:147]
	v_mul_f32_e32 v154, v154, v156
	v_cvt_pk_bf16_f32 v154, v154, v154
	global_store_short_d16_hi v[146:147], v154, off
	v_sub_f32_e32 v146, v141, v145
	v_mul_f32_e32 v146, 0x3fb8aa3b, v146
	v_exp_f32_e32 v146, v146
	s_nop 0
	v_mul_f32_e32 v146, v146, v156
	v_cvt_pk_bf16_f32 v154, v146, v146
	v_lshlrev_b32_e32 v146, 1, v60
	v_mov_b32_e32 v147, v3
	v_lshl_add_u64 v[146:147], v[6:7], 0, v[146:147]
	v_lshrrev_b32_e32 v220, 16, v154
	ds_read_u16 v147, v91 offset:24576
	v_cndmask_b32_e64 v146, v214, v198, s[4:5]
	v_add_f32_e32 v145, v146, v145
	ds_read_u16 v146, v91 offset:8192
	s_waitcnt lgkmcnt(1)
	v_lshlrev_b32_e32 v156, 16, v147
	v_mul_f32_e32 v147, 0x3fb8aa3b, v145
	v_exp_f32_e32 v147, v147
	s_waitcnt lgkmcnt(0)
	v_lshlrev_b32_e32 v146, 16, v146
	v_mul_f32_e32 v146, 0x3db504f3, v146
	v_mul_f32_e32 v146, v147, v146
	v_cvt_pk_bf16_f32 v157, v146, v146
	v_or_b32_e32 v146, v142, v62
	v_mov_b32_e32 v147, v143
	v_lshlrev_b64 v[146:147], 8, v[146:147]
	v_or_b32_e32 v146, v146, v144
	v_lshl_add_u64 v[154:155], s[36:37], 0, v[146:147]
	global_store_short_d16_hi v[154:155], v157, off
	v_mul_f32_e32 v154, 0xbfb8aa3b, v145
	v_exp_f32_e32 v154, v154
	v_lshl_add_u64 v[146:147], s[38:39], 0, v[146:147]
	v_mul_f32_e32 v154, v154, v156
	v_cvt_pk_bf16_f32 v154, v154, v154
	global_store_short_d16_hi v[146:147], v154, off
	v_sub_f32_e32 v146, v141, v145
	v_mul_f32_e32 v146, 0x3fb8aa3b, v146
	v_exp_f32_e32 v146, v146
	s_nop 0
	v_mul_f32_e32 v146, v146, v156
	v_cvt_pk_bf16_f32 v154, v146, v146
	v_lshlrev_b32_e32 v146, 1, v62
	v_mov_b32_e32 v147, v3
	v_lshl_add_u64 v[146:147], v[6:7], 0, v[146:147]
	v_and_or_b32 v220, v154, s98, v220
	ds_read_u16 v147, v93 offset:24576
	v_cndmask_b32_e64 v146, v209, v199, s[4:5]
	v_add_f32_e32 v145, v146, v145
	ds_read_u16 v146, v93 offset:8192
	s_waitcnt lgkmcnt(1)
	v_lshlrev_b32_e32 v156, 16, v147
	v_mul_f32_e32 v147, 0x3fb8aa3b, v145
	v_exp_f32_e32 v147, v147
	s_waitcnt lgkmcnt(0)
	v_lshlrev_b32_e32 v146, 16, v146
	v_mul_f32_e32 v146, 0x3db504f3, v146
	v_mul_f32_e32 v146, v147, v146
	v_cvt_pk_bf16_f32 v157, v146, v146
	v_or_b32_e32 v146, v142, v64
	v_mov_b32_e32 v147, v143
	v_lshlrev_b64 v[146:147], 8, v[146:147]
	v_or_b32_e32 v146, v146, v144
	v_lshl_add_u64 v[154:155], s[36:37], 0, v[146:147]
	global_store_short_d16_hi v[154:155], v157, off
	v_mul_f32_e32 v154, 0xbfb8aa3b, v145
	v_exp_f32_e32 v154, v154
	v_lshl_add_u64 v[146:147], s[38:39], 0, v[146:147]
	v_mul_f32_e32 v154, v154, v156
	v_cvt_pk_bf16_f32 v154, v154, v154
	global_store_short_d16_hi v[146:147], v154, off
	v_sub_f32_e32 v146, v141, v145
	v_mul_f32_e32 v146, 0x3fb8aa3b, v146
	v_exp_f32_e32 v146, v146
	s_nop 0
	v_mul_f32_e32 v146, v146, v156
	v_cvt_pk_bf16_f32 v154, v146, v146
	v_lshlrev_b32_e32 v146, 1, v64
	v_mov_b32_e32 v147, v3
	v_lshl_add_u64 v[146:147], v[6:7], 0, v[146:147]
	v_lshrrev_b32_e32 v221, 16, v154
	ds_read_u16 v147, v95 offset:24576
	v_cndmask_b32_e64 v146, v206, v200, s[4:5]
	v_add_f32_e32 v145, v146, v145
	ds_read_u16 v146, v95 offset:8192
	s_waitcnt lgkmcnt(1)
	v_lshlrev_b32_e32 v156, 16, v147
	v_mul_f32_e32 v147, 0x3fb8aa3b, v145
	v_exp_f32_e32 v147, v147
	s_waitcnt lgkmcnt(0)
	v_lshlrev_b32_e32 v146, 16, v146
	v_mul_f32_e32 v146, 0x3db504f3, v146
	v_mul_f32_e32 v146, v147, v146
	v_cvt_pk_bf16_f32 v157, v146, v146
	v_or_b32_e32 v146, v142, v66
	v_mov_b32_e32 v147, v143
	v_lshlrev_b64 v[146:147], 8, v[146:147]
	v_or_b32_e32 v146, v146, v144
	v_lshl_add_u64 v[154:155], s[36:37], 0, v[146:147]
	global_store_short_d16_hi v[154:155], v157, off
	v_mul_f32_e32 v154, 0xbfb8aa3b, v145
	v_exp_f32_e32 v154, v154
	v_lshl_add_u64 v[146:147], s[38:39], 0, v[146:147]
	v_mul_f32_e32 v154, v154, v156
	v_cvt_pk_bf16_f32 v154, v154, v154
	global_store_short_d16_hi v[146:147], v154, off
	v_sub_f32_e32 v146, v141, v145
	v_mul_f32_e32 v146, 0x3fb8aa3b, v146
	v_exp_f32_e32 v146, v146
	s_nop 0
	v_mul_f32_e32 v146, v146, v156
	v_cvt_pk_bf16_f32 v154, v146, v146
	v_lshlrev_b32_e32 v146, 1, v66
	v_mov_b32_e32 v147, v3
	v_lshl_add_u64 v[146:147], v[6:7], 0, v[146:147]
	v_and_or_b32 v221, v154, s98, v221
	ds_read_u16 v147, v97 offset:24576
	v_cndmask_b32_e64 v146, v212, v201, s[4:5]
	v_add_f32_e32 v145, v146, v145
	ds_read_u16 v146, v97 offset:8192
	s_waitcnt lgkmcnt(1)
	v_lshlrev_b32_e32 v156, 16, v147
	v_mul_f32_e32 v147, 0x3fb8aa3b, v145
	v_exp_f32_e32 v147, v147
	s_waitcnt lgkmcnt(0)
	v_lshlrev_b32_e32 v146, 16, v146
	v_mul_f32_e32 v146, 0x3db504f3, v146
	v_mul_f32_e32 v146, v147, v146
	v_cvt_pk_bf16_f32 v157, v146, v146
	v_or_b32_e32 v146, v142, v68
	v_mov_b32_e32 v147, v143
	v_lshlrev_b64 v[146:147], 8, v[146:147]
	v_or_b32_e32 v146, v146, v144
	v_lshl_add_u64 v[154:155], s[36:37], 0, v[146:147]
	global_store_short_d16_hi v[154:155], v157, off
	v_mul_f32_e32 v154, 0xbfb8aa3b, v145
	v_exp_f32_e32 v154, v154
	v_lshl_add_u64 v[146:147], s[38:39], 0, v[146:147]
	v_mul_f32_e32 v154, v154, v156
	v_cvt_pk_bf16_f32 v154, v154, v154
	global_store_short_d16_hi v[146:147], v154, off
	v_sub_f32_e32 v146, v141, v145
	v_mul_f32_e32 v146, 0x3fb8aa3b, v146
	v_exp_f32_e32 v146, v146
	s_nop 0
	v_mul_f32_e32 v146, v146, v156
	v_cvt_pk_bf16_f32 v154, v146, v146
	v_lshlrev_b32_e32 v146, 1, v68
	v_mov_b32_e32 v147, v3
	v_lshl_add_u64 v[146:147], v[6:7], 0, v[146:147]
	v_lshrrev_b32_e32 v222, 16, v154
	ds_read_u16 v147, v99 offset:24576
	v_cndmask_b32_e64 v146, v210, v202, s[4:5]
	v_add_f32_e32 v145, v146, v145
	ds_read_u16 v146, v99 offset:8192
	s_waitcnt lgkmcnt(1)
	v_lshlrev_b32_e32 v156, 16, v147
	v_mul_f32_e32 v147, 0x3fb8aa3b, v145
	v_exp_f32_e32 v147, v147
	s_waitcnt lgkmcnt(0)
	v_lshlrev_b32_e32 v146, 16, v146
	v_mul_f32_e32 v146, 0x3db504f3, v146
	v_mul_f32_e32 v146, v147, v146
	v_cvt_pk_bf16_f32 v157, v146, v146
	v_or_b32_e32 v146, v142, v70
	v_mov_b32_e32 v147, v143
	v_lshlrev_b64 v[146:147], 8, v[146:147]
	v_or_b32_e32 v146, v146, v144
	v_lshl_add_u64 v[154:155], s[36:37], 0, v[146:147]
	global_store_short_d16_hi v[154:155], v157, off
	v_mul_f32_e32 v154, 0xbfb8aa3b, v145
	v_exp_f32_e32 v154, v154
	v_lshl_add_u64 v[146:147], s[38:39], 0, v[146:147]
	v_mul_f32_e32 v154, v154, v156
	v_cvt_pk_bf16_f32 v154, v154, v154
	global_store_short_d16_hi v[146:147], v154, off
	v_sub_f32_e32 v146, v141, v145
	v_mul_f32_e32 v146, 0x3fb8aa3b, v146
	v_exp_f32_e32 v146, v146
	s_nop 0
	v_mul_f32_e32 v146, v146, v156
	v_cvt_pk_bf16_f32 v154, v146, v146
	v_lshlrev_b32_e32 v146, 1, v70
	v_mov_b32_e32 v147, v3
	v_lshl_add_u64 v[146:147], v[6:7], 0, v[146:147]
	v_and_or_b32 v222, v154, s98, v222
	ds_read_u16 v147, v101 offset:24576
	v_cndmask_b32_e64 v146, v207, v203, s[4:5]
	v_add_f32_e32 v145, v146, v145
	ds_read_u16 v146, v101 offset:8192
	s_waitcnt lgkmcnt(1)
	v_lshlrev_b32_e32 v156, 16, v147
	v_mul_f32_e32 v147, 0x3fb8aa3b, v145
	v_exp_f32_e32 v147, v147
	s_waitcnt lgkmcnt(0)
	v_lshlrev_b32_e32 v146, 16, v146
	v_mul_f32_e32 v146, 0x3db504f3, v146
	v_mul_f32_e32 v146, v147, v146
	v_cvt_pk_bf16_f32 v157, v146, v146
	v_or_b32_e32 v146, v142, v72
	v_mov_b32_e32 v147, v143
	v_lshlrev_b64 v[146:147], 8, v[146:147]
	v_or_b32_e32 v146, v146, v144
	v_lshl_add_u64 v[154:155], s[36:37], 0, v[146:147]
	global_store_short_d16_hi v[154:155], v157, off
	v_mul_f32_e32 v154, 0xbfb8aa3b, v145
	v_exp_f32_e32 v154, v154
	v_lshl_add_u64 v[146:147], s[38:39], 0, v[146:147]
	v_mul_f32_e32 v154, v154, v156
	v_cvt_pk_bf16_f32 v154, v154, v154
	global_store_short_d16_hi v[146:147], v154, off
	v_sub_f32_e32 v146, v141, v145
	v_mul_f32_e32 v146, 0x3fb8aa3b, v146
	v_exp_f32_e32 v146, v146
	s_nop 0
	v_mul_f32_e32 v146, v146, v156
	v_cvt_pk_bf16_f32 v154, v146, v146
	v_lshlrev_b32_e32 v146, 1, v72
	v_mov_b32_e32 v147, v3
	v_lshl_add_u64 v[146:147], v[6:7], 0, v[146:147]
	v_lshrrev_b32_e32 v223, 16, v154
	ds_read_u16 v147, v103 offset:24576
	v_cndmask_b32_e64 v146, v205, v204, s[4:5]
	v_add_f32_e32 v145, v146, v145
	ds_read_u16 v146, v103 offset:8192
	s_waitcnt lgkmcnt(1)
	v_lshlrev_b32_e32 v156, 16, v147
	v_mul_f32_e32 v147, 0x3fb8aa3b, v145
	v_exp_f32_e32 v147, v147
	s_waitcnt lgkmcnt(0)
	v_lshlrev_b32_e32 v146, 16, v146
	v_mul_f32_e32 v146, 0x3db504f3, v146
	v_mul_f32_e32 v146, v147, v146
	v_cvt_pk_bf16_f32 v157, v146, v146
	v_or_b32_e32 v146, v142, v74
	v_mov_b32_e32 v147, v143
	v_lshlrev_b64 v[146:147], 8, v[146:147]
	v_or_b32_e32 v146, v146, v144
	v_lshl_add_u64 v[154:155], s[36:37], 0, v[146:147]
	global_store_short_d16_hi v[154:155], v157, off
	v_mul_f32_e32 v154, 0xbfb8aa3b, v145
	v_exp_f32_e32 v154, v154
	v_lshl_add_u64 v[146:147], s[38:39], 0, v[146:147]
	v_mul_f32_e32 v154, v154, v156
	v_cvt_pk_bf16_f32 v154, v154, v154
	global_store_short_d16_hi v[146:147], v154, off
	v_sub_f32_e32 v146, v141, v145
	v_mul_f32_e32 v146, 0x3fb8aa3b, v146
	v_exp_f32_e32 v146, v146
	s_nop 0
	v_mul_f32_e32 v146, v146, v156
	v_cvt_pk_bf16_f32 v154, v146, v146
	v_lshlrev_b32_e32 v146, 1, v74
	v_mov_b32_e32 v147, v3
	v_lshl_add_u64 v[146:147], v[6:7], 0, v[146:147]
	v_and_or_b32 v223, v154, s98, v223
	v_alignbit_b32 v226, v223, v223, 16
	v_alignbit_b32 v218, v220, v220, 16
	v_cndmask_b32_e64 v220, v226, v220, s[4:5]
	v_cndmask_b32_e64 v223, v218, v223, s[4:5]
	v_alignbit_b32 v226, v222, v222, 16
	v_alignbit_b32 v218, v221, v221, 16
	v_cndmask_b32_e64 v221, v226, v221, s[4:5]
	v_cndmask_b32_e64 v222, v218, v222, s[4:5]
	v_lshl_add_u64 v[218:219], v[146:147], 0, v[224:225]
	global_store_dwordx4 v[218:219], v[220:223], off
	s_nop 1
	ds_read_u16 v147, v105 offset:24576
	v_cndmask_b32_e64 v146, v204, v205, s[4:5]
	v_add_f32_e32 v145, v146, v145
	ds_read_u16 v146, v105 offset:8192
	s_waitcnt lgkmcnt(1)
	v_lshlrev_b32_e32 v156, 16, v147
	v_mul_f32_e32 v147, 0x3fb8aa3b, v145
	v_exp_f32_e32 v147, v147
	s_waitcnt lgkmcnt(0)
	v_lshlrev_b32_e32 v146, 16, v146
	v_mul_f32_e32 v146, 0x3db504f3, v146
	v_mul_f32_e32 v146, v147, v146
	v_cvt_pk_bf16_f32 v157, v146, v146
	v_or_b32_e32 v146, v142, v76
	v_mov_b32_e32 v147, v143
	v_lshlrev_b64 v[146:147], 8, v[146:147]
	v_or_b32_e32 v146, v146, v144
	v_lshl_add_u64 v[154:155], s[36:37], 0, v[146:147]
	global_store_short_d16_hi v[154:155], v157, off
	v_mul_f32_e32 v154, 0xbfb8aa3b, v145
	v_exp_f32_e32 v154, v154
	v_lshl_add_u64 v[146:147], s[38:39], 0, v[146:147]
	v_mul_f32_e32 v154, v154, v156
	v_cvt_pk_bf16_f32 v154, v154, v154
	global_store_short_d16_hi v[146:147], v154, off
	v_sub_f32_e32 v146, v141, v145
	v_mul_f32_e32 v146, 0x3fb8aa3b, v146
	v_exp_f32_e32 v146, v146
	s_nop 0
	v_mul_f32_e32 v146, v146, v156
	v_cvt_pk_bf16_f32 v154, v146, v146
	v_lshlrev_b32_e32 v146, 1, v76
	v_mov_b32_e32 v147, v3
	v_lshl_add_u64 v[146:147], v[6:7], 0, v[146:147]
	v_lshrrev_b32_e32 v220, 16, v154
	ds_read_u16 v147, v107 offset:24576
	v_cndmask_b32_e64 v146, v203, v207, s[4:5]
	v_add_f32_e32 v145, v146, v145
	ds_read_u16 v146, v107 offset:8192
	s_waitcnt lgkmcnt(1)
	v_lshlrev_b32_e32 v156, 16, v147
	v_mul_f32_e32 v147, 0x3fb8aa3b, v145
	v_exp_f32_e32 v147, v147
	s_waitcnt lgkmcnt(0)
	v_lshlrev_b32_e32 v146, 16, v146
	v_mul_f32_e32 v146, 0x3db504f3, v146
	v_mul_f32_e32 v146, v147, v146
	v_cvt_pk_bf16_f32 v157, v146, v146
	v_or_b32_e32 v146, v142, v78
	v_mov_b32_e32 v147, v143
	v_lshlrev_b64 v[146:147], 8, v[146:147]
	v_or_b32_e32 v146, v146, v144
	v_lshl_add_u64 v[154:155], s[36:37], 0, v[146:147]
	global_store_short_d16_hi v[154:155], v157, off
	v_mul_f32_e32 v154, 0xbfb8aa3b, v145
	v_exp_f32_e32 v154, v154
	v_lshl_add_u64 v[146:147], s[38:39], 0, v[146:147]
	v_mul_f32_e32 v154, v154, v156
	v_cvt_pk_bf16_f32 v154, v154, v154
	global_store_short_d16_hi v[146:147], v154, off
	v_sub_f32_e32 v146, v141, v145
	v_mul_f32_e32 v146, 0x3fb8aa3b, v146
	v_exp_f32_e32 v146, v146
	s_nop 0
	v_mul_f32_e32 v146, v146, v156
	v_cvt_pk_bf16_f32 v154, v146, v146
	v_lshlrev_b32_e32 v146, 1, v78
	v_mov_b32_e32 v147, v3
	v_lshl_add_u64 v[146:147], v[6:7], 0, v[146:147]
	v_and_or_b32 v220, v154, s98, v220
	ds_read_u16 v147, v109 offset:24576
	v_cndmask_b32_e64 v146, v202, v210, s[4:5]
	v_add_f32_e32 v145, v146, v145
	ds_read_u16 v146, v109 offset:8192
	s_waitcnt lgkmcnt(1)
	v_lshlrev_b32_e32 v156, 16, v147
	v_mul_f32_e32 v147, 0x3fb8aa3b, v145
	v_exp_f32_e32 v147, v147
	s_waitcnt lgkmcnt(0)
	v_lshlrev_b32_e32 v146, 16, v146
	v_mul_f32_e32 v146, 0x3db504f3, v146
	v_mul_f32_e32 v146, v147, v146
	v_cvt_pk_bf16_f32 v157, v146, v146
	v_or_b32_e32 v146, v142, v80
	v_mov_b32_e32 v147, v143
	v_lshlrev_b64 v[146:147], 8, v[146:147]
	v_or_b32_e32 v146, v146, v144
	v_lshl_add_u64 v[154:155], s[36:37], 0, v[146:147]
	global_store_short_d16_hi v[154:155], v157, off
	v_mul_f32_e32 v154, 0xbfb8aa3b, v145
	v_exp_f32_e32 v154, v154
	v_lshl_add_u64 v[146:147], s[38:39], 0, v[146:147]
	v_mul_f32_e32 v154, v154, v156
	v_cvt_pk_bf16_f32 v154, v154, v154
	global_store_short_d16_hi v[146:147], v154, off
	v_sub_f32_e32 v146, v141, v145
	v_mul_f32_e32 v146, 0x3fb8aa3b, v146
	v_exp_f32_e32 v146, v146
	s_nop 0
	v_mul_f32_e32 v146, v146, v156
	v_cvt_pk_bf16_f32 v154, v146, v146
	v_lshlrev_b32_e32 v146, 1, v80
	v_mov_b32_e32 v147, v3
	v_lshl_add_u64 v[146:147], v[6:7], 0, v[146:147]
	v_lshrrev_b32_e32 v221, 16, v154
	ds_read_u16 v147, v111 offset:24576
	v_cndmask_b32_e64 v146, v201, v212, s[4:5]
	v_add_f32_e32 v145, v146, v145
	ds_read_u16 v146, v111 offset:8192
	s_waitcnt lgkmcnt(1)
	v_lshlrev_b32_e32 v156, 16, v147
	v_mul_f32_e32 v147, 0x3fb8aa3b, v145
	v_exp_f32_e32 v147, v147
	s_waitcnt lgkmcnt(0)
	v_lshlrev_b32_e32 v146, 16, v146
	v_mul_f32_e32 v146, 0x3db504f3, v146
	v_mul_f32_e32 v146, v147, v146
	v_cvt_pk_bf16_f32 v157, v146, v146
	v_or_b32_e32 v146, v142, v82
	v_mov_b32_e32 v147, v143
	v_lshlrev_b64 v[146:147], 8, v[146:147]
	v_or_b32_e32 v146, v146, v144
	v_lshl_add_u64 v[154:155], s[36:37], 0, v[146:147]
	global_store_short_d16_hi v[154:155], v157, off
	v_mul_f32_e32 v154, 0xbfb8aa3b, v145
	v_exp_f32_e32 v154, v154
	v_lshl_add_u64 v[146:147], s[38:39], 0, v[146:147]
	v_mul_f32_e32 v154, v154, v156
	v_cvt_pk_bf16_f32 v154, v154, v154
	global_store_short_d16_hi v[146:147], v154, off
	v_sub_f32_e32 v146, v141, v145
	v_mul_f32_e32 v146, 0x3fb8aa3b, v146
	v_exp_f32_e32 v146, v146
	s_nop 0
	v_mul_f32_e32 v146, v146, v156
	v_cvt_pk_bf16_f32 v154, v146, v146
	v_lshlrev_b32_e32 v146, 1, v82
	v_mov_b32_e32 v147, v3
	v_lshl_add_u64 v[146:147], v[6:7], 0, v[146:147]
	v_and_or_b32 v221, v154, s98, v221
	ds_read_u16 v147, v113 offset:24576
	v_cndmask_b32_e64 v146, v200, v206, s[4:5]
	v_add_f32_e32 v145, v146, v145
	ds_read_u16 v146, v113 offset:8192
	s_waitcnt lgkmcnt(1)
	v_lshlrev_b32_e32 v156, 16, v147
	v_mul_f32_e32 v147, 0x3fb8aa3b, v145
	v_exp_f32_e32 v147, v147
	s_waitcnt lgkmcnt(0)
	v_lshlrev_b32_e32 v146, 16, v146
	v_mul_f32_e32 v146, 0x3db504f3, v146
	v_mul_f32_e32 v146, v147, v146
	v_cvt_pk_bf16_f32 v157, v146, v146
	v_or_b32_e32 v146, v142, v84
	v_mov_b32_e32 v147, v143
	v_lshlrev_b64 v[146:147], 8, v[146:147]
	v_or_b32_e32 v146, v146, v144
	v_lshl_add_u64 v[154:155], s[36:37], 0, v[146:147]
	global_store_short_d16_hi v[154:155], v157, off
	v_mul_f32_e32 v154, 0xbfb8aa3b, v145
	v_exp_f32_e32 v154, v154
	v_lshl_add_u64 v[146:147], s[38:39], 0, v[146:147]
	v_mul_f32_e32 v154, v154, v156
	v_cvt_pk_bf16_f32 v154, v154, v154
	global_store_short_d16_hi v[146:147], v154, off
	v_sub_f32_e32 v146, v141, v145
	v_mul_f32_e32 v146, 0x3fb8aa3b, v146
	v_exp_f32_e32 v146, v146
	s_nop 0
	v_mul_f32_e32 v146, v146, v156
	v_cvt_pk_bf16_f32 v154, v146, v146
	v_lshlrev_b32_e32 v146, 1, v84
	v_mov_b32_e32 v147, v3
	v_lshl_add_u64 v[146:147], v[6:7], 0, v[146:147]
	v_lshrrev_b32_e32 v222, 16, v154
	ds_read_u16 v147, v115 offset:24576
	v_cndmask_b32_e64 v146, v199, v209, s[4:5]
	v_add_f32_e32 v145, v146, v145
	ds_read_u16 v146, v115 offset:8192
	s_waitcnt lgkmcnt(1)
	v_lshlrev_b32_e32 v156, 16, v147
	v_mul_f32_e32 v147, 0x3fb8aa3b, v145
	v_exp_f32_e32 v147, v147
	s_waitcnt lgkmcnt(0)
	v_lshlrev_b32_e32 v146, 16, v146
	v_mul_f32_e32 v146, 0x3db504f3, v146
	v_mul_f32_e32 v146, v147, v146
	v_cvt_pk_bf16_f32 v157, v146, v146
	v_or_b32_e32 v146, v142, v86
	v_mov_b32_e32 v147, v143
	v_lshlrev_b64 v[146:147], 8, v[146:147]
	v_or_b32_e32 v146, v146, v144
	v_lshl_add_u64 v[154:155], s[36:37], 0, v[146:147]
	global_store_short_d16_hi v[154:155], v157, off
	v_mul_f32_e32 v154, 0xbfb8aa3b, v145
	v_exp_f32_e32 v154, v154
	v_lshl_add_u64 v[146:147], s[38:39], 0, v[146:147]
	v_mul_f32_e32 v154, v154, v156
	v_cvt_pk_bf16_f32 v154, v154, v154
	global_store_short_d16_hi v[146:147], v154, off
	v_sub_f32_e32 v146, v141, v145
	v_mul_f32_e32 v146, 0x3fb8aa3b, v146
	v_exp_f32_e32 v146, v146
	s_nop 0
	v_mul_f32_e32 v146, v146, v156
	v_cvt_pk_bf16_f32 v154, v146, v146
	v_lshlrev_b32_e32 v146, 1, v86
	v_mov_b32_e32 v147, v3
	v_lshl_add_u64 v[146:147], v[6:7], 0, v[146:147]
	v_and_or_b32 v222, v154, s98, v222
	ds_read_u16 v147, v117 offset:24576
	v_cndmask_b32_e64 v146, v198, v214, s[4:5]
	v_add_f32_e32 v145, v146, v145
	ds_read_u16 v146, v117 offset:8192
	s_waitcnt lgkmcnt(1)
	v_lshlrev_b32_e32 v156, 16, v147
	v_mul_f32_e32 v147, 0x3fb8aa3b, v145
	v_exp_f32_e32 v147, v147
	s_waitcnt lgkmcnt(0)
	v_lshlrev_b32_e32 v146, 16, v146
	v_mul_f32_e32 v146, 0x3db504f3, v146
	v_mul_f32_e32 v146, v147, v146
	v_cvt_pk_bf16_f32 v157, v146, v146
	v_or_b32_e32 v146, v142, v88
	v_mov_b32_e32 v147, v143
	v_lshlrev_b64 v[146:147], 8, v[146:147]
	v_or_b32_e32 v146, v146, v144
	v_lshl_add_u64 v[154:155], s[36:37], 0, v[146:147]
	global_store_short_d16_hi v[154:155], v157, off
	v_mul_f32_e32 v154, 0xbfb8aa3b, v145
	v_exp_f32_e32 v154, v154
	v_lshl_add_u64 v[146:147], s[38:39], 0, v[146:147]
	v_mul_f32_e32 v154, v154, v156
	v_cvt_pk_bf16_f32 v154, v154, v154
	global_store_short_d16_hi v[146:147], v154, off
	v_sub_f32_e32 v146, v141, v145
	v_mul_f32_e32 v146, 0x3fb8aa3b, v146
	v_exp_f32_e32 v146, v146
	s_nop 0
	v_mul_f32_e32 v146, v146, v156
	v_cvt_pk_bf16_f32 v154, v146, v146
	v_lshlrev_b32_e32 v146, 1, v88
	v_mov_b32_e32 v147, v3
	v_lshl_add_u64 v[146:147], v[6:7], 0, v[146:147]
	v_lshrrev_b32_e32 v223, 16, v154
	ds_read_u16 v147, v119 offset:24576
	v_cndmask_b32_e64 v146, v197, v216, s[4:5]
	v_add_f32_e32 v145, v146, v145
	ds_read_u16 v146, v119 offset:8192
	s_waitcnt lgkmcnt(1)
	v_lshlrev_b32_e32 v156, 16, v147
	v_mul_f32_e32 v147, 0x3fb8aa3b, v145
	v_exp_f32_e32 v147, v147
	s_waitcnt lgkmcnt(0)
	v_lshlrev_b32_e32 v146, 16, v146
	v_mul_f32_e32 v146, 0x3db504f3, v146
	v_mul_f32_e32 v146, v147, v146
	v_cvt_pk_bf16_f32 v157, v146, v146
	v_or_b32_e32 v146, v142, v90
	v_mov_b32_e32 v147, v143
	v_lshlrev_b64 v[146:147], 8, v[146:147]
	v_or_b32_e32 v146, v146, v144
	v_lshl_add_u64 v[154:155], s[36:37], 0, v[146:147]
	global_store_short_d16_hi v[154:155], v157, off
	v_mul_f32_e32 v154, 0xbfb8aa3b, v145
	v_exp_f32_e32 v154, v154
	v_lshl_add_u64 v[146:147], s[38:39], 0, v[146:147]
	v_mul_f32_e32 v154, v154, v156
	v_cvt_pk_bf16_f32 v154, v154, v154
	global_store_short_d16_hi v[146:147], v154, off
	v_sub_f32_e32 v146, v141, v145
	v_mul_f32_e32 v146, 0x3fb8aa3b, v146
	v_exp_f32_e32 v146, v146
	s_nop 0
	v_mul_f32_e32 v146, v146, v156
	v_cvt_pk_bf16_f32 v154, v146, v146
	v_lshlrev_b32_e32 v146, 1, v90
	v_mov_b32_e32 v147, v3
	v_lshl_add_u64 v[146:147], v[6:7], 0, v[146:147]
	v_and_or_b32 v223, v154, s98, v223
	v_alignbit_b32 v226, v223, v223, 16
	v_alignbit_b32 v218, v220, v220, 16
	v_cndmask_b32_e64 v220, v226, v220, s[4:5]
	v_cndmask_b32_e64 v223, v218, v223, s[4:5]
	v_alignbit_b32 v226, v222, v222, 16
	v_alignbit_b32 v218, v221, v221, 16
	v_cndmask_b32_e64 v221, v226, v221, s[4:5]
	v_cndmask_b32_e64 v222, v218, v222, s[4:5]
	v_lshl_add_u64 v[218:219], v[146:147], 0, v[224:225]
	global_store_dwordx4 v[218:219], v[220:223], off
	s_nop 1
	ds_read_u16 v147, v121 offset:24576
	v_cndmask_b32_e64 v146, v196, v208, s[4:5]
	v_add_f32_e32 v145, v146, v145
	ds_read_u16 v146, v121 offset:8192
	s_waitcnt lgkmcnt(1)
	v_lshlrev_b32_e32 v156, 16, v147
	v_mul_f32_e32 v147, 0x3fb8aa3b, v145
	v_exp_f32_e32 v147, v147
	s_waitcnt lgkmcnt(0)
	v_lshlrev_b32_e32 v146, 16, v146
	v_mul_f32_e32 v146, 0x3db504f3, v146
	v_mul_f32_e32 v146, v147, v146
	v_cvt_pk_bf16_f32 v157, v146, v146
	v_or_b32_e32 v146, v142, v92
	v_mov_b32_e32 v147, v143
	v_lshlrev_b64 v[146:147], 8, v[146:147]
	v_or_b32_e32 v146, v146, v144
	v_lshl_add_u64 v[154:155], s[36:37], 0, v[146:147]
	global_store_short_d16_hi v[154:155], v157, off
	v_mul_f32_e32 v154, 0xbfb8aa3b, v145
	v_exp_f32_e32 v154, v154
	v_lshl_add_u64 v[146:147], s[38:39], 0, v[146:147]
	v_mul_f32_e32 v154, v154, v156
	v_cvt_pk_bf16_f32 v154, v154, v154
	global_store_short_d16_hi v[146:147], v154, off
	v_sub_f32_e32 v146, v141, v145
	v_mul_f32_e32 v146, 0x3fb8aa3b, v146
	v_exp_f32_e32 v146, v146
	s_nop 0
	v_mul_f32_e32 v146, v146, v156
	v_cvt_pk_bf16_f32 v154, v146, v146
	v_lshlrev_b32_e32 v146, 1, v92
	v_mov_b32_e32 v147, v3
	v_lshl_add_u64 v[146:147], v[6:7], 0, v[146:147]
	v_lshrrev_b32_e32 v220, 16, v154
	ds_read_u16 v147, v123 offset:24576
	v_cndmask_b32_e64 v146, v195, v213, s[4:5]
	v_add_f32_e32 v145, v146, v145
	ds_read_u16 v146, v123 offset:8192
	s_waitcnt lgkmcnt(1)
	v_lshlrev_b32_e32 v156, 16, v147
	v_mul_f32_e32 v147, 0x3fb8aa3b, v145
	v_exp_f32_e32 v147, v147
	s_waitcnt lgkmcnt(0)
	v_lshlrev_b32_e32 v146, 16, v146
	v_mul_f32_e32 v146, 0x3db504f3, v146
	v_mul_f32_e32 v146, v147, v146
	v_cvt_pk_bf16_f32 v157, v146, v146
	v_or_b32_e32 v146, v142, v94
	v_mov_b32_e32 v147, v143
	v_lshlrev_b64 v[146:147], 8, v[146:147]
	v_or_b32_e32 v146, v146, v144
	v_lshl_add_u64 v[154:155], s[36:37], 0, v[146:147]
	global_store_short_d16_hi v[154:155], v157, off
	v_mul_f32_e32 v154, 0xbfb8aa3b, v145
	v_exp_f32_e32 v154, v154
	v_lshl_add_u64 v[146:147], s[38:39], 0, v[146:147]
	v_mul_f32_e32 v154, v154, v156
	v_cvt_pk_bf16_f32 v154, v154, v154
	global_store_short_d16_hi v[146:147], v154, off
	v_sub_f32_e32 v146, v141, v145
	v_mul_f32_e32 v146, 0x3fb8aa3b, v146
	v_exp_f32_e32 v146, v146
	s_nop 0
	v_mul_f32_e32 v146, v146, v156
	v_cvt_pk_bf16_f32 v154, v146, v146
	v_lshlrev_b32_e32 v146, 1, v94
	v_mov_b32_e32 v147, v3
	v_lshl_add_u64 v[146:147], v[6:7], 0, v[146:147]
	v_and_or_b32 v220, v154, s98, v220
	ds_read_u16 v147, v125 offset:24576
	v_cndmask_b32_e64 v146, v194, v234, s[4:5]
	v_add_f32_e32 v145, v146, v145
	ds_read_u16 v146, v125 offset:8192
	s_waitcnt lgkmcnt(1)
	v_lshlrev_b32_e32 v156, 16, v147
	v_mul_f32_e32 v147, 0x3fb8aa3b, v145
	v_exp_f32_e32 v147, v147
	s_waitcnt lgkmcnt(0)
	v_lshlrev_b32_e32 v146, 16, v146
	v_mul_f32_e32 v146, 0x3db504f3, v146
	v_mul_f32_e32 v146, v147, v146
	v_cvt_pk_bf16_f32 v157, v146, v146
	v_or_b32_e32 v146, v142, v96
	v_mov_b32_e32 v147, v143
	v_lshlrev_b64 v[146:147], 8, v[146:147]
	v_or_b32_e32 v146, v146, v144
	v_lshl_add_u64 v[154:155], s[36:37], 0, v[146:147]
	global_store_short_d16_hi v[154:155], v157, off
	v_mul_f32_e32 v154, 0xbfb8aa3b, v145
	v_exp_f32_e32 v154, v154
	v_lshl_add_u64 v[146:147], s[38:39], 0, v[146:147]
	v_mul_f32_e32 v154, v154, v156
	v_cvt_pk_bf16_f32 v154, v154, v154
	global_store_short_d16_hi v[146:147], v154, off
	v_sub_f32_e32 v146, v141, v145
	v_mul_f32_e32 v146, 0x3fb8aa3b, v146
	v_exp_f32_e32 v146, v146
	s_nop 0
	v_mul_f32_e32 v146, v146, v156
	v_cvt_pk_bf16_f32 v154, v146, v146
	v_lshlrev_b32_e32 v146, 1, v96
	v_mov_b32_e32 v147, v3
	v_lshl_add_u64 v[146:147], v[6:7], 0, v[146:147]
	v_lshrrev_b32_e32 v221, 16, v154
	ds_read_u16 v147, v127 offset:24576
	v_cndmask_b32_e64 v146, v193, v236, s[4:5]
	v_add_f32_e32 v145, v146, v145
	ds_read_u16 v146, v127 offset:8192
	s_waitcnt lgkmcnt(1)
	v_lshlrev_b32_e32 v156, 16, v147
	v_mul_f32_e32 v147, 0x3fb8aa3b, v145
	v_exp_f32_e32 v147, v147
	s_waitcnt lgkmcnt(0)
	v_lshlrev_b32_e32 v146, 16, v146
	v_mul_f32_e32 v146, 0x3db504f3, v146
	v_mul_f32_e32 v146, v147, v146
	v_cvt_pk_bf16_f32 v157, v146, v146
	v_or_b32_e32 v146, v142, v98
	v_mov_b32_e32 v147, v143
	v_lshlrev_b64 v[146:147], 8, v[146:147]
	v_or_b32_e32 v146, v146, v144
	v_lshl_add_u64 v[154:155], s[36:37], 0, v[146:147]
	global_store_short_d16_hi v[154:155], v157, off
	v_mul_f32_e32 v154, 0xbfb8aa3b, v145
	v_exp_f32_e32 v154, v154
	v_lshl_add_u64 v[146:147], s[38:39], 0, v[146:147]
	v_mul_f32_e32 v154, v154, v156
	v_cvt_pk_bf16_f32 v154, v154, v154
	global_store_short_d16_hi v[146:147], v154, off
	v_sub_f32_e32 v146, v141, v145
	v_mul_f32_e32 v146, 0x3fb8aa3b, v146
	v_exp_f32_e32 v146, v146
	s_nop 0
	v_mul_f32_e32 v146, v146, v156
	v_cvt_pk_bf16_f32 v154, v146, v146
	v_lshlrev_b32_e32 v146, 1, v98
	v_mov_b32_e32 v147, v3
	v_lshl_add_u64 v[146:147], v[6:7], 0, v[146:147]
	v_and_or_b32 v221, v154, s98, v221
	ds_read_u16 v147, v129 offset:24576
	v_cndmask_b32_e64 v146, v192, v211, s[4:5]
	v_add_f32_e32 v145, v146, v145
	ds_read_u16 v146, v129 offset:8192
	s_waitcnt lgkmcnt(1)
	v_lshlrev_b32_e32 v156, 16, v147
	v_mul_f32_e32 v147, 0x3fb8aa3b, v145
	v_exp_f32_e32 v147, v147
	s_waitcnt lgkmcnt(0)
	v_lshlrev_b32_e32 v146, 16, v146
	v_mul_f32_e32 v146, 0x3db504f3, v146
	v_mul_f32_e32 v146, v147, v146
	v_cvt_pk_bf16_f32 v157, v146, v146
	v_or_b32_e32 v146, v142, v100
	v_mov_b32_e32 v147, v143
	v_lshlrev_b64 v[146:147], 8, v[146:147]
	v_or_b32_e32 v146, v146, v144
	v_lshl_add_u64 v[154:155], s[36:37], 0, v[146:147]
	global_store_short_d16_hi v[154:155], v157, off
	v_mul_f32_e32 v154, 0xbfb8aa3b, v145
	v_exp_f32_e32 v154, v154
	v_lshl_add_u64 v[146:147], s[38:39], 0, v[146:147]
	v_mul_f32_e32 v154, v154, v156
	v_cvt_pk_bf16_f32 v154, v154, v154
	global_store_short_d16_hi v[146:147], v154, off
	v_sub_f32_e32 v146, v141, v145
	v_mul_f32_e32 v146, 0x3fb8aa3b, v146
	v_exp_f32_e32 v146, v146
	s_nop 0
	v_mul_f32_e32 v146, v146, v156
	v_cvt_pk_bf16_f32 v154, v146, v146
	v_lshlrev_b32_e32 v146, 1, v100
	v_mov_b32_e32 v147, v3
	v_lshl_add_u64 v[146:147], v[6:7], 0, v[146:147]
	v_lshrrev_b32_e32 v222, 16, v154
	ds_read_u16 v147, v131 offset:24576
	v_cndmask_b32_e64 v146, v191, v217, s[4:5]
	v_add_f32_e32 v145, v146, v145
	ds_read_u16 v146, v131 offset:8192
	s_waitcnt lgkmcnt(1)
	v_lshlrev_b32_e32 v156, 16, v147
	v_mul_f32_e32 v147, 0x3fb8aa3b, v145
	v_exp_f32_e32 v147, v147
	s_waitcnt lgkmcnt(0)
	v_lshlrev_b32_e32 v146, 16, v146
	v_mul_f32_e32 v146, 0x3db504f3, v146
	v_mul_f32_e32 v146, v147, v146
	v_cvt_pk_bf16_f32 v157, v146, v146
	v_or_b32_e32 v146, v142, v102
	v_mov_b32_e32 v147, v143
	v_lshlrev_b64 v[146:147], 8, v[146:147]
	v_or_b32_e32 v146, v146, v144
	v_lshl_add_u64 v[154:155], s[36:37], 0, v[146:147]
	global_store_short_d16_hi v[154:155], v157, off
	v_mul_f32_e32 v154, 0xbfb8aa3b, v145
	v_exp_f32_e32 v154, v154
	v_lshl_add_u64 v[146:147], s[38:39], 0, v[146:147]
	v_mul_f32_e32 v154, v154, v156
	v_cvt_pk_bf16_f32 v154, v154, v154
	global_store_short_d16_hi v[146:147], v154, off
	v_sub_f32_e32 v146, v141, v145
	v_mul_f32_e32 v146, 0x3fb8aa3b, v146
	v_exp_f32_e32 v146, v146
	s_nop 0
	v_mul_f32_e32 v146, v146, v156
	v_cvt_pk_bf16_f32 v154, v146, v146
	v_lshlrev_b32_e32 v146, 1, v102
	v_mov_b32_e32 v147, v3
	v_lshl_add_u64 v[146:147], v[6:7], 0, v[146:147]
	v_and_or_b32 v222, v154, s98, v222
	ds_read_u16 v147, v133 offset:24576
	v_cndmask_b32_e64 v146, v190, v238, s[4:5]
	v_add_f32_e32 v145, v146, v145
	ds_read_u16 v146, v133 offset:8192
	s_waitcnt lgkmcnt(1)
	v_lshlrev_b32_e32 v156, 16, v147
	v_mul_f32_e32 v147, 0x3fb8aa3b, v145
	v_exp_f32_e32 v147, v147
	s_waitcnt lgkmcnt(0)
	v_lshlrev_b32_e32 v146, 16, v146
	v_mul_f32_e32 v146, 0x3db504f3, v146
	v_mul_f32_e32 v146, v147, v146
	v_cvt_pk_bf16_f32 v157, v146, v146
	v_or_b32_e32 v146, v142, v104
	v_mov_b32_e32 v147, v143
	v_lshlrev_b64 v[146:147], 8, v[146:147]
	v_or_b32_e32 v146, v146, v144
	v_lshl_add_u64 v[154:155], s[36:37], 0, v[146:147]
	global_store_short_d16_hi v[154:155], v157, off
	v_mul_f32_e32 v154, 0xbfb8aa3b, v145
	v_exp_f32_e32 v154, v154
	v_lshl_add_u64 v[146:147], s[38:39], 0, v[146:147]
	v_mul_f32_e32 v154, v154, v156
	v_cvt_pk_bf16_f32 v154, v154, v154
	global_store_short_d16_hi v[146:147], v154, off
	v_sub_f32_e32 v146, v141, v145
	v_mul_f32_e32 v146, 0x3fb8aa3b, v146
	v_exp_f32_e32 v146, v146
	s_nop 0
	v_mul_f32_e32 v146, v146, v156
	v_cvt_pk_bf16_f32 v154, v146, v146
	v_lshlrev_b32_e32 v146, 1, v104
	v_mov_b32_e32 v147, v3
	v_lshl_add_u64 v[146:147], v[6:7], 0, v[146:147]
	v_lshrrev_b32_e32 v223, 16, v154
	ds_read_u16 v147, v135 offset:24576
	v_cndmask_b32_e64 v146, v189, v240, s[4:5]
	v_add_f32_e32 v145, v146, v145
	ds_read_u16 v146, v135 offset:8192
	s_waitcnt lgkmcnt(1)
	v_lshlrev_b32_e32 v156, 16, v147
	v_mul_f32_e32 v147, 0x3fb8aa3b, v145
	v_exp_f32_e32 v147, v147
	s_waitcnt lgkmcnt(0)
	v_lshlrev_b32_e32 v146, 16, v146
	v_mul_f32_e32 v146, 0x3db504f3, v146
	v_mul_f32_e32 v146, v147, v146
	v_cvt_pk_bf16_f32 v157, v146, v146
	v_or_b32_e32 v146, v142, v106
	v_mov_b32_e32 v147, v143
	v_lshlrev_b64 v[146:147], 8, v[146:147]
	v_or_b32_e32 v146, v146, v144
	v_lshl_add_u64 v[154:155], s[36:37], 0, v[146:147]
	global_store_short_d16_hi v[154:155], v157, off
	v_mul_f32_e32 v154, 0xbfb8aa3b, v145
	v_exp_f32_e32 v154, v154
	v_lshl_add_u64 v[146:147], s[38:39], 0, v[146:147]
	v_mul_f32_e32 v154, v154, v156
	v_cvt_pk_bf16_f32 v154, v154, v154
	global_store_short_d16_hi v[146:147], v154, off
	v_sub_f32_e32 v146, v141, v145
	v_mul_f32_e32 v146, 0x3fb8aa3b, v146
	v_exp_f32_e32 v146, v146
	s_nop 0
	v_mul_f32_e32 v146, v146, v156
	v_cvt_pk_bf16_f32 v154, v146, v146
	v_lshlrev_b32_e32 v146, 1, v106
	v_mov_b32_e32 v147, v3
	v_lshl_add_u64 v[146:147], v[6:7], 0, v[146:147]
	v_and_or_b32 v223, v154, s98, v223
	v_alignbit_b32 v226, v223, v223, 16
	v_alignbit_b32 v218, v220, v220, 16
	v_cndmask_b32_e64 v220, v226, v220, s[4:5]
	v_cndmask_b32_e64 v223, v218, v223, s[4:5]
	v_alignbit_b32 v226, v222, v222, 16
	v_alignbit_b32 v218, v221, v221, 16
	v_cndmask_b32_e64 v221, v226, v221, s[4:5]
	v_cndmask_b32_e64 v222, v218, v222, s[4:5]
	v_lshl_add_u64 v[218:219], v[146:147], 0, v[224:225]
	global_store_dwordx4 v[218:219], v[220:223], off
	s_nop 1
	ds_read_u16 v147, v137 offset:24576
	v_cndmask_b32_e64 v146, v188, v215, s[4:5]
	v_add_f32_e32 v145, v146, v145
	ds_read_u16 v146, v137 offset:8192
	s_waitcnt lgkmcnt(1)
	v_lshlrev_b32_e32 v156, 16, v147
	v_mul_f32_e32 v147, 0x3fb8aa3b, v145
	v_exp_f32_e32 v147, v147
	s_waitcnt lgkmcnt(0)
	v_lshlrev_b32_e32 v146, 16, v146
	v_mul_f32_e32 v146, 0x3db504f3, v146
	v_mul_f32_e32 v146, v147, v146
	v_cvt_pk_bf16_f32 v157, v146, v146
	v_or_b32_e32 v146, v142, v108
	v_mov_b32_e32 v147, v143
	v_lshlrev_b64 v[146:147], 8, v[146:147]
	v_or_b32_e32 v146, v146, v144
	v_lshl_add_u64 v[154:155], s[36:37], 0, v[146:147]
	global_store_short_d16_hi v[154:155], v157, off
	v_mul_f32_e32 v154, 0xbfb8aa3b, v145
	v_exp_f32_e32 v154, v154
	v_lshl_add_u64 v[146:147], s[38:39], 0, v[146:147]
	v_mul_f32_e32 v154, v154, v156
	v_cvt_pk_bf16_f32 v154, v154, v154
	global_store_short_d16_hi v[146:147], v154, off
	v_sub_f32_e32 v146, v141, v145
	v_mul_f32_e32 v146, 0x3fb8aa3b, v146
	v_exp_f32_e32 v146, v146
	s_nop 0
	v_mul_f32_e32 v146, v146, v156
	v_cvt_pk_bf16_f32 v154, v146, v146
	v_lshlrev_b32_e32 v146, 1, v108
	v_mov_b32_e32 v147, v3
	v_lshl_add_u64 v[146:147], v[6:7], 0, v[146:147]
	v_lshrrev_b32_e32 v220, 16, v154
	ds_read_u16 v147, v139 offset:24576
	v_cndmask_b32_e64 v146, v187, v237, s[4:5]
	v_add_f32_e32 v145, v146, v145
	ds_read_u16 v146, v139 offset:8192
	s_waitcnt lgkmcnt(1)
	v_lshlrev_b32_e32 v156, 16, v147
	v_mul_f32_e32 v147, 0x3fb8aa3b, v145
	v_exp_f32_e32 v147, v147
	s_waitcnt lgkmcnt(0)
	v_lshlrev_b32_e32 v146, 16, v146
	v_mul_f32_e32 v146, 0x3db504f3, v146
	v_mul_f32_e32 v146, v147, v146
	v_cvt_pk_bf16_f32 v157, v146, v146
	v_or_b32_e32 v146, v142, v110
	v_mov_b32_e32 v147, v143
	v_lshlrev_b64 v[146:147], 8, v[146:147]
	v_or_b32_e32 v146, v146, v144
	v_lshl_add_u64 v[154:155], s[36:37], 0, v[146:147]
	global_store_short_d16_hi v[154:155], v157, off
	v_mul_f32_e32 v154, 0xbfb8aa3b, v145
	v_exp_f32_e32 v154, v154
	v_lshl_add_u64 v[146:147], s[38:39], 0, v[146:147]
	v_mul_f32_e32 v154, v154, v156
	v_cvt_pk_bf16_f32 v154, v154, v154
	global_store_short_d16_hi v[146:147], v154, off
	v_sub_f32_e32 v146, v141, v145
	v_mul_f32_e32 v146, 0x3fb8aa3b, v146
	v_exp_f32_e32 v146, v146
	s_nop 0
	v_mul_f32_e32 v146, v146, v156
	v_cvt_pk_bf16_f32 v154, v146, v146
	v_lshlrev_b32_e32 v146, 1, v110
	v_mov_b32_e32 v147, v3
	v_lshl_add_u64 v[146:147], v[6:7], 0, v[146:147]
	v_and_or_b32 v220, v154, s98, v220
	ds_read_u16 v147, v148 offset:24576
	v_cndmask_b32_e64 v146, v186, v242, s[4:5]
	v_add_f32_e32 v145, v146, v145
	ds_read_u16 v146, v148 offset:8192
	s_waitcnt lgkmcnt(1)
	v_lshlrev_b32_e32 v156, 16, v147
	v_mul_f32_e32 v147, 0x3fb8aa3b, v145
	v_exp_f32_e32 v147, v147
	s_waitcnt lgkmcnt(0)
	v_lshlrev_b32_e32 v146, 16, v146
	v_mul_f32_e32 v146, 0x3db504f3, v146
	v_mul_f32_e32 v146, v147, v146
	v_cvt_pk_bf16_f32 v157, v146, v146
	v_or_b32_e32 v146, v142, v112
	v_mov_b32_e32 v147, v143
	v_lshlrev_b64 v[146:147], 8, v[146:147]
	v_or_b32_e32 v146, v146, v144
	v_lshl_add_u64 v[154:155], s[36:37], 0, v[146:147]
	global_store_short_d16_hi v[154:155], v157, off
	v_mul_f32_e32 v154, 0xbfb8aa3b, v145
	v_exp_f32_e32 v154, v154
	v_lshl_add_u64 v[146:147], s[38:39], 0, v[146:147]
	v_mul_f32_e32 v154, v154, v156
	v_cvt_pk_bf16_f32 v154, v154, v154
	global_store_short_d16_hi v[146:147], v154, off
	v_sub_f32_e32 v146, v141, v145
	v_mul_f32_e32 v146, 0x3fb8aa3b, v146
	v_exp_f32_e32 v146, v146
	s_nop 0
	v_mul_f32_e32 v146, v146, v156
	v_cvt_pk_bf16_f32 v154, v146, v146
	v_lshlrev_b32_e32 v146, 1, v112
	v_mov_b32_e32 v147, v3
	v_lshl_add_u64 v[146:147], v[6:7], 0, v[146:147]
	v_lshrrev_b32_e32 v221, 16, v154
	ds_read_u16 v147, v149 offset:24576
	v_cndmask_b32_e64 v146, v185, v244, s[4:5]
	v_add_f32_e32 v145, v146, v145
	ds_read_u16 v146, v149 offset:8192
	s_waitcnt lgkmcnt(1)
	v_lshlrev_b32_e32 v156, 16, v147
	v_mul_f32_e32 v147, 0x3fb8aa3b, v145
	v_exp_f32_e32 v147, v147
	s_waitcnt lgkmcnt(0)
	v_lshlrev_b32_e32 v146, 16, v146
	v_mul_f32_e32 v146, 0x3db504f3, v146
	v_mul_f32_e32 v146, v147, v146
	v_cvt_pk_bf16_f32 v157, v146, v146
	v_or_b32_e32 v146, v142, v114
	v_mov_b32_e32 v147, v143
	v_lshlrev_b64 v[146:147], 8, v[146:147]
	v_or_b32_e32 v146, v146, v144
	v_lshl_add_u64 v[154:155], s[36:37], 0, v[146:147]
	global_store_short_d16_hi v[154:155], v157, off
	v_mul_f32_e32 v154, 0xbfb8aa3b, v145
	v_exp_f32_e32 v154, v154
	v_lshl_add_u64 v[146:147], s[38:39], 0, v[146:147]
	v_mul_f32_e32 v154, v154, v156
	v_cvt_pk_bf16_f32 v154, v154, v154
	global_store_short_d16_hi v[146:147], v154, off
	v_sub_f32_e32 v146, v141, v145
	v_mul_f32_e32 v146, 0x3fb8aa3b, v146
	v_exp_f32_e32 v146, v146
	s_nop 0
	v_mul_f32_e32 v146, v146, v156
	v_cvt_pk_bf16_f32 v154, v146, v146
	v_lshlrev_b32_e32 v146, 1, v114
	v_mov_b32_e32 v147, v3
	v_lshl_add_u64 v[146:147], v[6:7], 0, v[146:147]
	v_and_or_b32 v221, v154, s98, v221
	ds_read_u16 v147, v150 offset:24576
	v_cndmask_b32_e64 v146, v184, v235, s[4:5]
	v_add_f32_e32 v145, v146, v145
	ds_read_u16 v146, v150 offset:8192
	s_waitcnt lgkmcnt(1)
	v_lshlrev_b32_e32 v156, 16, v147
	v_mul_f32_e32 v147, 0x3fb8aa3b, v145
	v_exp_f32_e32 v147, v147
	s_waitcnt lgkmcnt(0)
	v_lshlrev_b32_e32 v146, 16, v146
	v_mul_f32_e32 v146, 0x3db504f3, v146
	v_mul_f32_e32 v146, v147, v146
	v_cvt_pk_bf16_f32 v157, v146, v146
	v_or_b32_e32 v146, v142, v116
	v_mov_b32_e32 v147, v143
	v_lshlrev_b64 v[146:147], 8, v[146:147]
	v_or_b32_e32 v146, v146, v144
	v_lshl_add_u64 v[154:155], s[36:37], 0, v[146:147]
	global_store_short_d16_hi v[154:155], v157, off
	v_mul_f32_e32 v154, 0xbfb8aa3b, v145
	v_exp_f32_e32 v154, v154
	v_lshl_add_u64 v[146:147], s[38:39], 0, v[146:147]
	v_mul_f32_e32 v154, v154, v156
	v_cvt_pk_bf16_f32 v154, v154, v154
	global_store_short_d16_hi v[146:147], v154, off
	v_sub_f32_e32 v146, v141, v145
	v_mul_f32_e32 v146, 0x3fb8aa3b, v146
	v_exp_f32_e32 v146, v146
	s_nop 0
	v_mul_f32_e32 v146, v146, v156
	v_cvt_pk_bf16_f32 v154, v146, v146
	v_lshlrev_b32_e32 v146, 1, v116
	v_mov_b32_e32 v147, v3
	v_lshl_add_u64 v[146:147], v[6:7], 0, v[146:147]
	v_lshrrev_b32_e32 v222, 16, v154
	ds_read_u16 v147, v151 offset:24576
	v_cndmask_b32_e64 v146, v183, v241, s[4:5]
	v_add_f32_e32 v145, v146, v145
	ds_read_u16 v146, v151 offset:8192
	s_waitcnt lgkmcnt(1)
	v_lshlrev_b32_e32 v156, 16, v147
	v_mul_f32_e32 v147, 0x3fb8aa3b, v145
	v_exp_f32_e32 v147, v147
	s_waitcnt lgkmcnt(0)
	v_lshlrev_b32_e32 v146, 16, v146
	v_mul_f32_e32 v146, 0x3db504f3, v146
	v_mul_f32_e32 v146, v147, v146
	v_cvt_pk_bf16_f32 v157, v146, v146
	v_or_b32_e32 v146, v142, v118
	v_mov_b32_e32 v147, v143
	v_lshlrev_b64 v[146:147], 8, v[146:147]
	v_or_b32_e32 v146, v146, v144
	v_lshl_add_u64 v[154:155], s[36:37], 0, v[146:147]
	global_store_short_d16_hi v[154:155], v157, off
	v_mul_f32_e32 v154, 0xbfb8aa3b, v145
	v_exp_f32_e32 v154, v154
	v_lshl_add_u64 v[146:147], s[38:39], 0, v[146:147]
	v_mul_f32_e32 v154, v154, v156
	v_cvt_pk_bf16_f32 v154, v154, v154
	global_store_short_d16_hi v[146:147], v154, off
	v_sub_f32_e32 v146, v141, v145
	v_mul_f32_e32 v146, 0x3fb8aa3b, v146
	v_exp_f32_e32 v146, v146
	s_nop 0
	v_mul_f32_e32 v146, v146, v156
	v_cvt_pk_bf16_f32 v154, v146, v146
	v_lshlrev_b32_e32 v146, 1, v118
	v_mov_b32_e32 v147, v3
	v_lshl_add_u64 v[146:147], v[6:7], 0, v[146:147]
	v_and_or_b32 v222, v154, s98, v222
	ds_read_u16 v147, v152 offset:24576
	v_cndmask_b32_e64 v146, v182, v246, s[4:5]
	v_add_f32_e32 v145, v146, v145
	ds_read_u16 v146, v152 offset:8192
	s_waitcnt lgkmcnt(1)
	v_lshlrev_b32_e32 v156, 16, v147
	v_mul_f32_e32 v147, 0x3fb8aa3b, v145
	v_exp_f32_e32 v147, v147
	s_waitcnt lgkmcnt(0)
	v_lshlrev_b32_e32 v146, 16, v146
	v_mul_f32_e32 v146, 0x3db504f3, v146
	v_mul_f32_e32 v146, v147, v146
	v_cvt_pk_bf16_f32 v157, v146, v146
	v_or_b32_e32 v146, v142, v120
	v_mov_b32_e32 v147, v143
	v_lshlrev_b64 v[146:147], 8, v[146:147]
	v_or_b32_e32 v146, v146, v144
	v_lshl_add_u64 v[154:155], s[36:37], 0, v[146:147]
	global_store_short_d16_hi v[154:155], v157, off
	v_mul_f32_e32 v154, 0xbfb8aa3b, v145
	v_exp_f32_e32 v154, v154
	v_lshl_add_u64 v[146:147], s[38:39], 0, v[146:147]
	v_mul_f32_e32 v154, v154, v156
	v_cvt_pk_bf16_f32 v154, v154, v154
	global_store_short_d16_hi v[146:147], v154, off
	v_sub_f32_e32 v146, v141, v145
	v_mul_f32_e32 v146, 0x3fb8aa3b, v146
	v_exp_f32_e32 v146, v146
	s_nop 0
	v_mul_f32_e32 v146, v146, v156
	v_cvt_pk_bf16_f32 v154, v146, v146
	v_lshlrev_b32_e32 v146, 1, v120
	v_mov_b32_e32 v147, v3
	v_lshl_add_u64 v[146:147], v[6:7], 0, v[146:147]
	v_lshrrev_b32_e32 v223, 16, v154
	ds_read_u16 v147, v153 offset:24576
	v_cndmask_b32_e64 v146, v181, v247, s[4:5]
	v_add_f32_e32 v145, v146, v145
	ds_read_u16 v146, v153 offset:8192
	s_waitcnt lgkmcnt(1)
	v_lshlrev_b32_e32 v156, 16, v147
	v_mul_f32_e32 v147, 0x3fb8aa3b, v145
	v_exp_f32_e32 v147, v147
	s_waitcnt lgkmcnt(0)
	v_lshlrev_b32_e32 v146, 16, v146
	v_mul_f32_e32 v146, 0x3db504f3, v146
	v_mul_f32_e32 v146, v147, v146
	v_cvt_pk_bf16_f32 v157, v146, v146
	v_or_b32_e32 v146, v142, v122
	v_mov_b32_e32 v147, v143
	v_lshlrev_b64 v[146:147], 8, v[146:147]
	v_or_b32_e32 v146, v146, v144
	v_lshl_add_u64 v[154:155], s[36:37], 0, v[146:147]
	global_store_short_d16_hi v[154:155], v157, off
	v_mul_f32_e32 v154, 0xbfb8aa3b, v145
	v_exp_f32_e32 v154, v154
	v_lshl_add_u64 v[146:147], s[38:39], 0, v[146:147]
	v_mul_f32_e32 v154, v154, v156
	v_cvt_pk_bf16_f32 v154, v154, v154
	global_store_short_d16_hi v[146:147], v154, off
	v_sub_f32_e32 v146, v141, v145
	v_mul_f32_e32 v146, 0x3fb8aa3b, v146
	v_exp_f32_e32 v146, v146
	s_nop 0
	v_mul_f32_e32 v146, v146, v156
	v_cvt_pk_bf16_f32 v154, v146, v146
	v_lshlrev_b32_e32 v146, 1, v122
	v_mov_b32_e32 v147, v3
	v_lshl_add_u64 v[146:147], v[6:7], 0, v[146:147]
	v_and_or_b32 v223, v154, s98, v223
	v_alignbit_b32 v226, v223, v223, 16
	v_alignbit_b32 v218, v220, v220, 16
	v_cndmask_b32_e64 v220, v226, v220, s[4:5]
	v_cndmask_b32_e64 v223, v218, v223, s[4:5]
	v_alignbit_b32 v226, v222, v222, 16
	v_alignbit_b32 v218, v221, v221, 16
	v_cndmask_b32_e64 v221, v226, v221, s[4:5]
	v_cndmask_b32_e64 v222, v218, v222, s[4:5]
	v_lshl_add_u64 v[218:219], v[146:147], 0, v[224:225]
	global_store_dwordx4 v[218:219], v[220:223], off
	s_nop 1
	ds_read_u16 v147, v162 offset:24576
	v_cndmask_b32_e64 v146, v180, v239, s[4:5]
	v_add_f32_e32 v145, v146, v145
	ds_read_u16 v146, v162 offset:8192
	s_waitcnt lgkmcnt(1)
	v_lshlrev_b32_e32 v156, 16, v147
	v_mul_f32_e32 v147, 0x3fb8aa3b, v145
	v_exp_f32_e32 v147, v147
	s_waitcnt lgkmcnt(0)
	v_lshlrev_b32_e32 v146, 16, v146
	v_mul_f32_e32 v146, 0x3db504f3, v146
	v_mul_f32_e32 v146, v147, v146
	v_cvt_pk_bf16_f32 v157, v146, v146
	v_or_b32_e32 v146, v142, v124
	v_mov_b32_e32 v147, v143
	v_lshlrev_b64 v[146:147], 8, v[146:147]
	v_or_b32_e32 v146, v146, v144
	v_lshl_add_u64 v[154:155], s[36:37], 0, v[146:147]
	global_store_short_d16_hi v[154:155], v157, off
	v_mul_f32_e32 v154, 0xbfb8aa3b, v145
	v_exp_f32_e32 v154, v154
	v_lshl_add_u64 v[146:147], s[38:39], 0, v[146:147]
	v_mul_f32_e32 v154, v154, v156
	v_cvt_pk_bf16_f32 v154, v154, v154
	global_store_short_d16_hi v[146:147], v154, off
	v_sub_f32_e32 v146, v141, v145
	v_mul_f32_e32 v146, 0x3fb8aa3b, v146
	v_exp_f32_e32 v146, v146
	s_nop 0
	v_mul_f32_e32 v146, v146, v156
	v_cvt_pk_bf16_f32 v154, v146, v146
	v_lshlrev_b32_e32 v146, 1, v124
	v_mov_b32_e32 v147, v3
	v_lshl_add_u64 v[146:147], v[6:7], 0, v[146:147]
	v_lshrrev_b32_e32 v220, 16, v154
	ds_read_u16 v147, v163 offset:24576
	v_cndmask_b32_e64 v146, v179, v245, s[4:5]
	v_add_f32_e32 v145, v146, v145
	ds_read_u16 v146, v163 offset:8192
	s_waitcnt lgkmcnt(1)
	v_lshlrev_b32_e32 v156, 16, v147
	v_mul_f32_e32 v147, 0x3fb8aa3b, v145
	v_exp_f32_e32 v147, v147
	s_waitcnt lgkmcnt(0)
	v_lshlrev_b32_e32 v146, 16, v146
	v_mul_f32_e32 v146, 0x3db504f3, v146
	v_mul_f32_e32 v146, v147, v146
	v_cvt_pk_bf16_f32 v157, v146, v146
	v_or_b32_e32 v146, v142, v126
	v_mov_b32_e32 v147, v143
	v_lshlrev_b64 v[146:147], 8, v[146:147]
	v_or_b32_e32 v146, v146, v144
	v_lshl_add_u64 v[154:155], s[36:37], 0, v[146:147]
	global_store_short_d16_hi v[154:155], v157, off
	v_mul_f32_e32 v154, 0xbfb8aa3b, v145
	v_exp_f32_e32 v154, v154
	v_lshl_add_u64 v[146:147], s[38:39], 0, v[146:147]
	v_mul_f32_e32 v154, v154, v156
	v_cvt_pk_bf16_f32 v154, v154, v154
	global_store_short_d16_hi v[146:147], v154, off
	v_sub_f32_e32 v146, v141, v145
	v_mul_f32_e32 v146, 0x3fb8aa3b, v146
	v_exp_f32_e32 v146, v146
	s_nop 0
	v_mul_f32_e32 v146, v146, v156
	v_cvt_pk_bf16_f32 v154, v146, v146
	v_lshlrev_b32_e32 v146, 1, v126
	v_mov_b32_e32 v147, v3
	v_lshl_add_u64 v[146:147], v[6:7], 0, v[146:147]
	v_and_or_b32 v220, v154, s98, v220
	ds_read_u16 v147, v164 offset:24576
	v_cndmask_b32_e64 v146, v178, v249, s[4:5]
	v_add_f32_e32 v145, v146, v145
	ds_read_u16 v146, v164 offset:8192
	s_waitcnt lgkmcnt(1)
	v_lshlrev_b32_e32 v156, 16, v147
	v_mul_f32_e32 v147, 0x3fb8aa3b, v145
	v_exp_f32_e32 v147, v147
	s_waitcnt lgkmcnt(0)
	v_lshlrev_b32_e32 v146, 16, v146
	v_mul_f32_e32 v146, 0x3db504f3, v146
	v_mul_f32_e32 v146, v147, v146
	v_cvt_pk_bf16_f32 v157, v146, v146
	v_or_b32_e32 v146, v142, v128
	v_mov_b32_e32 v147, v143
	v_lshlrev_b64 v[146:147], 8, v[146:147]
	v_or_b32_e32 v146, v146, v144
	v_lshl_add_u64 v[154:155], s[36:37], 0, v[146:147]
	global_store_short_d16_hi v[154:155], v157, off
	v_mul_f32_e32 v154, 0xbfb8aa3b, v145
	v_exp_f32_e32 v154, v154
	v_lshl_add_u64 v[146:147], s[38:39], 0, v[146:147]
	v_mul_f32_e32 v154, v154, v156
	v_cvt_pk_bf16_f32 v154, v154, v154
	global_store_short_d16_hi v[146:147], v154, off
	v_sub_f32_e32 v146, v141, v145
	v_mul_f32_e32 v146, 0x3fb8aa3b, v146
	v_exp_f32_e32 v146, v146
	s_nop 0
	v_mul_f32_e32 v146, v146, v156
	v_cvt_pk_bf16_f32 v154, v146, v146
	v_lshlrev_b32_e32 v146, 1, v128
	v_mov_b32_e32 v147, v3
	v_lshl_add_u64 v[146:147], v[6:7], 0, v[146:147]
	v_lshrrev_b32_e32 v221, 16, v154
	ds_read_u16 v147, v165 offset:24576
	v_cndmask_b32_e64 v146, v177, v250, s[4:5]
	v_add_f32_e32 v145, v146, v145
	ds_read_u16 v146, v165 offset:8192
	s_waitcnt lgkmcnt(1)
	v_lshlrev_b32_e32 v156, 16, v147
	v_mul_f32_e32 v147, 0x3fb8aa3b, v145
	v_exp_f32_e32 v147, v147
	s_waitcnt lgkmcnt(0)
	v_lshlrev_b32_e32 v146, 16, v146
	v_mul_f32_e32 v146, 0x3db504f3, v146
	v_mul_f32_e32 v146, v147, v146
	v_cvt_pk_bf16_f32 v157, v146, v146
	v_or_b32_e32 v146, v142, v130
	v_mov_b32_e32 v147, v143
	v_lshlrev_b64 v[146:147], 8, v[146:147]
	v_or_b32_e32 v146, v146, v144
	v_lshl_add_u64 v[154:155], s[36:37], 0, v[146:147]
	global_store_short_d16_hi v[154:155], v157, off
	v_mul_f32_e32 v154, 0xbfb8aa3b, v145
	v_exp_f32_e32 v154, v154
	v_lshl_add_u64 v[146:147], s[38:39], 0, v[146:147]
	v_mul_f32_e32 v154, v154, v156
	v_cvt_pk_bf16_f32 v154, v154, v154
	global_store_short_d16_hi v[146:147], v154, off
	v_sub_f32_e32 v146, v141, v145
	v_mul_f32_e32 v146, 0x3fb8aa3b, v146
	v_exp_f32_e32 v146, v146
	s_nop 0
	v_mul_f32_e32 v146, v146, v156
	v_cvt_pk_bf16_f32 v154, v146, v146
	v_lshlrev_b32_e32 v146, 1, v130
	v_mov_b32_e32 v147, v3
	v_lshl_add_u64 v[146:147], v[6:7], 0, v[146:147]
	v_and_or_b32 v221, v154, s98, v221
	ds_read_u16 v147, v166 offset:24576
	v_cndmask_b32_e64 v146, v176, v243, s[4:5]
	v_add_f32_e32 v145, v146, v145
	ds_read_u16 v146, v166 offset:8192
	s_waitcnt lgkmcnt(1)
	v_lshlrev_b32_e32 v156, 16, v147
	v_mul_f32_e32 v147, 0x3fb8aa3b, v145
	v_exp_f32_e32 v147, v147
	s_waitcnt lgkmcnt(0)
	v_lshlrev_b32_e32 v146, 16, v146
	v_mul_f32_e32 v146, 0x3db504f3, v146
	v_mul_f32_e32 v146, v147, v146
	v_cvt_pk_bf16_f32 v157, v146, v146
	v_or_b32_e32 v146, v142, v132
	v_mov_b32_e32 v147, v143
	v_lshlrev_b64 v[146:147], 8, v[146:147]
	v_or_b32_e32 v146, v146, v144
	v_lshl_add_u64 v[154:155], s[36:37], 0, v[146:147]
	global_store_short_d16_hi v[154:155], v157, off
	v_mul_f32_e32 v154, 0xbfb8aa3b, v145
	v_exp_f32_e32 v154, v154
	v_lshl_add_u64 v[146:147], s[38:39], 0, v[146:147]
	v_mul_f32_e32 v154, v154, v156
	v_cvt_pk_bf16_f32 v154, v154, v154
	global_store_short_d16_hi v[146:147], v154, off
	v_sub_f32_e32 v146, v141, v145
	v_mul_f32_e32 v146, 0x3fb8aa3b, v146
	v_exp_f32_e32 v146, v146
	s_nop 0
	v_mul_f32_e32 v146, v146, v156
	v_cvt_pk_bf16_f32 v154, v146, v146
	v_lshlrev_b32_e32 v146, 1, v132
	v_mov_b32_e32 v147, v3
	v_lshl_add_u64 v[146:147], v[6:7], 0, v[146:147]
	v_lshrrev_b32_e32 v222, 16, v154
	ds_read_u16 v147, v167 offset:24576
	v_cndmask_b32_e64 v146, v175, v248, s[4:5]
	v_add_f32_e32 v145, v146, v145
	ds_read_u16 v146, v167 offset:8192
	s_waitcnt lgkmcnt(1)
	v_lshlrev_b32_e32 v156, 16, v147
	v_mul_f32_e32 v147, 0x3fb8aa3b, v145
	v_exp_f32_e32 v147, v147
	s_waitcnt lgkmcnt(0)
	v_lshlrev_b32_e32 v146, 16, v146
	v_mul_f32_e32 v146, 0x3db504f3, v146
	v_mul_f32_e32 v146, v147, v146
	v_cvt_pk_bf16_f32 v157, v146, v146
	v_or_b32_e32 v146, v142, v134
	v_mov_b32_e32 v147, v143
	v_lshlrev_b64 v[146:147], 8, v[146:147]
	v_or_b32_e32 v146, v146, v144
	v_lshl_add_u64 v[154:155], s[36:37], 0, v[146:147]
	global_store_short_d16_hi v[154:155], v157, off
	v_mul_f32_e32 v154, 0xbfb8aa3b, v145
	v_exp_f32_e32 v154, v154
	v_lshl_add_u64 v[146:147], s[38:39], 0, v[146:147]
	v_mul_f32_e32 v154, v154, v156
	v_cvt_pk_bf16_f32 v154, v154, v154
	global_store_short_d16_hi v[146:147], v154, off
	v_sub_f32_e32 v146, v141, v145
	v_mul_f32_e32 v146, 0x3fb8aa3b, v146
	v_exp_f32_e32 v146, v146
	s_nop 0
	v_mul_f32_e32 v146, v146, v156
	v_cvt_pk_bf16_f32 v154, v146, v146
	v_lshlrev_b32_e32 v146, 1, v134
	v_mov_b32_e32 v147, v3
	v_lshl_add_u64 v[146:147], v[6:7], 0, v[146:147]
	v_and_or_b32 v222, v154, s98, v222
	ds_read_u16 v147, v168 offset:24576
	v_cndmask_b32_e64 v146, v174, v251, s[4:5]
	v_add_f32_e32 v145, v146, v145
	ds_read_u16 v146, v168 offset:8192
	s_waitcnt lgkmcnt(1)
	v_lshlrev_b32_e32 v156, 16, v147
	v_mul_f32_e32 v147, 0x3fb8aa3b, v145
	v_exp_f32_e32 v147, v147
	s_waitcnt lgkmcnt(0)
	v_lshlrev_b32_e32 v146, 16, v146
	v_mul_f32_e32 v146, 0x3db504f3, v146
	v_mul_f32_e32 v146, v147, v146
	v_cvt_pk_bf16_f32 v157, v146, v146
	v_or_b32_e32 v146, v142, v136
	v_mov_b32_e32 v147, v143
	v_lshlrev_b64 v[146:147], 8, v[146:147]
	v_or_b32_e32 v146, v146, v144
	v_lshl_add_u64 v[154:155], s[36:37], 0, v[146:147]
	global_store_short_d16_hi v[154:155], v157, off
	v_mul_f32_e32 v154, 0xbfb8aa3b, v145
	v_exp_f32_e32 v154, v154
	v_lshl_add_u64 v[146:147], s[38:39], 0, v[146:147]
	v_or_b32_e32 v142, v142, v138
	v_lshlrev_b64 v[142:143], 8, v[142:143]
	v_mul_f32_e32 v154, v154, v156
	v_bfe_u32 v155, v154, 16, 1
	v_add3_u32 v154, v154, v155, s73
	global_store_short_d16_hi v[146:147], v154, off
	v_sub_f32_e32 v146, v141, v145
	v_mul_f32_e32 v146, 0x3fb8aa3b, v146
	v_exp_f32_e32 v146, v146
	v_or_b32_e32 v142, v142, v144
	v_mul_f32_e32 v146, v146, v156
	v_cvt_pk_bf16_f32 v154, v146, v146
	v_lshlrev_b32_e32 v146, 1, v136
	v_mov_b32_e32 v147, v3
	v_lshl_add_u64 v[146:147], v[6:7], 0, v[146:147]
	v_lshrrev_b32_e32 v223, 16, v154
	v_cndmask_b32_e64 v146, v173, v252, s[4:5]
	v_add_f32_e32 v146, v146, v145
	ds_read_u16 v145, v169 offset:8192
	v_mul_f32_e32 v154, 0x3fb8aa3b, v146
	v_exp_f32_e32 v154, v154
	ds_read_u16 v147, v169 offset:24576
	s_waitcnt lgkmcnt(1)
	v_lshlrev_b32_e32 v145, 16, v145
	v_mul_f32_e32 v145, 0x3db504f3, v145
	v_mul_f32_e32 v145, v154, v145
	v_cvt_pk_bf16_f32 v154, v145, v145
	v_lshl_add_u64 v[144:145], s[36:37], 0, v[142:143]
	global_store_short_d16_hi v[144:145], v154, off
	v_mul_f32_e32 v144, 0xbfb8aa3b, v146
	v_exp_f32_e32 v144, v144
	s_waitcnt lgkmcnt(0)
	v_lshlrev_b32_e32 v147, 16, v147
	v_lshl_add_u64 v[142:143], s[38:39], 0, v[142:143]
	v_mul_f32_e32 v144, v144, v147
	v_bfe_u32 v145, v144, 16, 1
	v_add3_u32 v144, v144, v145, s73
	global_store_short_d16_hi v[142:143], v144, off
	v_sub_f32_e32 v142, v141, v146
	v_mul_f32_e32 v142, 0x3fb8aa3b, v142
	v_exp_f32_e32 v142, v142
	s_nop 0
	v_mul_f32_e32 v142, v142, v147
	v_cvt_pk_bf16_f32 v144, v142, v142
	v_lshlrev_b32_e32 v142, 1, v138
	v_mov_b32_e32 v143, v3
	v_lshl_add_u64 v[6:7], v[6:7], 0, v[142:143]
	v_and_or_b32 v223, v144, s98, v223
	v_alignbit_b32 v226, v223, v223, 16
	v_alignbit_b32 v218, v220, v220, 16
	v_cndmask_b32_e64 v220, v226, v220, s[4:5]
	v_cndmask_b32_e64 v223, v218, v223, s[4:5]
	v_alignbit_b32 v226, v222, v222, 16
	v_alignbit_b32 v218, v221, v221, 16
	v_cndmask_b32_e64 v221, v226, v221, s[4:5]
	v_cndmask_b32_e64 v222, v218, v222, s[4:5]
	v_lshl_add_u64 v[218:219], v[6:7], 0, v[224:225]
	global_store_dwordx4 v[218:219], v[220:223], off
	s_nop 1
	v_and_b32_e32 v227, 0xff, v0
	v_lshrrev_b32_e32 v228, 8, v0
	v_lshlrev_b32_e32 v227, 2, v227
	v_lshl_add_u32 v227, v228, 16, v227
	ds_read_b32 v218, v227 offset:40960
	ds_read_b32 v219, v227 offset:41984
	ds_read_b32 v220, v227 offset:43008
	ds_read_b32 v221, v227 offset:44032
	ds_read_b32 v222, v227 offset:45056
	ds_read_b32 v223, v227 offset:46080
	ds_read_b32 v224, v227 offset:47104
	ds_read_b32 v225, v227 offset:48128
	ds_read_b32 v226, v227 offset:49152
	s_waitcnt lgkmcnt(0)
	v_mul_f32_e32 v6, 0x3fb8aa3b, v141
	v_exp_f32_e32 v6, v6
	global_store_dword v[4:5], v6, off
	s_andn2_b64 exec, exec, s[12:13]
	s_cbranch_execnz .LBB0_759
